# K-loop: fragment read order A0,B0,A1.. with per-MFMA lgkmcnt ladder at both half-step starts
# speedup vs baseline: 1.0004x; 1.0004x over previous
.LBB0_466:
	s_bitcmp1_b32 s4, 0
	s_cselect_b32 s21, 0x12000, 0
	v_or_b32_e32 v184, s21, v206
	v_add_u32_e32 v185, v184, v0
	v_add_u32_e32 v184, v184, v167
	ds_read_b128 v[210:213], v185
	ds_read_b128 v[226:229], v184 offset:32768
	ds_read_b128 v[214:217], v185 offset:2048
	ds_read_b128 v[218:221], v185 offset:4096
	ds_read_b128 v[222:225], v185 offset:6144
	ds_read_b128 v[230:233], v184 offset:34816
	ds_read_b128 v[234:237], v184 offset:36864
	ds_read_b128 v[238:241], v184 offset:38912
	ds_read_b128 v[242:245], v184 offset:40960
	ds_read_b128 v[246:249], v184 offset:43008
	ds_read_b128 v[198:201], v184 offset:45056
	ds_read_b128 v[184:187], v184 offset:47104
	s_add_i32 s10, s4, 1
	s_bitcmp1_b32 s10, 0
	s_cselect_b32 s23, 0x12000, 0
	v_add_u32_e32 v171, s23, v166
	v_xor_b32_e32 v169, 64, v206
	v_add3_u32 v169, s21, v167, v169
	s_waitcnt lgkmcnt(10)
	v_mfma_f32_16x16x32_bf16 v[158:161], v[226:229], v[210:213], v[158:161]
	s_waitcnt lgkmcnt(9)
	v_mfma_f32_16x16x32_bf16 v[94:97], v[226:229], v[214:217], v[94:97]
	s_waitcnt lgkmcnt(8)
	v_mfma_f32_16x16x32_bf16 v[62:65], v[226:229], v[218:221], v[62:65]
	s_waitcnt lgkmcnt(7)
	v_mfma_f32_16x16x32_bf16 v[30:33], v[226:229], v[222:225], v[30:33]
	ds_read_b128 v[226:229], v169 offset:32768
	s_waitcnt lgkmcnt(7)
	v_mfma_f32_16x16x32_bf16 v[154:157], v[230:233], v[210:213], v[154:157]
	v_mfma_f32_16x16x32_bf16 v[90:93], v[230:233], v[214:217], v[90:93]
	v_mfma_f32_16x16x32_bf16 v[58:61], v[230:233], v[218:221], v[58:61]
	v_mfma_f32_16x16x32_bf16 v[26:29], v[230:233], v[222:225], v[26:29]
	ds_read_b128 v[230:233], v169 offset:34816
	s_waitcnt lgkmcnt(7)
	v_mfma_f32_16x16x32_bf16 v[150:153], v[234:237], v[210:213], v[150:153]
	v_mfma_f32_16x16x32_bf16 v[86:89], v[234:237], v[214:217], v[86:89]
	v_mfma_f32_16x16x32_bf16 v[54:57], v[234:237], v[218:221], v[54:57]
	v_mfma_f32_16x16x32_bf16 v[22:25], v[234:237], v[222:225], v[22:25]
	ds_read_b128 v[234:237], v169 offset:36864
	s_waitcnt lgkmcnt(7)
	v_mfma_f32_16x16x32_bf16 v[146:149], v[238:241], v[210:213], v[146:149]
	v_mfma_f32_16x16x32_bf16 v[82:85], v[238:241], v[214:217], v[82:85]
	v_mfma_f32_16x16x32_bf16 v[50:53], v[238:241], v[218:221], v[50:53]
	v_mfma_f32_16x16x32_bf16 v[18:21], v[238:241], v[222:225], v[18:21]
	ds_read_b128 v[238:241], v169 offset:38912
	s_waitcnt lgkmcnt(7)
	v_mfma_f32_16x16x32_bf16 v[142:145], v[242:245], v[210:213], v[142:145]
	v_mfma_f32_16x16x32_bf16 v[78:81], v[242:245], v[214:217], v[78:81]
	v_mfma_f32_16x16x32_bf16 v[46:49], v[242:245], v[218:221], v[46:49]
	v_mfma_f32_16x16x32_bf16 v[14:17], v[242:245], v[222:225], v[14:17]
	ds_read_b128 v[242:245], v169 offset:40960
	s_waitcnt lgkmcnt(7)
	v_mfma_f32_16x16x32_bf16 v[138:141], v[246:249], v[210:213], v[138:141]
	v_mfma_f32_16x16x32_bf16 v[74:77], v[246:249], v[214:217], v[74:77]
	v_mfma_f32_16x16x32_bf16 v[42:45], v[246:249], v[218:221], v[42:45]
	v_mfma_f32_16x16x32_bf16 v[10:13], v[246:249], v[222:225], v[10:13]
	ds_read_b128 v[246:249], v169 offset:43008
	s_waitcnt lgkmcnt(7)
	v_mfma_f32_16x16x32_bf16 v[102:105], v[198:201], v[210:213], v[102:105]
	v_mfma_f32_16x16x32_bf16 v[70:73], v[198:201], v[214:217], v[70:73]
	v_mfma_f32_16x16x32_bf16 v[38:41], v[198:201], v[218:221], v[38:41]
	v_mfma_f32_16x16x32_bf16 v[6:9], v[198:201], v[222:225], v[6:9]
	ds_read_b128 v[198:201], v169 offset:45056
	s_waitcnt lgkmcnt(7)
	v_mfma_f32_16x16x32_bf16 v[98:101], v[184:187], v[210:213], v[98:101]
	v_mfma_f32_16x16x32_bf16 v[66:69], v[184:187], v[214:217], v[66:69]
	v_xor_b32_e32 v169, 64, v206
	v_add3_u32 v169, s21, v0, v169
	ds_read_b128 v[210:213], v169
	ds_read_b128 v[214:217], v169 offset:2048
	v_mfma_f32_16x16x32_bf16 v[34:37], v[184:187], v[218:221], v[34:37]
	ds_read_b128 v[218:221], v169 offset:4096
	v_mfma_f32_16x16x32_bf16 v[2:5], v[184:187], v[222:225], v[2:5]
	ds_read_b128 v[222:225], v169 offset:6144
	v_xor_b32_e32 v169, 64, v206
	v_add3_u32 v169, s21, v167, v169
	ds_read_b128 v[184:187], v169 offset:47104
	s_waitcnt lgkmcnt(4)
	v_mfma_f32_16x16x32_bf16 v[158:161], v[226:229], v[210:213], v[158:161]
	s_waitcnt lgkmcnt(3)
	v_mfma_f32_16x16x32_bf16 v[94:97], v[226:229], v[214:217], v[94:97]
	s_waitcnt lgkmcnt(2)
	v_mfma_f32_16x16x32_bf16 v[62:65], v[226:229], v[218:221], v[62:65]
	s_waitcnt lgkmcnt(1)
	v_mfma_f32_16x16x32_bf16 v[30:33], v[226:229], v[222:225], v[30:33]
	s_waitcnt vmcnt(7)
	ds_write_b128 v171, v[114:117]
	v_mfma_f32_16x16x32_bf16 v[154:157], v[230:233], v[210:213], v[154:157]
	v_mfma_f32_16x16x32_bf16 v[90:93], v[230:233], v[214:217], v[90:93]
	global_load_dwordx4 v[114:117], v168, vcc offset:256
	v_mfma_f32_16x16x32_bf16 v[58:61], v[230:233], v[218:221], v[58:61]
	v_mfma_f32_16x16x32_bf16 v[26:29], v[230:233], v[222:225], v[26:29]
	s_waitcnt vmcnt(7)
	ds_write_b128 v171, v[106:109] offset:8192
	v_mfma_f32_16x16x32_bf16 v[150:153], v[234:237], v[210:213], v[150:153]
	v_mfma_f32_16x16x32_bf16 v[86:89], v[234:237], v[214:217], v[86:89]
	v_add_u32_e32 v106, s34, v168
	global_load_dwordx4 v[106:109], v106, vcc offset:256
	v_mfma_f32_16x16x32_bf16 v[54:57], v[234:237], v[218:221], v[54:57]
	v_mfma_f32_16x16x32_bf16 v[22:25], v[234:237], v[222:225], v[22:25]
	s_waitcnt vmcnt(7)
	ds_write_b128 v171, v[110:113] offset:16384
	v_mfma_f32_16x16x32_bf16 v[146:149], v[238:241], v[210:213], v[146:149]
	v_mfma_f32_16x16x32_bf16 v[82:85], v[238:241], v[214:217], v[82:85]
	v_add_u32_e32 v110, s35, v168
	global_load_dwordx4 v[110:113], v110, vcc offset:256
	v_mfma_f32_16x16x32_bf16 v[50:53], v[238:241], v[218:221], v[50:53]
	v_mfma_f32_16x16x32_bf16 v[18:21], v[238:241], v[222:225], v[18:21]
	s_waitcnt vmcnt(7)
	ds_write_b128 v171, v[126:129] offset:24576
	v_mfma_f32_16x16x32_bf16 v[142:145], v[242:245], v[210:213], v[142:145]
	v_mfma_f32_16x16x32_bf16 v[78:81], v[242:245], v[214:217], v[78:81]
	v_add_u32_e32 v126, s36, v168
	global_load_dwordx4 v[126:129], v126, vcc offset:256
	v_mfma_f32_16x16x32_bf16 v[46:49], v[242:245], v[218:221], v[46:49]
	v_mfma_f32_16x16x32_bf16 v[14:17], v[242:245], v[222:225], v[14:17]
	s_waitcnt vmcnt(7)
	ds_write_b128 v171, v[122:125] offset:32768
	v_mfma_f32_16x16x32_bf16 v[138:141], v[246:249], v[210:213], v[138:141]
	v_mfma_f32_16x16x32_bf16 v[74:77], v[246:249], v[214:217], v[74:77]
	global_load_dwordx4 v[122:125], v170, s[100:101] offset:256
	v_mfma_f32_16x16x32_bf16 v[42:45], v[246:249], v[218:221], v[42:45]
	v_mfma_f32_16x16x32_bf16 v[10:13], v[246:249], v[222:225], v[10:13]
	s_waitcnt vmcnt(7)
	ds_write_b128 v171, v[118:121] offset:40960
	v_mfma_f32_16x16x32_bf16 v[102:105], v[198:201], v[210:213], v[102:105]
	v_mfma_f32_16x16x32_bf16 v[70:73], v[198:201], v[214:217], v[70:73]
	v_add_u32_e32 v118, s34, v170
	global_load_dwordx4 v[118:121], v118, s[100:101] offset:256
	v_mfma_f32_16x16x32_bf16 v[38:41], v[198:201], v[218:221], v[38:41]
	v_mfma_f32_16x16x32_bf16 v[6:9], v[198:201], v[222:225], v[6:9]
	s_waitcnt vmcnt(7)
	ds_write_b128 v171, v[134:137] offset:49152
	s_waitcnt lgkmcnt(7)
	v_mfma_f32_16x16x32_bf16 v[98:101], v[184:187], v[210:213], v[98:101]
	v_mfma_f32_16x16x32_bf16 v[66:69], v[184:187], v[214:217], v[66:69]
	v_add_u32_e32 v134, s35, v170
	global_load_dwordx4 v[134:137], v134, s[100:101] offset:256
	v_mfma_f32_16x16x32_bf16 v[34:37], v[184:187], v[218:221], v[34:37]
	v_mfma_f32_16x16x32_bf16 v[2:5], v[184:187], v[222:225], v[2:5]
	s_waitcnt vmcnt(7)
	ds_write_b128 v171, v[130:133] offset:57344
	v_add_u32_e32 v130, s36, v170
	global_load_dwordx4 v[130:133], v130, s[100:101] offset:256
	v_add_u32_e32 v168, 0x80, v168
	v_add_u32_e32 v170, 0x80, v170
	s_waitcnt lgkmcnt(0)
	s_barrier
	s_cmp_eq_u32 s10, 16
	s_mov_b32 s4, s10
	s_cbranch_scc0 .LBB0_466
	s_waitcnt vmcnt(6)
	v_mul_f32_e32 v109, 0xbfb8aa3b, v158
	v_exp_f32_e32 v109, v109
	s_waitcnt vmcnt(5)
	v_mul_f32_e32 v111, 0xbfb8aa3b, v159
	v_exp_f32_e32 v111, v111
	v_mul_f32_e32 v115, 0xbfb8aa3b, v161
	v_add_f32_e32 v109, 1.0, v109
	v_rcp_f32_e32 v114, v109
	v_add_f32_e32 v109, 1.0, v111
	v_mul_f32_e32 v111, 0xbfb8aa3b, v160
	v_exp_f32_e32 v111, v111
	v_exp_f32_e32 v117, v115
	v_rcp_f32_e32 v116, v109
	s_waitcnt vmcnt(2)
	v_mov_b32_e32 v118, v158
	v_add_f32_e32 v109, 1.0, v111
	v_rcp_f32_e32 v115, v109
	v_add_f32_e32 v109, 1.0, v117
	v_rcp_f32_e32 v117, v109
	v_mov_b32_e32 v119, v160
	v_pk_mul_f32 v[114:115], v[118:119], v[114:115]
	v_mov_b32_e32 v118, v154
	v_mov_b32_e32 v119, v156
	v_mov_b32_e32 v160, v159
	v_pk_mul_f32 v[114:115], v[118:119], v[114:115]
	v_pk_mul_f32 v[116:117], v[160:161], v[116:117]
	v_mov_b32_e32 v156, v155
	v_pk_mul_f32 v[116:117], v[156:157], v[116:117]
	v_and_b32_sdwa v111, v115, v177 dst_sel:DWORD dst_unused:UNUSED_PAD src0_sel:WORD_1 src1_sel:DWORD
	v_and_b32_sdwa v118, v114, v177 dst_sel:DWORD dst_unused:UNUSED_PAD src0_sel:WORD_1 src1_sel:DWORD
	v_add3_u32 v111, v115, v111, s28
	v_and_b32_sdwa v115, v117, v177 dst_sel:DWORD dst_unused:UNUSED_PAD src0_sel:WORD_1 src1_sel:DWORD
	v_add3_u32 v114, v114, v118, s28
	v_and_b32_sdwa v118, v116, v177 dst_sel:DWORD dst_unused:UNUSED_PAD src0_sel:WORD_1 src1_sel:DWORD
	v_add3_u32 v115, v117, v115, s28
	v_or_b32_e32 v106, s7, v207
	v_add3_u32 v116, v116, v118, s28
	v_and_b32_e32 v115, 0xffff0000, v115
	v_ashrrev_i32_e32 v106, 1, v106
	v_and_b32_e32 v116, 0xffff0000, v116
	v_or_b32_sdwa v115, v115, v111 dst_sel:DWORD dst_unused:UNUSED_PAD src0_sel:DWORD src1_sel:WORD_1
	v_mul_f32_e32 v111, 0xbfb8aa3b, v150
	v_or_b32_e32 v108, v106, v208
	v_or_b32_sdwa v114, v116, v114 dst_sel:DWORD dst_unused:UNUSED_PAD src0_sel:DWORD src1_sel:WORD_1
	v_exp_f32_e32 v111, v111
	v_mul_f32_e32 v116, 0xbfb8aa3b, v151
	v_add_u32_e32 v110, s6, v205
	v_mov_b64_e32 v[106:107], s[14:15]
	v_ashrrev_i32_e32 v109, 31, v108
	v_exp_f32_e32 v116, v116
	v_mad_i64_i32 v[112:113], s[6:7], v110, s52, v[106:107]
	v_lshlrev_b64 v[108:109], 1, v[108:109]
	v_lshl_add_u64 v[112:113], v[112:113], 0, v[108:109]
	s_waitcnt vmcnt(0)
	global_store_dwordx2 v[112:113], v[114:115], off
	v_add_f32_e32 v111, 1.0, v111
	v_mul_f32_e32 v115, 0xbfb8aa3b, v152
	v_rcp_f32_e32 v114, v111
	v_add_f32_e32 v111, 1.0, v116
	v_exp_f32_e32 v115, v115
	v_mul_f32_e32 v116, 0xbfb8aa3b, v153
	v_exp_f32_e32 v117, v116
	v_rcp_f32_e32 v116, v111
	v_add_f32_e32 v111, 1.0, v115
	v_rcp_f32_e32 v115, v111
	v_add_f32_e32 v111, 1.0, v117
	v_rcp_f32_e32 v117, v111
	v_mov_b32_e32 v118, v150
	v_mov_b32_e32 v119, v152
	v_pk_mul_f32 v[114:115], v[118:119], v[114:115]
	v_mov_b32_e32 v118, v146
	v_mov_b32_e32 v119, v148
	v_mov_b32_e32 v152, v151
	v_pk_mul_f32 v[114:115], v[118:119], v[114:115]
	v_pk_mul_f32 v[116:117], v[152:153], v[116:117]
	v_mov_b32_e32 v148, v147
	v_pk_mul_f32 v[116:117], v[148:149], v[116:117]
	v_and_b32_sdwa v111, v115, v177 dst_sel:DWORD dst_unused:UNUSED_PAD src0_sel:WORD_1 src1_sel:DWORD
	v_and_b32_sdwa v118, v114, v177 dst_sel:DWORD dst_unused:UNUSED_PAD src0_sel:WORD_1 src1_sel:DWORD
	v_add3_u32 v111, v115, v111, s28
	v_and_b32_sdwa v115, v117, v177 dst_sel:DWORD dst_unused:UNUSED_PAD src0_sel:WORD_1 src1_sel:DWORD
	v_add3_u32 v114, v114, v118, s28
	v_and_b32_sdwa v118, v116, v177 dst_sel:DWORD dst_unused:UNUSED_PAD src0_sel:WORD_1 src1_sel:DWORD
	v_add3_u32 v115, v117, v115, s28
	v_add3_u32 v116, v116, v118, s28
	v_and_b32_e32 v115, 0xffff0000, v115
	v_and_b32_e32 v116, 0xffff0000, v116
	v_or_b32_sdwa v115, v115, v111 dst_sel:DWORD dst_unused:UNUSED_PAD src0_sel:DWORD src1_sel:WORD_1
	v_mul_f32_e32 v111, 0xbfb8aa3b, v142
	v_or_b32_sdwa v114, v116, v114 dst_sel:DWORD dst_unused:UNUSED_PAD src0_sel:DWORD src1_sel:WORD_1
	v_exp_f32_e32 v111, v111
	v_mul_f32_e32 v116, 0xbfb8aa3b, v143
	v_exp_f32_e32 v116, v116
	global_store_dwordx2 v[112:113], v[114:115], off offset:32
	v_add_f32_e32 v111, 1.0, v111
	v_mul_f32_e32 v115, 0xbfb8aa3b, v144
	v_rcp_f32_e32 v114, v111
	v_add_f32_e32 v111, 1.0, v116
	v_exp_f32_e32 v115, v115
	v_mul_f32_e32 v116, 0xbfb8aa3b, v145
	v_exp_f32_e32 v117, v116
	v_rcp_f32_e32 v116, v111
	v_add_f32_e32 v111, 1.0, v115
	v_rcp_f32_e32 v115, v111
	v_add_f32_e32 v111, 1.0, v117
	v_rcp_f32_e32 v117, v111
	v_mov_b32_e32 v118, v142
	v_mov_b32_e32 v119, v144
	v_pk_mul_f32 v[114:115], v[118:119], v[114:115]
	v_mov_b32_e32 v118, v138
	v_mov_b32_e32 v119, v140
	v_mov_b32_e32 v144, v143
	v_pk_mul_f32 v[114:115], v[118:119], v[114:115]
	v_pk_mul_f32 v[116:117], v[144:145], v[116:117]
	v_mov_b32_e32 v140, v139
	v_pk_mul_f32 v[116:117], v[140:141], v[116:117]
	v_and_b32_sdwa v111, v115, v177 dst_sel:DWORD dst_unused:UNUSED_PAD src0_sel:WORD_1 src1_sel:DWORD
	v_and_b32_sdwa v118, v114, v177 dst_sel:DWORD dst_unused:UNUSED_PAD src0_sel:WORD_1 src1_sel:DWORD
	v_add3_u32 v111, v115, v111, s28
	v_and_b32_sdwa v115, v117, v177 dst_sel:DWORD dst_unused:UNUSED_PAD src0_sel:WORD_1 src1_sel:DWORD
	v_add3_u32 v114, v114, v118, s28
	v_and_b32_sdwa v118, v116, v177 dst_sel:DWORD dst_unused:UNUSED_PAD src0_sel:WORD_1 src1_sel:DWORD
	v_add3_u32 v115, v117, v115, s28
	v_add3_u32 v116, v116, v118, s28
	v_and_b32_e32 v115, 0xffff0000, v115
	v_and_b32_e32 v116, 0xffff0000, v116
	v_or_b32_sdwa v115, v115, v111 dst_sel:DWORD dst_unused:UNUSED_PAD src0_sel:DWORD src1_sel:WORD_1
	v_mul_f32_e32 v111, 0xbfb8aa3b, v102
	v_or_b32_sdwa v114, v116, v114 dst_sel:DWORD dst_unused:UNUSED_PAD src0_sel:DWORD src1_sel:WORD_1
	v_exp_f32_e32 v111, v111
	v_mul_f32_e32 v116, 0xbfb8aa3b, v103
	v_exp_f32_e32 v116, v116
	global_store_dwordx2 v[112:113], v[114:115], off offset:64
	v_add_f32_e32 v111, 1.0, v111
	v_mul_f32_e32 v115, 0xbfb8aa3b, v104
	v_rcp_f32_e32 v114, v111
	v_add_f32_e32 v111, 1.0, v116
	v_exp_f32_e32 v115, v115
	v_mul_f32_e32 v116, 0xbfb8aa3b, v105
	v_exp_f32_e32 v117, v116
	v_rcp_f32_e32 v116, v111
	v_add_f32_e32 v111, 1.0, v115
	v_rcp_f32_e32 v115, v111
	v_add_f32_e32 v111, 1.0, v117
	v_rcp_f32_e32 v117, v111
	v_mov_b32_e32 v118, v102
	v_mov_b32_e32 v119, v104
	v_mov_b32_e32 v104, v103
	v_pk_mul_f32 v[114:115], v[118:119], v[114:115]
	v_mov_b32_e32 v119, v100
	v_pk_mul_f32 v[102:103], v[104:105], v[116:117]
	v_mov_b32_e32 v100, v99
	v_mov_b32_e32 v118, v98
	v_pk_mul_f32 v[98:99], v[100:101], v[102:103]
	v_pk_mul_f32 v[114:115], v[118:119], v[114:115]
	v_and_b32_sdwa v102, v99, v177 dst_sel:DWORD dst_unused:UNUSED_PAD src0_sel:WORD_1 src1_sel:DWORD
	v_and_b32_sdwa v103, v98, v177 dst_sel:DWORD dst_unused:UNUSED_PAD src0_sel:WORD_1 src1_sel:DWORD
	v_and_b32_sdwa v100, v115, v177 dst_sel:DWORD dst_unused:UNUSED_PAD src0_sel:WORD_1 src1_sel:DWORD
	v_and_b32_sdwa v101, v114, v177 dst_sel:DWORD dst_unused:UNUSED_PAD src0_sel:WORD_1 src1_sel:DWORD
	v_add3_u32 v99, v99, v102, s28
	v_add3_u32 v98, v98, v103, s28
	v_add3_u32 v101, v114, v101, s28
	v_add3_u32 v100, v115, v100, s28
	v_and_b32_e32 v99, 0xffff0000, v99
	v_and_b32_e32 v98, 0xffff0000, v98
	v_or_b32_sdwa v99, v99, v100 dst_sel:DWORD dst_unused:UNUSED_PAD src0_sel:DWORD src1_sel:WORD_1
	v_or_b32_sdwa v98, v98, v101 dst_sel:DWORD dst_unused:UNUSED_PAD src0_sel:DWORD src1_sel:WORD_1
	global_store_dwordx2 v[112:113], v[98:99], off offset:96
	v_mul_f32_e32 v99, 0xbfb8aa3b, v94
	v_exp_f32_e32 v100, v99
	v_mul_f32_e32 v99, 0xbfb8aa3b, v95
	v_mul_f32_e32 v102, 0xbfb8aa3b, v96
	v_exp_f32_e32 v101, v99
	v_exp_f32_e32 v103, v102
	v_mul_f32_e32 v102, 0xbfb8aa3b, v97
	v_exp_f32_e32 v104, v102
	v_add_f32_e32 v101, 1.0, v101
	v_add_f32_e32 v100, 1.0, v100
	v_rcp_f32_e32 v102, v101
	v_add_f32_e32 v101, 1.0, v103
	v_add_f32_e32 v103, 1.0, v104
	v_rcp_f32_e32 v100, v100
	v_rcp_f32_e32 v101, v101
	v_rcp_f32_e32 v103, v103
	v_mov_b32_e32 v104, v94
	v_mov_b32_e32 v105, v96
	v_mov_b32_e32 v96, v95
	v_pk_mul_f32 v[100:101], v[104:105], v[100:101]
	v_mov_b32_e32 v105, v92
	v_pk_mul_f32 v[94:95], v[96:97], v[102:103]
	v_mov_b32_e32 v92, v91
	v_mov_b32_e32 v104, v90
	v_pk_mul_f32 v[90:91], v[92:93], v[94:95]
	v_pk_mul_f32 v[100:101], v[104:105], v[100:101]
	v_and_b32_sdwa v94, v91, v177 dst_sel:DWORD dst_unused:UNUSED_PAD src0_sel:WORD_1 src1_sel:DWORD
	v_and_b32_sdwa v92, v101, v177 dst_sel:DWORD dst_unused:UNUSED_PAD src0_sel:WORD_1 src1_sel:DWORD
	v_and_b32_sdwa v95, v90, v177 dst_sel:DWORD dst_unused:UNUSED_PAD src0_sel:WORD_1 src1_sel:DWORD
	v_add3_u32 v91, v91, v94, s28
	v_and_b32_sdwa v93, v100, v177 dst_sel:DWORD dst_unused:UNUSED_PAD src0_sel:WORD_1 src1_sel:DWORD
	v_add3_u32 v92, v101, v92, s28
	v_add3_u32 v90, v90, v95, s28
	v_and_b32_e32 v91, 0xffff0000, v91
	v_add3_u32 v93, v100, v93, s28
	v_and_b32_e32 v90, 0xffff0000, v90
	v_or_b32_sdwa v91, v91, v92 dst_sel:DWORD dst_unused:UNUSED_PAD src0_sel:DWORD src1_sel:WORD_1
	v_mul_f32_e32 v92, 0xbfb8aa3b, v86
	v_or_b32_sdwa v90, v90, v93 dst_sel:DWORD dst_unused:UNUSED_PAD src0_sel:DWORD src1_sel:WORD_1
	v_exp_f32_e32 v92, v92
	v_mul_f32_e32 v93, 0xbfb8aa3b, v87
	v_or_b32_e32 v98, 16, v110
	v_exp_f32_e32 v93, v93
	v_mad_i64_i32 v[98:99], s[6:7], v98, s52, v[106:107]
	v_lshl_add_u64 v[98:99], v[98:99], 0, v[108:109]
	global_store_dwordx2 v[98:99], v[90:91], off
	v_add_f32_e32 v90, 1.0, v92
	v_mul_f32_e32 v92, 0xbfb8aa3b, v88
	v_add_f32_e32 v91, 1.0, v93
	v_exp_f32_e32 v93, v92
	v_mul_f32_e32 v92, 0xbfb8aa3b, v89
	v_exp_f32_e32 v94, v92
	v_rcp_f32_e32 v92, v91
	v_add_f32_e32 v91, 1.0, v93
	v_rcp_f32_e32 v90, v90
	v_add_f32_e32 v93, 1.0, v94
	v_rcp_f32_e32 v91, v91
	v_rcp_f32_e32 v93, v93
	v_mov_b32_e32 v94, v86
	v_mov_b32_e32 v95, v88
	v_mov_b32_e32 v88, v87
	v_pk_mul_f32 v[90:91], v[94:95], v[90:91]
	v_mov_b32_e32 v95, v84
	v_pk_mul_f32 v[86:87], v[88:89], v[92:93]
	v_mov_b32_e32 v84, v83
	v_mov_b32_e32 v94, v82
	v_pk_mul_f32 v[82:83], v[84:85], v[86:87]
	v_pk_mul_f32 v[90:91], v[94:95], v[90:91]
	v_and_b32_sdwa v86, v83, v177 dst_sel:DWORD dst_unused:UNUSED_PAD src0_sel:WORD_1 src1_sel:DWORD
	v_and_b32_sdwa v84, v91, v177 dst_sel:DWORD dst_unused:UNUSED_PAD src0_sel:WORD_1 src1_sel:DWORD
	v_and_b32_sdwa v87, v82, v177 dst_sel:DWORD dst_unused:UNUSED_PAD src0_sel:WORD_1 src1_sel:DWORD
	v_add3_u32 v83, v83, v86, s28
	v_and_b32_sdwa v85, v90, v177 dst_sel:DWORD dst_unused:UNUSED_PAD src0_sel:WORD_1 src1_sel:DWORD
	v_add3_u32 v84, v91, v84, s28
	v_add3_u32 v82, v82, v87, s28
	v_and_b32_e32 v83, 0xffff0000, v83
	v_add3_u32 v85, v90, v85, s28
	v_and_b32_e32 v82, 0xffff0000, v82
	v_or_b32_sdwa v83, v83, v84 dst_sel:DWORD dst_unused:UNUSED_PAD src0_sel:DWORD src1_sel:WORD_1
	v_mul_f32_e32 v84, 0xbfb8aa3b, v78
	v_or_b32_sdwa v82, v82, v85 dst_sel:DWORD dst_unused:UNUSED_PAD src0_sel:DWORD src1_sel:WORD_1
	v_exp_f32_e32 v84, v84
	v_mul_f32_e32 v85, 0xbfb8aa3b, v79
	v_exp_f32_e32 v85, v85
	global_store_dwordx2 v[98:99], v[82:83], off offset:32
	v_add_f32_e32 v82, 1.0, v84
	v_mul_f32_e32 v84, 0xbfb8aa3b, v80
	v_add_f32_e32 v83, 1.0, v85
	v_exp_f32_e32 v85, v84
	v_mul_f32_e32 v84, 0xbfb8aa3b, v81
	v_exp_f32_e32 v86, v84
	v_rcp_f32_e32 v84, v83
	v_add_f32_e32 v83, 1.0, v85
	v_rcp_f32_e32 v82, v82
	v_add_f32_e32 v85, 1.0, v86
	v_rcp_f32_e32 v83, v83
	v_rcp_f32_e32 v85, v85
	v_mov_b32_e32 v86, v78
	v_mov_b32_e32 v87, v80
	v_mov_b32_e32 v80, v79
	v_pk_mul_f32 v[82:83], v[86:87], v[82:83]
	v_mov_b32_e32 v87, v76
	v_pk_mul_f32 v[78:79], v[80:81], v[84:85]
	v_mov_b32_e32 v76, v75
	v_mov_b32_e32 v86, v74
	v_pk_mul_f32 v[74:75], v[76:77], v[78:79]
	v_pk_mul_f32 v[82:83], v[86:87], v[82:83]
	v_and_b32_sdwa v78, v75, v177 dst_sel:DWORD dst_unused:UNUSED_PAD src0_sel:WORD_1 src1_sel:DWORD
	v_and_b32_sdwa v76, v83, v177 dst_sel:DWORD dst_unused:UNUSED_PAD src0_sel:WORD_1 src1_sel:DWORD
	v_and_b32_sdwa v79, v74, v177 dst_sel:DWORD dst_unused:UNUSED_PAD src0_sel:WORD_1 src1_sel:DWORD
	v_add3_u32 v75, v75, v78, s28
	v_and_b32_sdwa v77, v82, v177 dst_sel:DWORD dst_unused:UNUSED_PAD src0_sel:WORD_1 src1_sel:DWORD
	v_add3_u32 v76, v83, v76, s28
	v_add3_u32 v74, v74, v79, s28
	v_and_b32_e32 v75, 0xffff0000, v75
	v_add3_u32 v77, v82, v77, s28
	v_and_b32_e32 v74, 0xffff0000, v74
	v_or_b32_sdwa v75, v75, v76 dst_sel:DWORD dst_unused:UNUSED_PAD src0_sel:DWORD src1_sel:WORD_1
	v_mul_f32_e32 v76, 0xbfb8aa3b, v70
	v_or_b32_sdwa v74, v74, v77 dst_sel:DWORD dst_unused:UNUSED_PAD src0_sel:DWORD src1_sel:WORD_1
	v_exp_f32_e32 v76, v76
	v_mul_f32_e32 v77, 0xbfb8aa3b, v71
	v_exp_f32_e32 v77, v77
	global_store_dwordx2 v[98:99], v[74:75], off offset:64
	v_add_f32_e32 v74, 1.0, v76
	v_mul_f32_e32 v76, 0xbfb8aa3b, v72
	v_add_f32_e32 v75, 1.0, v77
	v_exp_f32_e32 v77, v76
	v_mul_f32_e32 v76, 0xbfb8aa3b, v73
	v_exp_f32_e32 v78, v76
	v_rcp_f32_e32 v76, v75
	v_add_f32_e32 v75, 1.0, v77
	v_rcp_f32_e32 v74, v74
	v_add_f32_e32 v77, 1.0, v78
	v_rcp_f32_e32 v75, v75
	v_rcp_f32_e32 v77, v77
	v_mov_b32_e32 v78, v70
	v_mov_b32_e32 v79, v72
	v_mov_b32_e32 v72, v71
	v_pk_mul_f32 v[74:75], v[78:79], v[74:75]
	v_mov_b32_e32 v79, v68
	v_pk_mul_f32 v[70:71], v[72:73], v[76:77]
	v_mov_b32_e32 v68, v67
	v_mov_b32_e32 v78, v66
	v_pk_mul_f32 v[66:67], v[68:69], v[70:71]
	v_pk_mul_f32 v[74:75], v[78:79], v[74:75]
	v_and_b32_sdwa v70, v67, v177 dst_sel:DWORD dst_unused:UNUSED_PAD src0_sel:WORD_1 src1_sel:DWORD
	v_and_b32_sdwa v71, v66, v177 dst_sel:DWORD dst_unused:UNUSED_PAD src0_sel:WORD_1 src1_sel:DWORD
	v_and_b32_sdwa v68, v75, v177 dst_sel:DWORD dst_unused:UNUSED_PAD src0_sel:WORD_1 src1_sel:DWORD
	v_and_b32_sdwa v69, v74, v177 dst_sel:DWORD dst_unused:UNUSED_PAD src0_sel:WORD_1 src1_sel:DWORD
	v_add3_u32 v67, v67, v70, s28
	v_add3_u32 v66, v66, v71, s28
	v_add3_u32 v69, v74, v69, s28
	v_add3_u32 v68, v75, v68, s28
	v_and_b32_e32 v67, 0xffff0000, v67
	v_and_b32_e32 v66, 0xffff0000, v66
	v_or_b32_sdwa v67, v67, v68 dst_sel:DWORD dst_unused:UNUSED_PAD src0_sel:DWORD src1_sel:WORD_1
	v_or_b32_sdwa v66, v66, v69 dst_sel:DWORD dst_unused:UNUSED_PAD src0_sel:DWORD src1_sel:WORD_1
	global_store_dwordx2 v[98:99], v[66:67], off offset:96
	v_mul_f32_e32 v67, 0xbfb8aa3b, v62
	v_exp_f32_e32 v68, v67
	v_mul_f32_e32 v67, 0xbfb8aa3b, v63
	v_mul_f32_e32 v70, 0xbfb8aa3b, v64
	v_exp_f32_e32 v69, v67
	v_exp_f32_e32 v71, v70
	v_mul_f32_e32 v70, 0xbfb8aa3b, v65
	v_exp_f32_e32 v72, v70
	v_add_f32_e32 v69, 1.0, v69
	v_add_f32_e32 v68, 1.0, v68
	v_rcp_f32_e32 v70, v69
	v_add_f32_e32 v69, 1.0, v71
	v_add_f32_e32 v71, 1.0, v72
	v_rcp_f32_e32 v68, v68
	v_rcp_f32_e32 v69, v69
	v_rcp_f32_e32 v71, v71
	v_mov_b32_e32 v72, v62
	v_mov_b32_e32 v73, v64
	v_mov_b32_e32 v64, v63
	v_pk_mul_f32 v[68:69], v[72:73], v[68:69]
	v_mov_b32_e32 v73, v60
	v_pk_mul_f32 v[62:63], v[64:65], v[70:71]
	v_mov_b32_e32 v60, v59
	v_mov_b32_e32 v72, v58
	v_pk_mul_f32 v[58:59], v[60:61], v[62:63]
	v_pk_mul_f32 v[68:69], v[72:73], v[68:69]
	v_and_b32_sdwa v62, v59, v177 dst_sel:DWORD dst_unused:UNUSED_PAD src0_sel:WORD_1 src1_sel:DWORD
	v_and_b32_sdwa v60, v69, v177 dst_sel:DWORD dst_unused:UNUSED_PAD src0_sel:WORD_1 src1_sel:DWORD
	v_and_b32_sdwa v63, v58, v177 dst_sel:DWORD dst_unused:UNUSED_PAD src0_sel:WORD_1 src1_sel:DWORD
	v_add3_u32 v59, v59, v62, s28
	v_and_b32_sdwa v61, v68, v177 dst_sel:DWORD dst_unused:UNUSED_PAD src0_sel:WORD_1 src1_sel:DWORD
	v_add3_u32 v60, v69, v60, s28
	v_add3_u32 v58, v58, v63, s28
	v_and_b32_e32 v59, 0xffff0000, v59
	v_add3_u32 v61, v68, v61, s28
	v_and_b32_e32 v58, 0xffff0000, v58
	v_or_b32_sdwa v59, v59, v60 dst_sel:DWORD dst_unused:UNUSED_PAD src0_sel:DWORD src1_sel:WORD_1
	v_mul_f32_e32 v60, 0xbfb8aa3b, v54
	v_or_b32_sdwa v58, v58, v61 dst_sel:DWORD dst_unused:UNUSED_PAD src0_sel:DWORD src1_sel:WORD_1
	v_exp_f32_e32 v60, v60
	v_mul_f32_e32 v61, 0xbfb8aa3b, v55
	v_or_b32_e32 v66, 32, v110
	v_exp_f32_e32 v61, v61
	v_mad_i64_i32 v[66:67], s[6:7], v66, s52, v[106:107]
	v_lshl_add_u64 v[66:67], v[66:67], 0, v[108:109]
	global_store_dwordx2 v[66:67], v[58:59], off
	v_add_f32_e32 v58, 1.0, v60
	v_mul_f32_e32 v60, 0xbfb8aa3b, v56
	v_add_f32_e32 v59, 1.0, v61
	v_exp_f32_e32 v61, v60
	v_mul_f32_e32 v60, 0xbfb8aa3b, v57
	v_exp_f32_e32 v62, v60
	v_rcp_f32_e32 v60, v59
	v_add_f32_e32 v59, 1.0, v61
	v_rcp_f32_e32 v58, v58
	v_add_f32_e32 v61, 1.0, v62
	v_rcp_f32_e32 v59, v59
	v_rcp_f32_e32 v61, v61
	v_mov_b32_e32 v62, v54
	v_mov_b32_e32 v63, v56
	v_mov_b32_e32 v56, v55
	v_pk_mul_f32 v[58:59], v[62:63], v[58:59]
	v_mov_b32_e32 v63, v52
	v_pk_mul_f32 v[54:55], v[56:57], v[60:61]
	v_mov_b32_e32 v52, v51
	v_mov_b32_e32 v62, v50
	v_pk_mul_f32 v[50:51], v[52:53], v[54:55]
	v_pk_mul_f32 v[58:59], v[62:63], v[58:59]
	v_and_b32_sdwa v54, v51, v177 dst_sel:DWORD dst_unused:UNUSED_PAD src0_sel:WORD_1 src1_sel:DWORD
	v_and_b32_sdwa v52, v59, v177 dst_sel:DWORD dst_unused:UNUSED_PAD src0_sel:WORD_1 src1_sel:DWORD
	v_and_b32_sdwa v55, v50, v177 dst_sel:DWORD dst_unused:UNUSED_PAD src0_sel:WORD_1 src1_sel:DWORD
	v_add3_u32 v51, v51, v54, s28
	v_and_b32_sdwa v53, v58, v177 dst_sel:DWORD dst_unused:UNUSED_PAD src0_sel:WORD_1 src1_sel:DWORD
	v_add3_u32 v52, v59, v52, s28
	v_add3_u32 v50, v50, v55, s28
	v_and_b32_e32 v51, 0xffff0000, v51
	v_add3_u32 v53, v58, v53, s28
	v_and_b32_e32 v50, 0xffff0000, v50
	v_or_b32_sdwa v51, v51, v52 dst_sel:DWORD dst_unused:UNUSED_PAD src0_sel:DWORD src1_sel:WORD_1
	v_mul_f32_e32 v52, 0xbfb8aa3b, v46
	v_or_b32_sdwa v50, v50, v53 dst_sel:DWORD dst_unused:UNUSED_PAD src0_sel:DWORD src1_sel:WORD_1
	v_exp_f32_e32 v52, v52
	v_mul_f32_e32 v53, 0xbfb8aa3b, v47
	v_exp_f32_e32 v53, v53
	global_store_dwordx2 v[66:67], v[50:51], off offset:32
	v_add_f32_e32 v50, 1.0, v52
	v_mul_f32_e32 v52, 0xbfb8aa3b, v48
	v_add_f32_e32 v51, 1.0, v53
	v_exp_f32_e32 v53, v52
	v_mul_f32_e32 v52, 0xbfb8aa3b, v49
	v_exp_f32_e32 v54, v52
	v_rcp_f32_e32 v52, v51
	v_add_f32_e32 v51, 1.0, v53
	v_rcp_f32_e32 v50, v50
	v_add_f32_e32 v53, 1.0, v54
	v_rcp_f32_e32 v51, v51
	v_rcp_f32_e32 v53, v53
	v_mov_b32_e32 v54, v46
	v_mov_b32_e32 v55, v48
	v_mov_b32_e32 v48, v47
	v_pk_mul_f32 v[50:51], v[54:55], v[50:51]
	v_mov_b32_e32 v55, v44
	v_pk_mul_f32 v[46:47], v[48:49], v[52:53]
	v_mov_b32_e32 v44, v43
	v_mov_b32_e32 v54, v42
	v_pk_mul_f32 v[42:43], v[44:45], v[46:47]
	v_pk_mul_f32 v[50:51], v[54:55], v[50:51]
	v_and_b32_sdwa v46, v43, v177 dst_sel:DWORD dst_unused:UNUSED_PAD src0_sel:WORD_1 src1_sel:DWORD
	v_and_b32_sdwa v44, v51, v177 dst_sel:DWORD dst_unused:UNUSED_PAD src0_sel:WORD_1 src1_sel:DWORD
	v_and_b32_sdwa v47, v42, v177 dst_sel:DWORD dst_unused:UNUSED_PAD src0_sel:WORD_1 src1_sel:DWORD
	v_add3_u32 v43, v43, v46, s28
	v_and_b32_sdwa v45, v50, v177 dst_sel:DWORD dst_unused:UNUSED_PAD src0_sel:WORD_1 src1_sel:DWORD
	v_add3_u32 v44, v51, v44, s28
	v_add3_u32 v42, v42, v47, s28
	v_and_b32_e32 v43, 0xffff0000, v43
	v_add3_u32 v45, v50, v45, s28
	v_and_b32_e32 v42, 0xffff0000, v42
	v_or_b32_sdwa v43, v43, v44 dst_sel:DWORD dst_unused:UNUSED_PAD src0_sel:DWORD src1_sel:WORD_1
	v_mul_f32_e32 v44, 0xbfb8aa3b, v38
	v_or_b32_sdwa v42, v42, v45 dst_sel:DWORD dst_unused:UNUSED_PAD src0_sel:DWORD src1_sel:WORD_1
	v_exp_f32_e32 v44, v44
	v_mul_f32_e32 v45, 0xbfb8aa3b, v39
	v_exp_f32_e32 v45, v45
	global_store_dwordx2 v[66:67], v[42:43], off offset:64
	v_add_f32_e32 v42, 1.0, v44
	v_mul_f32_e32 v44, 0xbfb8aa3b, v40
	v_add_f32_e32 v43, 1.0, v45
	v_exp_f32_e32 v45, v44
	v_mul_f32_e32 v44, 0xbfb8aa3b, v41
	v_exp_f32_e32 v46, v44
	v_rcp_f32_e32 v44, v43
	v_add_f32_e32 v43, 1.0, v45
	v_rcp_f32_e32 v42, v42
	v_add_f32_e32 v45, 1.0, v46
	v_rcp_f32_e32 v43, v43
	v_rcp_f32_e32 v45, v45
	v_mov_b32_e32 v46, v38
	v_mov_b32_e32 v47, v40
	v_mov_b32_e32 v40, v39
	v_pk_mul_f32 v[42:43], v[46:47], v[42:43]
	v_mov_b32_e32 v47, v36
	v_pk_mul_f32 v[38:39], v[40:41], v[44:45]
	v_mov_b32_e32 v36, v35
	v_mov_b32_e32 v46, v34
	v_pk_mul_f32 v[34:35], v[36:37], v[38:39]
	v_pk_mul_f32 v[42:43], v[46:47], v[42:43]
	v_and_b32_sdwa v38, v35, v177 dst_sel:DWORD dst_unused:UNUSED_PAD src0_sel:WORD_1 src1_sel:DWORD
	v_and_b32_sdwa v39, v34, v177 dst_sel:DWORD dst_unused:UNUSED_PAD src0_sel:WORD_1 src1_sel:DWORD
	v_and_b32_sdwa v36, v43, v177 dst_sel:DWORD dst_unused:UNUSED_PAD src0_sel:WORD_1 src1_sel:DWORD
	v_and_b32_sdwa v37, v42, v177 dst_sel:DWORD dst_unused:UNUSED_PAD src0_sel:WORD_1 src1_sel:DWORD
	v_add3_u32 v35, v35, v38, s28
	v_add3_u32 v34, v34, v39, s28
	v_add3_u32 v37, v42, v37, s28
	v_add3_u32 v36, v43, v36, s28
	v_and_b32_e32 v35, 0xffff0000, v35
	v_and_b32_e32 v34, 0xffff0000, v34
	v_or_b32_sdwa v35, v35, v36 dst_sel:DWORD dst_unused:UNUSED_PAD src0_sel:DWORD src1_sel:WORD_1
	v_or_b32_sdwa v34, v34, v37 dst_sel:DWORD dst_unused:UNUSED_PAD src0_sel:DWORD src1_sel:WORD_1
	global_store_dwordx2 v[66:67], v[34:35], off offset:96
	v_mul_f32_e32 v35, 0xbfb8aa3b, v30
	v_exp_f32_e32 v36, v35
	v_mul_f32_e32 v35, 0xbfb8aa3b, v31
	v_mul_f32_e32 v38, 0xbfb8aa3b, v32
	v_exp_f32_e32 v37, v35
	v_exp_f32_e32 v39, v38
	v_mul_f32_e32 v38, 0xbfb8aa3b, v33
	v_exp_f32_e32 v40, v38
	v_add_f32_e32 v37, 1.0, v37
	v_add_f32_e32 v36, 1.0, v36
	v_rcp_f32_e32 v38, v37
	v_add_f32_e32 v37, 1.0, v39
	v_add_f32_e32 v39, 1.0, v40
	v_rcp_f32_e32 v36, v36
	v_rcp_f32_e32 v37, v37
	v_rcp_f32_e32 v39, v39
	v_mov_b32_e32 v40, v30
	v_mov_b32_e32 v41, v32
	v_mov_b32_e32 v32, v31
	v_pk_mul_f32 v[36:37], v[40:41], v[36:37]
	v_mov_b32_e32 v41, v28
	v_pk_mul_f32 v[30:31], v[32:33], v[38:39]
	v_mov_b32_e32 v28, v27
	v_mov_b32_e32 v40, v26
	v_pk_mul_f32 v[26:27], v[28:29], v[30:31]
	v_pk_mul_f32 v[36:37], v[40:41], v[36:37]
	v_and_b32_sdwa v30, v27, v177 dst_sel:DWORD dst_unused:UNUSED_PAD src0_sel:WORD_1 src1_sel:DWORD
	v_and_b32_sdwa v28, v37, v177 dst_sel:DWORD dst_unused:UNUSED_PAD src0_sel:WORD_1 src1_sel:DWORD
	v_and_b32_sdwa v31, v26, v177 dst_sel:DWORD dst_unused:UNUSED_PAD src0_sel:WORD_1 src1_sel:DWORD
	v_add3_u32 v27, v27, v30, s28
	v_and_b32_sdwa v29, v36, v177 dst_sel:DWORD dst_unused:UNUSED_PAD src0_sel:WORD_1 src1_sel:DWORD
	v_add3_u32 v28, v37, v28, s28
	v_add3_u32 v26, v26, v31, s28
	v_and_b32_e32 v27, 0xffff0000, v27
	v_add3_u32 v29, v36, v29, s28
	v_and_b32_e32 v26, 0xffff0000, v26
	v_or_b32_sdwa v27, v27, v28 dst_sel:DWORD dst_unused:UNUSED_PAD src0_sel:DWORD src1_sel:WORD_1
	v_mul_f32_e32 v28, 0xbfb8aa3b, v22
	v_or_b32_sdwa v26, v26, v29 dst_sel:DWORD dst_unused:UNUSED_PAD src0_sel:DWORD src1_sel:WORD_1
	v_exp_f32_e32 v28, v28
	v_mul_f32_e32 v29, 0xbfb8aa3b, v23
	v_or_b32_e32 v34, 48, v110
	v_exp_f32_e32 v29, v29
	v_mad_i64_i32 v[34:35], s[6:7], v34, s52, v[106:107]
	v_lshl_add_u64 v[34:35], v[34:35], 0, v[108:109]
	global_store_dwordx2 v[34:35], v[26:27], off
	v_add_f32_e32 v26, 1.0, v28
	v_mul_f32_e32 v28, 0xbfb8aa3b, v24
	v_add_f32_e32 v27, 1.0, v29
	v_exp_f32_e32 v29, v28
	v_mul_f32_e32 v28, 0xbfb8aa3b, v25
	v_exp_f32_e32 v30, v28
	v_rcp_f32_e32 v28, v27
	v_add_f32_e32 v27, 1.0, v29
	v_rcp_f32_e32 v26, v26
	v_add_f32_e32 v29, 1.0, v30
	v_rcp_f32_e32 v27, v27
	v_rcp_f32_e32 v29, v29
	v_mov_b32_e32 v30, v22
	v_mov_b32_e32 v31, v24
	v_mov_b32_e32 v24, v23
	v_pk_mul_f32 v[26:27], v[30:31], v[26:27]
	v_mov_b32_e32 v31, v20
	v_pk_mul_f32 v[22:23], v[24:25], v[28:29]
	v_mov_b32_e32 v20, v19
	v_mov_b32_e32 v30, v18
	v_pk_mul_f32 v[18:19], v[20:21], v[22:23]
	v_pk_mul_f32 v[26:27], v[30:31], v[26:27]
	v_and_b32_sdwa v22, v19, v177 dst_sel:DWORD dst_unused:UNUSED_PAD src0_sel:WORD_1 src1_sel:DWORD
	v_and_b32_sdwa v20, v27, v177 dst_sel:DWORD dst_unused:UNUSED_PAD src0_sel:WORD_1 src1_sel:DWORD
	v_and_b32_sdwa v23, v18, v177 dst_sel:DWORD dst_unused:UNUSED_PAD src0_sel:WORD_1 src1_sel:DWORD
	v_add3_u32 v19, v19, v22, s28
	v_and_b32_sdwa v21, v26, v177 dst_sel:DWORD dst_unused:UNUSED_PAD src0_sel:WORD_1 src1_sel:DWORD
	v_add3_u32 v20, v27, v20, s28
	v_add3_u32 v18, v18, v23, s28
	v_and_b32_e32 v19, 0xffff0000, v19
	v_add3_u32 v21, v26, v21, s28
	v_and_b32_e32 v18, 0xffff0000, v18
	v_or_b32_sdwa v19, v19, v20 dst_sel:DWORD dst_unused:UNUSED_PAD src0_sel:DWORD src1_sel:WORD_1
	v_mul_f32_e32 v20, 0xbfb8aa3b, v14
	v_or_b32_sdwa v18, v18, v21 dst_sel:DWORD dst_unused:UNUSED_PAD src0_sel:DWORD src1_sel:WORD_1
	v_exp_f32_e32 v20, v20
	v_mul_f32_e32 v21, 0xbfb8aa3b, v15
	v_exp_f32_e32 v21, v21
	global_store_dwordx2 v[34:35], v[18:19], off offset:32
	v_add_f32_e32 v18, 1.0, v20
	v_mul_f32_e32 v20, 0xbfb8aa3b, v16
	v_add_f32_e32 v19, 1.0, v21
	v_exp_f32_e32 v21, v20
	v_mul_f32_e32 v20, 0xbfb8aa3b, v17
	v_exp_f32_e32 v22, v20
	v_rcp_f32_e32 v20, v19
	v_add_f32_e32 v19, 1.0, v21
	v_rcp_f32_e32 v18, v18
	v_add_f32_e32 v21, 1.0, v22
	v_rcp_f32_e32 v19, v19
	v_rcp_f32_e32 v21, v21
	v_mov_b32_e32 v22, v14
	v_mov_b32_e32 v23, v16
	v_mov_b32_e32 v16, v15
	v_pk_mul_f32 v[18:19], v[22:23], v[18:19]
	v_mov_b32_e32 v23, v12
	v_pk_mul_f32 v[14:15], v[16:17], v[20:21]
	v_mov_b32_e32 v12, v11
	v_mov_b32_e32 v22, v10
	v_pk_mul_f32 v[10:11], v[12:13], v[14:15]
	v_pk_mul_f32 v[18:19], v[22:23], v[18:19]
	v_and_b32_sdwa v14, v11, v177 dst_sel:DWORD dst_unused:UNUSED_PAD src0_sel:WORD_1 src1_sel:DWORD
	v_and_b32_sdwa v12, v19, v177 dst_sel:DWORD dst_unused:UNUSED_PAD src0_sel:WORD_1 src1_sel:DWORD
	v_and_b32_sdwa v15, v10, v177 dst_sel:DWORD dst_unused:UNUSED_PAD src0_sel:WORD_1 src1_sel:DWORD
	v_add3_u32 v11, v11, v14, s28
	v_and_b32_sdwa v13, v18, v177 dst_sel:DWORD dst_unused:UNUSED_PAD src0_sel:WORD_1 src1_sel:DWORD
	v_add3_u32 v12, v19, v12, s28
	v_add3_u32 v10, v10, v15, s28
	v_and_b32_e32 v11, 0xffff0000, v11
	v_add3_u32 v13, v18, v13, s28
	v_and_b32_e32 v10, 0xffff0000, v10
	v_or_b32_sdwa v11, v11, v12 dst_sel:DWORD dst_unused:UNUSED_PAD src0_sel:DWORD src1_sel:WORD_1
	v_mul_f32_e32 v12, 0xbfb8aa3b, v6
	v_or_b32_sdwa v10, v10, v13 dst_sel:DWORD dst_unused:UNUSED_PAD src0_sel:DWORD src1_sel:WORD_1
	v_exp_f32_e32 v12, v12
	v_mul_f32_e32 v13, 0xbfb8aa3b, v7
	v_exp_f32_e32 v13, v13
	global_store_dwordx2 v[34:35], v[10:11], off offset:64
	v_add_f32_e32 v10, 1.0, v12
	v_mul_f32_e32 v12, 0xbfb8aa3b, v8
	v_add_f32_e32 v11, 1.0, v13
	v_exp_f32_e32 v13, v12
	v_mul_f32_e32 v12, 0xbfb8aa3b, v9
	v_exp_f32_e32 v14, v12
	v_rcp_f32_e32 v12, v11
	v_add_f32_e32 v11, 1.0, v13
	v_rcp_f32_e32 v10, v10
	v_add_f32_e32 v13, 1.0, v14
	v_rcp_f32_e32 v11, v11
	v_rcp_f32_e32 v13, v13
	v_mov_b32_e32 v14, v6
	v_mov_b32_e32 v15, v8
	v_mov_b32_e32 v8, v7
	v_pk_mul_f32 v[10:11], v[14:15], v[10:11]
	v_mov_b32_e32 v15, v4
	v_pk_mul_f32 v[6:7], v[8:9], v[12:13]
	v_mov_b32_e32 v4, v3
	v_mov_b32_e32 v14, v2
	v_pk_mul_f32 v[2:3], v[4:5], v[6:7]
	v_pk_mul_f32 v[10:11], v[14:15], v[10:11]
	v_and_b32_sdwa v6, v3, v177 dst_sel:DWORD dst_unused:UNUSED_PAD src0_sel:WORD_1 src1_sel:DWORD
	v_and_b32_sdwa v7, v2, v177 dst_sel:DWORD dst_unused:UNUSED_PAD src0_sel:WORD_1 src1_sel:DWORD
	v_and_b32_sdwa v4, v11, v177 dst_sel:DWORD dst_unused:UNUSED_PAD src0_sel:WORD_1 src1_sel:DWORD
	v_and_b32_sdwa v5, v10, v177 dst_sel:DWORD dst_unused:UNUSED_PAD src0_sel:WORD_1 src1_sel:DWORD
	v_add3_u32 v3, v3, v6, s28
	v_add3_u32 v2, v2, v7, s28
	v_add3_u32 v5, v10, v5, s28
	v_add3_u32 v4, v11, v4, s28
	v_and_b32_e32 v3, 0xffff0000, v3
	v_and_b32_e32 v2, 0xffff0000, v2
	s_add_i32 s20, s20, s11
	v_or_b32_sdwa v3, v3, v4 dst_sel:DWORD dst_unused:UNUSED_PAD src0_sel:DWORD src1_sel:WORD_1
	v_or_b32_sdwa v2, v2, v5 dst_sel:DWORD dst_unused:UNUSED_PAD src0_sel:DWORD src1_sel:WORD_1
	s_cmpk_gt_i32 s20, 0x5ff
	global_store_dwordx2 v[34:35], v[2:3], off offset:96
	s_cbranch_scc0 .LBB0_465

.LBB0_534:
	s_bitcmp1_b32 s4, 0
	s_cselect_b32 s21, 0x12000, 0
	v_or_b32_e32 v218, s21, v207
	v_add_u32_e32 v214, v218, v0
	v_add_u32_e32 v246, v218, v167
	ds_read_b128 v[184:187], v214
	ds_read_b128 v[218:221], v246 offset:32768
	ds_read_b128 v[198:201], v214 offset:2048
	ds_read_b128 v[210:213], v214 offset:4096
	ds_read_b128 v[214:217], v214 offset:6144
	ds_read_b128 v[222:225], v246 offset:34816
	ds_read_b128 v[226:229], v246 offset:36864
	ds_read_b128 v[230:233], v246 offset:38912
	ds_read_b128 v[234:237], v246 offset:40960
	ds_read_b128 v[238:241], v246 offset:43008
	ds_read_b128 v[242:245], v246 offset:45056
	ds_read_b128 v[246:249], v246 offset:47104
	s_add_i32 s20, s4, 1
	s_bitcmp1_b32 s20, 0
	s_cselect_b32 s23, 0x12000, 0
	v_add_u32_e32 v171, s23, v166
	v_xor_b32_e32 v169, 64, v207
	v_add3_u32 v169, s21, v167, v169
	s_waitcnt lgkmcnt(10)
	v_mfma_f32_16x16x32_bf16 v[158:161], v[218:221], v[184:187], v[158:161]
	s_waitcnt lgkmcnt(9)
	v_mfma_f32_16x16x32_bf16 v[94:97], v[218:221], v[198:201], v[94:97]
	s_waitcnt lgkmcnt(8)
	v_mfma_f32_16x16x32_bf16 v[62:65], v[218:221], v[210:213], v[62:65]
	s_waitcnt lgkmcnt(7)
	v_mfma_f32_16x16x32_bf16 v[30:33], v[218:221], v[214:217], v[30:33]
	ds_read_b128 v[218:221], v169 offset:32768
	s_waitcnt lgkmcnt(7)
	v_mfma_f32_16x16x32_bf16 v[154:157], v[222:225], v[184:187], v[154:157]
	v_mfma_f32_16x16x32_bf16 v[90:93], v[222:225], v[198:201], v[90:93]
	v_mfma_f32_16x16x32_bf16 v[58:61], v[222:225], v[210:213], v[58:61]
	v_mfma_f32_16x16x32_bf16 v[26:29], v[222:225], v[214:217], v[26:29]
	ds_read_b128 v[222:225], v169 offset:34816
	s_waitcnt lgkmcnt(7)
	v_mfma_f32_16x16x32_bf16 v[150:153], v[226:229], v[184:187], v[150:153]
	v_mfma_f32_16x16x32_bf16 v[86:89], v[226:229], v[198:201], v[86:89]
	v_mfma_f32_16x16x32_bf16 v[54:57], v[226:229], v[210:213], v[54:57]
	v_mfma_f32_16x16x32_bf16 v[22:25], v[226:229], v[214:217], v[22:25]
	ds_read_b128 v[226:229], v169 offset:36864
	s_waitcnt lgkmcnt(7)
	v_mfma_f32_16x16x32_bf16 v[146:149], v[230:233], v[184:187], v[146:149]
	v_mfma_f32_16x16x32_bf16 v[82:85], v[230:233], v[198:201], v[82:85]
	v_mfma_f32_16x16x32_bf16 v[50:53], v[230:233], v[210:213], v[50:53]
	v_mfma_f32_16x16x32_bf16 v[18:21], v[230:233], v[214:217], v[18:21]
	ds_read_b128 v[230:233], v169 offset:38912
	s_waitcnt lgkmcnt(7)
	v_mfma_f32_16x16x32_bf16 v[142:145], v[234:237], v[184:187], v[142:145]
	v_mfma_f32_16x16x32_bf16 v[78:81], v[234:237], v[198:201], v[78:81]
	v_mfma_f32_16x16x32_bf16 v[46:49], v[234:237], v[210:213], v[46:49]
	v_mfma_f32_16x16x32_bf16 v[14:17], v[234:237], v[214:217], v[14:17]
	ds_read_b128 v[234:237], v169 offset:40960
	s_waitcnt lgkmcnt(7)
	v_mfma_f32_16x16x32_bf16 v[138:141], v[238:241], v[184:187], v[138:141]
	v_mfma_f32_16x16x32_bf16 v[74:77], v[238:241], v[198:201], v[74:77]
	v_mfma_f32_16x16x32_bf16 v[42:45], v[238:241], v[210:213], v[42:45]
	v_mfma_f32_16x16x32_bf16 v[10:13], v[238:241], v[214:217], v[10:13]
	ds_read_b128 v[238:241], v169 offset:43008
	s_waitcnt lgkmcnt(7)
	v_mfma_f32_16x16x32_bf16 v[134:137], v[242:245], v[184:187], v[134:137]
	v_mfma_f32_16x16x32_bf16 v[70:73], v[242:245], v[198:201], v[70:73]
	v_mfma_f32_16x16x32_bf16 v[38:41], v[242:245], v[210:213], v[38:41]
	v_mfma_f32_16x16x32_bf16 v[6:9], v[242:245], v[214:217], v[6:9]
	ds_read_b128 v[242:245], v169 offset:45056
	s_waitcnt lgkmcnt(7)
	v_mfma_f32_16x16x32_bf16 v[98:101], v[246:249], v[184:187], v[98:101]
	v_mfma_f32_16x16x32_bf16 v[66:69], v[246:249], v[198:201], v[66:69]
	v_xor_b32_e32 v169, 64, v207
	v_add3_u32 v169, s21, v0, v169
	ds_read_b128 v[184:187], v169
	ds_read_b128 v[198:201], v169 offset:2048
	v_mfma_f32_16x16x32_bf16 v[34:37], v[246:249], v[210:213], v[34:37]
	ds_read_b128 v[210:213], v169 offset:4096
	v_mfma_f32_16x16x32_bf16 v[2:5], v[246:249], v[214:217], v[2:5]
	ds_read_b128 v[214:217], v169 offset:6144
	v_xor_b32_e32 v169, 64, v207
	v_add3_u32 v169, s21, v167, v169
	ds_read_b128 v[246:249], v169 offset:47104
	s_waitcnt lgkmcnt(4)
	v_mfma_f32_16x16x32_bf16 v[158:161], v[218:221], v[184:187], v[158:161]
	s_waitcnt lgkmcnt(3)
	v_mfma_f32_16x16x32_bf16 v[94:97], v[218:221], v[198:201], v[94:97]
	s_waitcnt lgkmcnt(2)
	v_mfma_f32_16x16x32_bf16 v[62:65], v[218:221], v[210:213], v[62:65]
	s_waitcnt lgkmcnt(1)
	v_mfma_f32_16x16x32_bf16 v[30:33], v[218:221], v[214:217], v[30:33]
	s_waitcnt vmcnt(7)
	ds_write_b128 v171, v[110:113]
	v_mfma_f32_16x16x32_bf16 v[154:157], v[222:225], v[184:187], v[154:157]
	v_mfma_f32_16x16x32_bf16 v[90:93], v[222:225], v[198:201], v[90:93]
	global_load_dwordx4 v[110:113], v168, vcc offset:256
	v_mfma_f32_16x16x32_bf16 v[58:61], v[222:225], v[210:213], v[58:61]
	v_mfma_f32_16x16x32_bf16 v[26:29], v[222:225], v[214:217], v[26:29]
	s_waitcnt vmcnt(7)
	ds_write_b128 v171, v[102:105] offset:8192
	v_mfma_f32_16x16x32_bf16 v[150:153], v[226:229], v[184:187], v[150:153]
	v_mfma_f32_16x16x32_bf16 v[86:89], v[226:229], v[198:201], v[86:89]
	v_add_u32_e32 v102, 0x58000, v168
	global_load_dwordx4 v[102:105], v102, vcc offset:256
	v_mfma_f32_16x16x32_bf16 v[54:57], v[226:229], v[210:213], v[54:57]
	v_mfma_f32_16x16x32_bf16 v[22:25], v[226:229], v[214:217], v[22:25]
	s_waitcnt vmcnt(7)
	ds_write_b128 v171, v[106:109] offset:16384
	v_mfma_f32_16x16x32_bf16 v[146:149], v[230:233], v[184:187], v[146:149]
	v_mfma_f32_16x16x32_bf16 v[82:85], v[230:233], v[198:201], v[82:85]
	v_add_u32_e32 v106, 0xb0000, v168
	global_load_dwordx4 v[106:109], v106, vcc offset:256
	v_mfma_f32_16x16x32_bf16 v[50:53], v[230:233], v[210:213], v[50:53]
	v_mfma_f32_16x16x32_bf16 v[18:21], v[230:233], v[214:217], v[18:21]
	s_waitcnt vmcnt(7)
	ds_write_b128 v171, v[122:125] offset:24576
	v_mfma_f32_16x16x32_bf16 v[142:145], v[234:237], v[184:187], v[142:145]
	v_mfma_f32_16x16x32_bf16 v[78:81], v[234:237], v[198:201], v[78:81]
	v_add_u32_e32 v122, 0x108000, v168
	global_load_dwordx4 v[122:125], v122, vcc offset:256
	v_mfma_f32_16x16x32_bf16 v[46:49], v[234:237], v[210:213], v[46:49]
	v_mfma_f32_16x16x32_bf16 v[14:17], v[234:237], v[214:217], v[14:17]
	s_waitcnt vmcnt(7)
	ds_write_b128 v171, v[118:121] offset:32768
	v_mfma_f32_16x16x32_bf16 v[138:141], v[238:241], v[184:187], v[138:141]
	v_mfma_f32_16x16x32_bf16 v[74:77], v[238:241], v[198:201], v[74:77]
	global_load_dwordx4 v[118:121], v170, s[100:101] offset:256
	v_mfma_f32_16x16x32_bf16 v[42:45], v[238:241], v[210:213], v[42:45]
	v_mfma_f32_16x16x32_bf16 v[10:13], v[238:241], v[214:217], v[10:13]
	s_waitcnt vmcnt(7)
	ds_write_b128 v171, v[114:117] offset:40960
	v_mfma_f32_16x16x32_bf16 v[134:137], v[242:245], v[184:187], v[134:137]
	v_mfma_f32_16x16x32_bf16 v[70:73], v[242:245], v[198:201], v[70:73]
	v_add_u32_e32 v114, 0x58000, v170
	global_load_dwordx4 v[114:117], v114, s[100:101] offset:256
	v_mfma_f32_16x16x32_bf16 v[38:41], v[242:245], v[210:213], v[38:41]
	v_mfma_f32_16x16x32_bf16 v[6:9], v[242:245], v[214:217], v[6:9]
	s_waitcnt vmcnt(7)
	ds_write_b128 v171, v[130:133] offset:49152
	s_waitcnt lgkmcnt(7)
	v_mfma_f32_16x16x32_bf16 v[98:101], v[246:249], v[184:187], v[98:101]
	v_mfma_f32_16x16x32_bf16 v[66:69], v[246:249], v[198:201], v[66:69]
	v_add_u32_e32 v130, 0xb0000, v170
	global_load_dwordx4 v[130:133], v130, s[100:101] offset:256
	v_mfma_f32_16x16x32_bf16 v[34:37], v[246:249], v[210:213], v[34:37]
	v_mfma_f32_16x16x32_bf16 v[2:5], v[246:249], v[214:217], v[2:5]
	s_waitcnt vmcnt(7)
	ds_write_b128 v171, v[126:129] offset:57344
	v_add_u32_e32 v126, 0x108000, v170
	global_load_dwordx4 v[126:129], v126, s[100:101] offset:256
	v_add_u32_e32 v168, 0x80, v168
	v_add_u32_e32 v170, 0x80, v170
	s_waitcnt lgkmcnt(0)
	s_barrier
	s_cmp_eq_u32 s20, 44
	s_mov_b32 s4, s20
	s_cbranch_scc0 .LBB0_534
	s_waitcnt vmcnt(4)
	v_add_u32_e32 v102, s7, v206
	v_or_b32_e32 v104, v102, v205
	v_cmp_lt_i32_e32 vcc, s97, v104
	s_waitcnt vmcnt(3)
	v_ashrrev_i32_e32 v106, 31, v104
	v_add_u32_e32 v107, 0xffffc000, v104
	v_ashrrev_i32_e32 v105, 11, v102
	v_cndmask_b32_e64 v111, v106, 0, vcc
	v_cndmask_b32_e32 v110, v104, v107, vcc
	v_mov_b32_e32 v106, s45
	v_mov_b32_e32 v107, s47
	v_mov_b32_e32 v108, s44
	v_mov_b32_e32 v109, s46
	v_or_b32_e32 v102, s6, v208
	s_waitcnt vmcnt(2)
	v_cndmask_b32_e64 v114, v105, 8, vcc
	v_cndmask_b32_e32 v113, v106, v107, vcc
	v_cndmask_b32_e32 v112, v108, v109, vcc
	v_lshlrev_b64 v[122:123], 12, v[110:111]
	v_ashrrev_i32_e32 v103, 31, v102
	v_lshl_add_u64 v[110:111], v[112:113], 0, v[122:123]
	v_mul_hi_i32_i24_e32 v113, 0x9000, v114
	v_mul_i32_i24_e32 v112, 0x9000, v114
	v_lshl_add_u64 v[112:113], s[12:13], 0, v[112:113]
	v_lshlrev_b64 v[102:103], 2, v[102:103]
	s_waitcnt vmcnt(0)
	v_lshl_add_u64 v[124:125], v[112:113], 0, v[102:103]
	global_load_dwordx4 v[114:117], v[124:125], off
	s_waitcnt vmcnt(1)
	v_lshl_add_u64 v[126:127], v[110:111], 0, v[102:103]
	global_load_dwordx4 v[118:121], v[126:127], off
	v_mov_b32_e32 v110, s49
	v_mov_b32_e32 v111, s17
	v_mov_b32_e32 v112, s48
	v_mov_b32_e32 v113, s16
	v_cndmask_b32_e32 v129, v110, v111, vcc
	v_cndmask_b32_e32 v128, v112, v113, vcc
	v_lshl_add_u64 v[122:123], v[128:129], 0, v[122:123]
	v_lshl_add_u64 v[122:123], v[122:123], 0, v[102:103]
	s_waitcnt vmcnt(1)
	v_pk_mul_f32 v[114:115], v[114:115], 0.5 op_sel_hi:[1,0]
	v_pk_mul_f32 v[116:117], v[116:117], 0.5 op_sel_hi:[1,0]
	s_waitcnt vmcnt(0)
	v_pk_fma_f32 v[114:115], v[158:159], v[114:115], v[118:119]
	v_pk_fma_f32 v[116:117], v[160:161], v[116:117], v[120:121]
	global_store_dwordx4 v[122:123], v[114:117], off
	global_load_dwordx4 v[114:117], v[124:125], off offset:64
	s_nop 0
	global_load_dwordx4 v[118:121], v[126:127], off offset:64
	s_waitcnt vmcnt(1)
	v_pk_mul_f32 v[114:115], v[114:115], 0.5 op_sel_hi:[1,0]
	v_pk_mul_f32 v[116:117], v[116:117], 0.5 op_sel_hi:[1,0]
	s_waitcnt vmcnt(0)
	v_pk_fma_f32 v[114:115], v[154:155], v[114:115], v[118:119]
	v_pk_fma_f32 v[116:117], v[156:157], v[116:117], v[120:121]
	global_store_dwordx4 v[122:123], v[114:117], off offset:64
	global_load_dwordx4 v[114:117], v[124:125], off offset:128
	s_nop 0
	global_load_dwordx4 v[118:121], v[126:127], off offset:128
	s_waitcnt vmcnt(1)
	v_pk_mul_f32 v[114:115], v[114:115], 0.5 op_sel_hi:[1,0]
	v_pk_mul_f32 v[116:117], v[116:117], 0.5 op_sel_hi:[1,0]
	s_waitcnt vmcnt(0)
	v_pk_fma_f32 v[114:115], v[150:151], v[114:115], v[118:119]
	v_pk_fma_f32 v[116:117], v[152:153], v[116:117], v[120:121]
	global_store_dwordx4 v[122:123], v[114:117], off offset:128
	global_load_dwordx4 v[114:117], v[124:125], off offset:192
	s_nop 0
	global_load_dwordx4 v[118:121], v[126:127], off offset:192
	s_waitcnt vmcnt(1)
	v_pk_mul_f32 v[114:115], v[114:115], 0.5 op_sel_hi:[1,0]
	v_pk_mul_f32 v[116:117], v[116:117], 0.5 op_sel_hi:[1,0]
	s_waitcnt vmcnt(0)
	v_pk_fma_f32 v[114:115], v[146:147], v[114:115], v[118:119]
	v_pk_fma_f32 v[116:117], v[148:149], v[116:117], v[120:121]
	global_store_dwordx4 v[122:123], v[114:117], off offset:192
	global_load_dwordx4 v[114:117], v[124:125], off offset:256
	s_nop 0
	global_load_dwordx4 v[118:121], v[126:127], off offset:256
	s_waitcnt vmcnt(1)
	v_pk_mul_f32 v[114:115], v[114:115], 0.5 op_sel_hi:[1,0]
	v_pk_mul_f32 v[116:117], v[116:117], 0.5 op_sel_hi:[1,0]
	s_waitcnt vmcnt(0)
	v_pk_fma_f32 v[114:115], v[142:143], v[114:115], v[118:119]
	v_pk_fma_f32 v[116:117], v[144:145], v[116:117], v[120:121]
	global_store_dwordx4 v[122:123], v[114:117], off offset:256
	global_load_dwordx4 v[114:117], v[124:125], off offset:320
	s_nop 0
	global_load_dwordx4 v[118:121], v[126:127], off offset:320
	s_waitcnt vmcnt(1)
	v_pk_mul_f32 v[114:115], v[114:115], 0.5 op_sel_hi:[1,0]
	v_pk_mul_f32 v[116:117], v[116:117], 0.5 op_sel_hi:[1,0]
	s_waitcnt vmcnt(0)
	v_pk_fma_f32 v[114:115], v[138:139], v[114:115], v[118:119]
	v_pk_fma_f32 v[116:117], v[140:141], v[116:117], v[120:121]
	global_store_dwordx4 v[122:123], v[114:117], off offset:320
	global_load_dwordx4 v[114:117], v[124:125], off offset:384
	s_nop 0
	global_load_dwordx4 v[118:121], v[126:127], off offset:384
	s_waitcnt vmcnt(1)
	v_pk_mul_f32 v[114:115], v[114:115], 0.5 op_sel_hi:[1,0]
	v_pk_mul_f32 v[116:117], v[116:117], 0.5 op_sel_hi:[1,0]
	s_waitcnt vmcnt(0)
	v_pk_fma_f32 v[114:115], v[134:135], v[114:115], v[118:119]
	v_pk_fma_f32 v[116:117], v[136:137], v[116:117], v[120:121]
	global_store_dwordx4 v[122:123], v[114:117], off offset:384
	global_load_dwordx4 v[114:117], v[124:125], off offset:448
	s_nop 0
	global_load_dwordx4 v[118:121], v[126:127], off offset:448
	s_waitcnt vmcnt(1)
	v_pk_mul_f32 v[114:115], v[114:115], 0.5 op_sel_hi:[1,0]
	v_pk_mul_f32 v[116:117], v[116:117], 0.5 op_sel_hi:[1,0]
	s_waitcnt vmcnt(0)
	v_pk_fma_f32 v[98:99], v[98:99], v[114:115], v[118:119]
	v_pk_fma_f32 v[100:101], v[100:101], v[116:117], v[120:121]
	global_store_dwordx4 v[122:123], v[98:101], off offset:448
	s_nop 1
	v_or_b32_e32 v98, 16, v104
	v_cmp_lt_i32_e32 vcc, s97, v98
	v_add_u32_e32 v100, 0xffffc010, v104
	v_ashrrev_i32_e32 v99, 31, v98
	v_cndmask_b32_e64 v116, v105, 8, vcc
	v_cndmask_b32_e64 v99, v99, 0, vcc
	v_cndmask_b32_e32 v98, v98, v100, vcc
	v_lshlrev_b64 v[118:119], 12, v[98:99]
	v_mul_hi_i32_i24_e32 v99, 0x9000, v116
	v_mul_i32_i24_e32 v98, 0x9000, v116
	v_cndmask_b32_e32 v101, v106, v107, vcc
	v_cndmask_b32_e32 v100, v108, v109, vcc
	v_lshl_add_u64 v[98:99], s[12:13], 0, v[98:99]
	v_lshl_add_u64 v[114:115], v[100:101], 0, v[118:119]
	v_lshl_add_u64 v[120:121], v[98:99], 0, v[102:103]
	global_load_dwordx4 v[98:101], v[120:121], off
	v_lshl_add_u64 v[122:123], v[114:115], 0, v[102:103]
	global_load_dwordx4 v[114:117], v[122:123], off
	v_cndmask_b32_e32 v125, v110, v111, vcc
	v_cndmask_b32_e32 v124, v112, v113, vcc
	v_lshl_add_u64 v[118:119], v[124:125], 0, v[118:119]
	v_lshl_add_u64 v[118:119], v[118:119], 0, v[102:103]
	s_waitcnt vmcnt(1)
	v_pk_mul_f32 v[98:99], v[98:99], 0.5 op_sel_hi:[1,0]
	v_pk_mul_f32 v[100:101], v[100:101], 0.5 op_sel_hi:[1,0]
	s_waitcnt vmcnt(0)
	v_pk_fma_f32 v[94:95], v[94:95], v[98:99], v[114:115]
	v_pk_fma_f32 v[96:97], v[96:97], v[100:101], v[116:117]
	global_store_dwordx4 v[118:119], v[94:97], off
	global_load_dwordx4 v[94:97], v[120:121], off offset:64
	s_nop 0
	global_load_dwordx4 v[98:101], v[122:123], off offset:64
	s_waitcnt vmcnt(1)
	v_pk_mul_f32 v[94:95], v[94:95], 0.5 op_sel_hi:[1,0]
	v_pk_mul_f32 v[96:97], v[96:97], 0.5 op_sel_hi:[1,0]
	s_waitcnt vmcnt(0)
	v_pk_fma_f32 v[90:91], v[90:91], v[94:95], v[98:99]
	v_pk_fma_f32 v[92:93], v[92:93], v[96:97], v[100:101]
	global_store_dwordx4 v[118:119], v[90:93], off offset:64
	global_load_dwordx4 v[90:93], v[120:121], off offset:128
	s_nop 0
	global_load_dwordx4 v[94:97], v[122:123], off offset:128
	s_waitcnt vmcnt(1)
	v_pk_mul_f32 v[90:91], v[90:91], 0.5 op_sel_hi:[1,0]
	v_pk_mul_f32 v[92:93], v[92:93], 0.5 op_sel_hi:[1,0]
	s_waitcnt vmcnt(0)
	v_pk_fma_f32 v[86:87], v[86:87], v[90:91], v[94:95]
	v_pk_fma_f32 v[88:89], v[88:89], v[92:93], v[96:97]
	global_store_dwordx4 v[118:119], v[86:89], off offset:128
	global_load_dwordx4 v[86:89], v[120:121], off offset:192
	s_nop 0
	global_load_dwordx4 v[90:93], v[122:123], off offset:192
	s_waitcnt vmcnt(1)
	v_pk_mul_f32 v[86:87], v[86:87], 0.5 op_sel_hi:[1,0]
	v_pk_mul_f32 v[88:89], v[88:89], 0.5 op_sel_hi:[1,0]
	s_waitcnt vmcnt(0)
	v_pk_fma_f32 v[82:83], v[82:83], v[86:87], v[90:91]
	v_pk_fma_f32 v[84:85], v[84:85], v[88:89], v[92:93]
	global_store_dwordx4 v[118:119], v[82:85], off offset:192
	global_load_dwordx4 v[82:85], v[120:121], off offset:256
	s_nop 0
	global_load_dwordx4 v[86:89], v[122:123], off offset:256
	s_waitcnt vmcnt(1)
	v_pk_mul_f32 v[82:83], v[82:83], 0.5 op_sel_hi:[1,0]
	v_pk_mul_f32 v[84:85], v[84:85], 0.5 op_sel_hi:[1,0]
	s_waitcnt vmcnt(0)
	v_pk_fma_f32 v[78:79], v[78:79], v[82:83], v[86:87]
	v_pk_fma_f32 v[80:81], v[80:81], v[84:85], v[88:89]
	global_store_dwordx4 v[118:119], v[78:81], off offset:256
	global_load_dwordx4 v[78:81], v[120:121], off offset:320
	s_nop 0
	global_load_dwordx4 v[82:85], v[122:123], off offset:320
	s_waitcnt vmcnt(1)
	v_pk_mul_f32 v[78:79], v[78:79], 0.5 op_sel_hi:[1,0]
	v_pk_mul_f32 v[80:81], v[80:81], 0.5 op_sel_hi:[1,0]
	s_waitcnt vmcnt(0)
	v_pk_fma_f32 v[74:75], v[74:75], v[78:79], v[82:83]
	v_pk_fma_f32 v[76:77], v[76:77], v[80:81], v[84:85]
	global_store_dwordx4 v[118:119], v[74:77], off offset:320
	global_load_dwordx4 v[74:77], v[120:121], off offset:384
	s_nop 0
	global_load_dwordx4 v[78:81], v[122:123], off offset:384
	s_waitcnt vmcnt(1)
	v_pk_mul_f32 v[74:75], v[74:75], 0.5 op_sel_hi:[1,0]
	v_pk_mul_f32 v[76:77], v[76:77], 0.5 op_sel_hi:[1,0]
	s_waitcnt vmcnt(0)
	v_pk_fma_f32 v[70:71], v[70:71], v[74:75], v[78:79]
	v_pk_fma_f32 v[72:73], v[72:73], v[76:77], v[80:81]
	global_store_dwordx4 v[118:119], v[70:73], off offset:384
	global_load_dwordx4 v[70:73], v[120:121], off offset:448
	s_nop 0
	global_load_dwordx4 v[74:77], v[122:123], off offset:448
	s_waitcnt vmcnt(1)
	v_pk_mul_f32 v[70:71], v[70:71], 0.5 op_sel_hi:[1,0]
	v_pk_mul_f32 v[72:73], v[72:73], 0.5 op_sel_hi:[1,0]
	s_waitcnt vmcnt(0)
	v_pk_fma_f32 v[66:67], v[66:67], v[70:71], v[74:75]
	v_pk_fma_f32 v[68:69], v[68:69], v[72:73], v[76:77]
	global_store_dwordx4 v[118:119], v[66:69], off offset:448
	s_nop 1
	v_or_b32_e32 v66, 32, v104
	v_cmp_lt_i32_e32 vcc, s97, v66
	v_add_u32_e32 v68, 0xffffc020, v104
	v_ashrrev_i32_e32 v67, 31, v66
	v_cndmask_b32_e64 v72, v105, 8, vcc
	v_cndmask_b32_e64 v67, v67, 0, vcc
	v_cndmask_b32_e32 v66, v66, v68, vcc
	v_lshlrev_b64 v[74:75], 12, v[66:67]
	v_mul_hi_i32_i24_e32 v67, 0x9000, v72
	v_mul_i32_i24_e32 v66, 0x9000, v72
	v_cndmask_b32_e32 v69, v106, v107, vcc
	v_cndmask_b32_e32 v68, v108, v109, vcc
	v_lshl_add_u64 v[66:67], s[12:13], 0, v[66:67]
	v_lshl_add_u64 v[70:71], v[68:69], 0, v[74:75]
	v_lshl_add_u64 v[76:77], v[66:67], 0, v[102:103]
	global_load_dwordx4 v[66:69], v[76:77], off
	v_lshl_add_u64 v[78:79], v[70:71], 0, v[102:103]
	global_load_dwordx4 v[70:73], v[78:79], off
	v_cndmask_b32_e32 v81, v110, v111, vcc
	v_cndmask_b32_e32 v80, v112, v113, vcc
	v_lshl_add_u64 v[74:75], v[80:81], 0, v[74:75]
	v_lshl_add_u64 v[74:75], v[74:75], 0, v[102:103]
	s_waitcnt vmcnt(1)
	v_pk_mul_f32 v[66:67], v[66:67], 0.5 op_sel_hi:[1,0]
	v_pk_mul_f32 v[68:69], v[68:69], 0.5 op_sel_hi:[1,0]
	s_waitcnt vmcnt(0)
	v_pk_fma_f32 v[62:63], v[62:63], v[66:67], v[70:71]
	v_pk_fma_f32 v[64:65], v[64:65], v[68:69], v[72:73]
	global_store_dwordx4 v[74:75], v[62:65], off
	global_load_dwordx4 v[62:65], v[76:77], off offset:64
	s_nop 0
	global_load_dwordx4 v[66:69], v[78:79], off offset:64
	s_waitcnt vmcnt(1)
	v_pk_mul_f32 v[62:63], v[62:63], 0.5 op_sel_hi:[1,0]
	v_pk_mul_f32 v[64:65], v[64:65], 0.5 op_sel_hi:[1,0]
	s_waitcnt vmcnt(0)
	v_pk_fma_f32 v[58:59], v[58:59], v[62:63], v[66:67]
	v_pk_fma_f32 v[60:61], v[60:61], v[64:65], v[68:69]
	global_store_dwordx4 v[74:75], v[58:61], off offset:64
	global_load_dwordx4 v[58:61], v[76:77], off offset:128
	s_nop 0
	global_load_dwordx4 v[62:65], v[78:79], off offset:128
	s_waitcnt vmcnt(1)
	v_pk_mul_f32 v[58:59], v[58:59], 0.5 op_sel_hi:[1,0]
	v_pk_mul_f32 v[60:61], v[60:61], 0.5 op_sel_hi:[1,0]
	s_waitcnt vmcnt(0)
	v_pk_fma_f32 v[54:55], v[54:55], v[58:59], v[62:63]
	v_pk_fma_f32 v[56:57], v[56:57], v[60:61], v[64:65]
	global_store_dwordx4 v[74:75], v[54:57], off offset:128
	global_load_dwordx4 v[54:57], v[76:77], off offset:192
	s_nop 0
	global_load_dwordx4 v[58:61], v[78:79], off offset:192
	s_waitcnt vmcnt(1)
	v_pk_mul_f32 v[54:55], v[54:55], 0.5 op_sel_hi:[1,0]
	v_pk_mul_f32 v[56:57], v[56:57], 0.5 op_sel_hi:[1,0]
	s_waitcnt vmcnt(0)
	v_pk_fma_f32 v[50:51], v[50:51], v[54:55], v[58:59]
	v_pk_fma_f32 v[52:53], v[52:53], v[56:57], v[60:61]
	global_store_dwordx4 v[74:75], v[50:53], off offset:192
	global_load_dwordx4 v[50:53], v[76:77], off offset:256
	s_nop 0
	global_load_dwordx4 v[54:57], v[78:79], off offset:256
	s_waitcnt vmcnt(1)
	v_pk_mul_f32 v[50:51], v[50:51], 0.5 op_sel_hi:[1,0]
	v_pk_mul_f32 v[52:53], v[52:53], 0.5 op_sel_hi:[1,0]
	s_waitcnt vmcnt(0)
	v_pk_fma_f32 v[46:47], v[46:47], v[50:51], v[54:55]
	v_pk_fma_f32 v[48:49], v[48:49], v[52:53], v[56:57]
	global_store_dwordx4 v[74:75], v[46:49], off offset:256
	global_load_dwordx4 v[46:49], v[76:77], off offset:320
	s_nop 0
	global_load_dwordx4 v[50:53], v[78:79], off offset:320
	s_waitcnt vmcnt(1)
	v_pk_mul_f32 v[46:47], v[46:47], 0.5 op_sel_hi:[1,0]
	v_pk_mul_f32 v[48:49], v[48:49], 0.5 op_sel_hi:[1,0]
	s_waitcnt vmcnt(0)
	v_pk_fma_f32 v[42:43], v[42:43], v[46:47], v[50:51]
	v_pk_fma_f32 v[44:45], v[44:45], v[48:49], v[52:53]
	global_store_dwordx4 v[74:75], v[42:45], off offset:320
	global_load_dwordx4 v[42:45], v[76:77], off offset:384
	s_nop 0
	global_load_dwordx4 v[46:49], v[78:79], off offset:384
	s_waitcnt vmcnt(1)
	v_pk_mul_f32 v[42:43], v[42:43], 0.5 op_sel_hi:[1,0]
	v_pk_mul_f32 v[44:45], v[44:45], 0.5 op_sel_hi:[1,0]
	s_waitcnt vmcnt(0)
	v_pk_fma_f32 v[38:39], v[38:39], v[42:43], v[46:47]
	v_pk_fma_f32 v[40:41], v[40:41], v[44:45], v[48:49]
	global_store_dwordx4 v[74:75], v[38:41], off offset:384
	global_load_dwordx4 v[38:41], v[76:77], off offset:448
	s_nop 0
	global_load_dwordx4 v[42:45], v[78:79], off offset:448
	s_waitcnt vmcnt(1)
	v_pk_mul_f32 v[38:39], v[38:39], 0.5 op_sel_hi:[1,0]
	v_pk_mul_f32 v[40:41], v[40:41], 0.5 op_sel_hi:[1,0]
	s_waitcnt vmcnt(0)
	v_pk_fma_f32 v[34:35], v[34:35], v[38:39], v[42:43]
	v_pk_fma_f32 v[36:37], v[36:37], v[40:41], v[44:45]
	global_store_dwordx4 v[74:75], v[34:37], off offset:448
	s_nop 1
	v_or_b32_e32 v34, 48, v104
	v_cmp_lt_i32_e32 vcc, s97, v34
	v_add_u32_e32 v36, 0xffffc030, v104
	v_ashrrev_i32_e32 v35, 31, v34
	v_cndmask_b32_e64 v35, v35, 0, vcc
	v_cndmask_b32_e32 v34, v34, v36, vcc
	v_cndmask_b32_e64 v40, v105, 8, vcc
	v_cndmask_b32_e32 v37, v106, v107, vcc
	v_cndmask_b32_e32 v36, v108, v109, vcc
	v_lshlrev_b64 v[34:35], 12, v[34:35]
	v_cndmask_b32_e32 v39, v110, v111, vcc
	v_cndmask_b32_e32 v38, v112, v113, vcc
	v_lshl_add_u64 v[36:37], v[36:37], 0, v[34:35]
	v_lshl_add_u64 v[34:35], v[38:39], 0, v[34:35]
	v_mul_hi_i32_i24_e32 v39, 0x9000, v40
	v_mul_i32_i24_e32 v38, 0x9000, v40
	v_lshl_add_u64 v[38:39], s[12:13], 0, v[38:39]
	v_lshl_add_u64 v[42:43], v[38:39], 0, v[102:103]
	v_lshl_add_u64 v[44:45], v[36:37], 0, v[102:103]
	v_lshl_add_u64 v[46:47], v[34:35], 0, v[102:103]
	global_load_dwordx4 v[34:37], v[42:43], off
	global_load_dwordx4 v[38:41], v[44:45], off
	s_waitcnt vmcnt(1)
	v_pk_mul_f32 v[34:35], v[34:35], 0.5 op_sel_hi:[1,0]
	s_waitcnt vmcnt(0)
	v_pk_fma_f32 v[30:31], v[30:31], v[34:35], v[38:39]
	v_pk_mul_f32 v[34:35], v[36:37], 0.5 op_sel_hi:[1,0]
	s_nop 0
	v_pk_fma_f32 v[32:33], v[32:33], v[34:35], v[40:41]
	global_store_dwordx4 v[46:47], v[30:33], off
	global_load_dwordx4 v[30:33], v[42:43], off offset:64
	s_nop 0
	global_load_dwordx4 v[34:37], v[44:45], off offset:64
	s_waitcnt vmcnt(1)
	v_pk_mul_f32 v[30:31], v[30:31], 0.5 op_sel_hi:[1,0]
	s_waitcnt vmcnt(0)
	v_pk_fma_f32 v[26:27], v[26:27], v[30:31], v[34:35]
	v_pk_mul_f32 v[30:31], v[32:33], 0.5 op_sel_hi:[1,0]
	s_nop 0
	v_pk_fma_f32 v[28:29], v[28:29], v[30:31], v[36:37]
	global_store_dwordx4 v[46:47], v[26:29], off offset:64
	global_load_dwordx4 v[26:29], v[42:43], off offset:128
	s_nop 0
	global_load_dwordx4 v[30:33], v[44:45], off offset:128
	s_waitcnt vmcnt(1)
	v_pk_mul_f32 v[26:27], v[26:27], 0.5 op_sel_hi:[1,0]
	s_waitcnt vmcnt(0)
	v_pk_fma_f32 v[22:23], v[22:23], v[26:27], v[30:31]
	v_pk_mul_f32 v[26:27], v[28:29], 0.5 op_sel_hi:[1,0]
	s_nop 0
	v_pk_fma_f32 v[24:25], v[24:25], v[26:27], v[32:33]
	global_store_dwordx4 v[46:47], v[22:25], off offset:128
	global_load_dwordx4 v[22:25], v[42:43], off offset:192
	s_nop 0
	global_load_dwordx4 v[26:29], v[44:45], off offset:192
	s_waitcnt vmcnt(1)
	v_pk_mul_f32 v[22:23], v[22:23], 0.5 op_sel_hi:[1,0]
	s_waitcnt vmcnt(0)
	v_pk_fma_f32 v[18:19], v[18:19], v[22:23], v[26:27]
	v_pk_mul_f32 v[22:23], v[24:25], 0.5 op_sel_hi:[1,0]
	s_nop 0
	v_pk_fma_f32 v[20:21], v[20:21], v[22:23], v[28:29]
	global_store_dwordx4 v[46:47], v[18:21], off offset:192
	global_load_dwordx4 v[18:21], v[42:43], off offset:256
	s_nop 0
	global_load_dwordx4 v[22:25], v[44:45], off offset:256
	s_waitcnt vmcnt(1)
	v_pk_mul_f32 v[18:19], v[18:19], 0.5 op_sel_hi:[1,0]
	s_waitcnt vmcnt(0)
	v_pk_fma_f32 v[14:15], v[14:15], v[18:19], v[22:23]
	v_pk_mul_f32 v[18:19], v[20:21], 0.5 op_sel_hi:[1,0]
	s_nop 0
	v_pk_fma_f32 v[16:17], v[16:17], v[18:19], v[24:25]
	global_store_dwordx4 v[46:47], v[14:17], off offset:256
	global_load_dwordx4 v[14:17], v[42:43], off offset:320
	s_nop 0
	global_load_dwordx4 v[18:21], v[44:45], off offset:320
	s_waitcnt vmcnt(1)
	v_pk_mul_f32 v[14:15], v[14:15], 0.5 op_sel_hi:[1,0]
	s_waitcnt vmcnt(0)
	v_pk_fma_f32 v[10:11], v[10:11], v[14:15], v[18:19]
	v_pk_mul_f32 v[14:15], v[16:17], 0.5 op_sel_hi:[1,0]
	s_nop 0
	v_pk_fma_f32 v[12:13], v[12:13], v[14:15], v[20:21]
	global_store_dwordx4 v[46:47], v[10:13], off offset:320
	global_load_dwordx4 v[10:13], v[42:43], off offset:384
	s_nop 0
	global_load_dwordx4 v[14:17], v[44:45], off offset:384
	s_waitcnt vmcnt(1)
	v_pk_mul_f32 v[10:11], v[10:11], 0.5 op_sel_hi:[1,0]
	s_waitcnt vmcnt(0)
	v_pk_fma_f32 v[6:7], v[6:7], v[10:11], v[14:15]
	v_pk_mul_f32 v[10:11], v[12:13], 0.5 op_sel_hi:[1,0]
	s_nop 0
	v_pk_fma_f32 v[8:9], v[8:9], v[10:11], v[16:17]
	global_store_dwordx4 v[46:47], v[6:9], off offset:384
	global_load_dwordx4 v[6:9], v[42:43], off offset:448
	s_nop 0
	global_load_dwordx4 v[10:13], v[44:45], off offset:448
	s_waitcnt vmcnt(1)
	v_pk_mul_f32 v[6:7], v[6:7], 0.5 op_sel_hi:[1,0]
	s_waitcnt vmcnt(0)
	v_pk_fma_f32 v[2:3], v[2:3], v[6:7], v[10:11]
	v_pk_mul_f32 v[6:7], v[8:9], 0.5 op_sel_hi:[1,0]
	s_nop 0
	v_pk_fma_f32 v[4:5], v[4:5], v[6:7], v[12:13]
	global_store_dwordx4 v[46:47], v[2:5], off offset:448
	s_add_i32 s11, s11, s10
	s_cmpk_gt_i32 s11, 0xff
	s_cbranch_scc0 .LBB0_533

.LBB0_665:
	s_bitcmp1_b32 s4, 0
	s_cselect_b32 s15, 0x12000, 0
	v_or_b32_e32 v208, s15, v206
	v_add_u32_e32 v214, v208, v0
	v_add_u32_e32 v208, v208, v167
	ds_read_b128 v[184:187], v214
	ds_read_b128 v[218:221], v208 offset:32768
	ds_read_b128 v[198:201], v214 offset:2048
	ds_read_b128 v[210:213], v214 offset:4096
	ds_read_b128 v[214:217], v214 offset:6144
	ds_read_b128 v[222:225], v208 offset:34816
	ds_read_b128 v[226:229], v208 offset:36864
	ds_read_b128 v[230:233], v208 offset:38912
	ds_read_b128 v[234:237], v208 offset:40960
	ds_read_b128 v[238:241], v208 offset:43008
	ds_read_b128 v[242:245], v208 offset:45056
	ds_read_b128 v[246:249], v208 offset:47104
	s_add_i32 s14, s4, 1
	s_bitcmp1_b32 s14, 0
	s_cselect_b32 s16, 0x12000, 0
	v_add_u32_e32 v208, s16, v166
	v_add_u32_e32 v171, s16, v166
	v_xor_b32_e32 v169, 64, v206
	v_add3_u32 v169, s15, v167, v169
	s_waitcnt lgkmcnt(10)
	v_mfma_f32_16x16x32_bf16 v[158:161], v[218:221], v[184:187], v[158:161]
	s_waitcnt lgkmcnt(9)
	v_mfma_f32_16x16x32_bf16 v[130:133], v[218:221], v[198:201], v[130:133]
	s_waitcnt lgkmcnt(8)
	v_mfma_f32_16x16x32_bf16 v[66:69], v[218:221], v[210:213], v[66:69]
	s_waitcnt lgkmcnt(7)
	v_mfma_f32_16x16x32_bf16 v[34:37], v[218:221], v[214:217], v[34:37]
	ds_read_b128 v[218:221], v169 offset:32768
	s_waitcnt lgkmcnt(7)
	v_mfma_f32_16x16x32_bf16 v[154:157], v[222:225], v[184:187], v[154:157]
	v_mfma_f32_16x16x32_bf16 v[122:125], v[222:225], v[198:201], v[122:125]
	v_mfma_f32_16x16x32_bf16 v[58:61], v[222:225], v[210:213], v[58:61]
	v_mfma_f32_16x16x32_bf16 v[26:29], v[222:225], v[214:217], v[26:29]
	ds_read_b128 v[222:225], v169 offset:34816
	s_waitcnt lgkmcnt(7)
	v_mfma_f32_16x16x32_bf16 v[150:153], v[226:229], v[184:187], v[150:153]
	v_mfma_f32_16x16x32_bf16 v[114:117], v[226:229], v[198:201], v[114:117]
	v_mfma_f32_16x16x32_bf16 v[54:57], v[226:229], v[210:213], v[54:57]
	v_mfma_f32_16x16x32_bf16 v[22:25], v[226:229], v[214:217], v[22:25]
	ds_read_b128 v[226:229], v169 offset:36864
	s_waitcnt lgkmcnt(7)
	v_mfma_f32_16x16x32_bf16 v[146:149], v[230:233], v[184:187], v[146:149]
	v_mfma_f32_16x16x32_bf16 v[82:85], v[230:233], v[198:201], v[82:85]
	v_mfma_f32_16x16x32_bf16 v[50:53], v[230:233], v[210:213], v[50:53]
	v_mfma_f32_16x16x32_bf16 v[18:21], v[230:233], v[214:217], v[18:21]
	ds_read_b128 v[230:233], v169 offset:38912
	s_waitcnt lgkmcnt(7)
	v_mfma_f32_16x16x32_bf16 v[142:145], v[234:237], v[184:187], v[142:145]
	v_mfma_f32_16x16x32_bf16 v[78:81], v[234:237], v[198:201], v[78:81]
	v_mfma_f32_16x16x32_bf16 v[46:49], v[234:237], v[210:213], v[46:49]
	v_mfma_f32_16x16x32_bf16 v[14:17], v[234:237], v[214:217], v[14:17]
	ds_read_b128 v[234:237], v169 offset:40960
	s_waitcnt lgkmcnt(7)
	v_mfma_f32_16x16x32_bf16 v[138:141], v[238:241], v[184:187], v[138:141]
	v_mfma_f32_16x16x32_bf16 v[74:77], v[238:241], v[198:201], v[74:77]
	v_mfma_f32_16x16x32_bf16 v[42:45], v[238:241], v[210:213], v[42:45]
	v_mfma_f32_16x16x32_bf16 v[10:13], v[238:241], v[214:217], v[10:13]
	ds_read_b128 v[238:241], v169 offset:43008
	s_waitcnt lgkmcnt(7)
	v_mfma_f32_16x16x32_bf16 v[134:137], v[242:245], v[184:187], v[134:137]
	v_mfma_f32_16x16x32_bf16 v[70:73], v[242:245], v[198:201], v[70:73]
	v_mfma_f32_16x16x32_bf16 v[38:41], v[242:245], v[210:213], v[38:41]
	v_mfma_f32_16x16x32_bf16 v[6:9], v[242:245], v[214:217], v[6:9]
	ds_read_b128 v[242:245], v169 offset:45056
	s_waitcnt lgkmcnt(7)
	v_mfma_f32_16x16x32_bf16 v[126:129], v[246:249], v[184:187], v[126:129]
	v_mfma_f32_16x16x32_bf16 v[62:65], v[246:249], v[198:201], v[62:65]
	v_xor_b32_e32 v169, 64, v206
	v_add3_u32 v169, s15, v0, v169
	ds_read_b128 v[184:187], v169
	ds_read_b128 v[198:201], v169 offset:2048
	v_mfma_f32_16x16x32_bf16 v[30:33], v[246:249], v[210:213], v[30:33]
	ds_read_b128 v[210:213], v169 offset:4096
	v_mfma_f32_16x16x32_bf16 v[2:5], v[246:249], v[214:217], v[2:5]
	ds_read_b128 v[214:217], v169 offset:6144
	v_xor_b32_e32 v169, 64, v206
	v_add3_u32 v169, s15, v167, v169
	ds_read_b128 v[246:249], v169 offset:47104
	s_waitcnt lgkmcnt(4)
	v_mfma_f32_16x16x32_bf16 v[158:161], v[218:221], v[184:187], v[158:161]
	s_waitcnt lgkmcnt(3)
	v_mfma_f32_16x16x32_bf16 v[130:133], v[218:221], v[198:201], v[130:133]
	s_waitcnt lgkmcnt(2)
	v_mfma_f32_16x16x32_bf16 v[66:69], v[218:221], v[210:213], v[66:69]
	s_waitcnt lgkmcnt(1)
	v_mfma_f32_16x16x32_bf16 v[34:37], v[218:221], v[214:217], v[34:37]
	s_waitcnt vmcnt(7)
	ds_write_b128 v171, v[94:97]
	v_mfma_f32_16x16x32_bf16 v[154:157], v[222:225], v[184:187], v[154:157]
	v_mfma_f32_16x16x32_bf16 v[122:125], v[222:225], v[198:201], v[122:125]
	global_load_dwordx4 v[94:97], v168, vcc offset:256
	v_mfma_f32_16x16x32_bf16 v[58:61], v[222:225], v[210:213], v[58:61]
	v_mfma_f32_16x16x32_bf16 v[26:29], v[222:225], v[214:217], v[26:29]
	s_waitcnt vmcnt(7)
	ds_write_b128 v171, v[86:89] offset:8192
	v_mfma_f32_16x16x32_bf16 v[150:153], v[226:229], v[184:187], v[150:153]
	v_mfma_f32_16x16x32_bf16 v[114:117], v[226:229], v[198:201], v[114:117]
	v_add_u32_e32 v86, s34, v168
	global_load_dwordx4 v[86:89], v86, vcc offset:256
	v_mfma_f32_16x16x32_bf16 v[54:57], v[226:229], v[210:213], v[54:57]
	v_mfma_f32_16x16x32_bf16 v[22:25], v[226:229], v[214:217], v[22:25]
	s_waitcnt vmcnt(7)
	ds_write_b128 v171, v[90:93] offset:16384
	v_mfma_f32_16x16x32_bf16 v[146:149], v[230:233], v[184:187], v[146:149]
	v_mfma_f32_16x16x32_bf16 v[82:85], v[230:233], v[198:201], v[82:85]
	v_add_u32_e32 v90, s35, v168
	global_load_dwordx4 v[90:93], v90, vcc offset:256
	v_mfma_f32_16x16x32_bf16 v[50:53], v[230:233], v[210:213], v[50:53]
	v_mfma_f32_16x16x32_bf16 v[18:21], v[230:233], v[214:217], v[18:21]
	s_waitcnt vmcnt(7)
	ds_write_b128 v171, v[106:109] offset:24576
	v_mfma_f32_16x16x32_bf16 v[142:145], v[234:237], v[184:187], v[142:145]
	v_mfma_f32_16x16x32_bf16 v[78:81], v[234:237], v[198:201], v[78:81]
	v_add_u32_e32 v106, s36, v168
	global_load_dwordx4 v[106:109], v106, vcc offset:256
	v_mfma_f32_16x16x32_bf16 v[46:49], v[234:237], v[210:213], v[46:49]
	v_mfma_f32_16x16x32_bf16 v[14:17], v[234:237], v[214:217], v[14:17]
	s_waitcnt vmcnt(7)
	ds_write_b128 v171, v[102:105] offset:32768
	v_mfma_f32_16x16x32_bf16 v[138:141], v[238:241], v[184:187], v[138:141]
	v_mfma_f32_16x16x32_bf16 v[74:77], v[238:241], v[198:201], v[74:77]
	global_load_dwordx4 v[102:105], v170, s[100:101] offset:256
	v_mfma_f32_16x16x32_bf16 v[42:45], v[238:241], v[210:213], v[42:45]
	v_mfma_f32_16x16x32_bf16 v[10:13], v[238:241], v[214:217], v[10:13]
	s_waitcnt vmcnt(7)
	ds_write_b128 v171, v[98:101] offset:40960
	v_mfma_f32_16x16x32_bf16 v[134:137], v[242:245], v[184:187], v[134:137]
	v_mfma_f32_16x16x32_bf16 v[70:73], v[242:245], v[198:201], v[70:73]
	v_add_u32_e32 v98, s34, v170
	global_load_dwordx4 v[98:101], v98, s[100:101] offset:256
	v_mfma_f32_16x16x32_bf16 v[38:41], v[242:245], v[210:213], v[38:41]
	v_mfma_f32_16x16x32_bf16 v[6:9], v[242:245], v[214:217], v[6:9]
	s_waitcnt vmcnt(7)
	ds_write_b128 v171, v[118:121] offset:49152
	s_waitcnt lgkmcnt(7)
	v_mfma_f32_16x16x32_bf16 v[126:129], v[246:249], v[184:187], v[126:129]
	v_mfma_f32_16x16x32_bf16 v[62:65], v[246:249], v[198:201], v[62:65]
	v_add_u32_e32 v118, s35, v170
	global_load_dwordx4 v[118:121], v118, s[100:101] offset:256
	v_mfma_f32_16x16x32_bf16 v[30:33], v[246:249], v[210:213], v[30:33]
	v_mfma_f32_16x16x32_bf16 v[2:5], v[246:249], v[214:217], v[2:5]
	s_waitcnt vmcnt(7)
	ds_write_b128 v171, v[110:113] offset:57344
	v_add_u32_e32 v110, s36, v170
	global_load_dwordx4 v[110:113], v110, s[100:101] offset:256
	v_add_u32_e32 v168, 0x80, v168
	v_add_u32_e32 v170, 0x80, v170
	s_waitcnt lgkmcnt(0)
	s_barrier
	s_cmp_eq_u32 s14, 16
	s_mov_b32 s4, s14
	s_cbranch_scc0 .LBB0_665
	s_waitcnt vmcnt(3)
	v_and_b32_sdwa v93, v158, v177 dst_sel:DWORD dst_unused:UNUSED_PAD src0_sel:WORD_1 src1_sel:DWORD
	v_or_b32_e32 v88, s7, v207
	v_add3_u32 v95, v158, v93, s28
	v_and_b32_sdwa v93, v161, v177 dst_sel:DWORD dst_unused:UNUSED_PAD src0_sel:WORD_1 src1_sel:DWORD
	v_and_b32_sdwa v96, v159, v177 dst_sel:DWORD dst_unused:UNUSED_PAD src0_sel:WORD_1 src1_sel:DWORD
	v_add_u32_e32 v94, s6, v205
	v_mov_b64_e32 v[86:87], s[12:13]
	v_ashrrev_i32_e32 v89, 31, v88
	v_and_b32_sdwa v92, v160, v177 dst_sel:DWORD dst_unused:UNUSED_PAD src0_sel:WORD_1 src1_sel:DWORD
	v_add3_u32 v93, v161, v93, s28
	v_add3_u32 v96, v159, v96, s28
	v_mad_i64_i32 v[90:91], s[6:7], v94, s8, v[86:87]
	v_lshlrev_b64 v[88:89], 1, v[88:89]
	v_add3_u32 v92, v160, v92, s28
	v_and_b32_e32 v93, 0xffff0000, v93
	v_and_b32_e32 v96, 0xffff0000, v96
	v_lshl_add_u64 v[90:91], v[90:91], 0, v[88:89]
	v_or_b32_sdwa v93, v93, v92 dst_sel:DWORD dst_unused:UNUSED_PAD src0_sel:DWORD src1_sel:WORD_1
	v_or_b32_sdwa v92, v96, v95 dst_sel:DWORD dst_unused:UNUSED_PAD src0_sel:DWORD src1_sel:WORD_1
	s_waitcnt vmcnt(0)
	global_store_dwordx2 v[90:91], v[92:93], off
	v_and_b32_sdwa v93, v154, v177 dst_sel:DWORD dst_unused:UNUSED_PAD src0_sel:WORD_1 src1_sel:DWORD
	v_add3_u32 v95, v154, v93, s28
	v_and_b32_sdwa v93, v157, v177 dst_sel:DWORD dst_unused:UNUSED_PAD src0_sel:WORD_1 src1_sel:DWORD
	v_and_b32_sdwa v96, v155, v177 dst_sel:DWORD dst_unused:UNUSED_PAD src0_sel:WORD_1 src1_sel:DWORD
	v_and_b32_sdwa v92, v156, v177 dst_sel:DWORD dst_unused:UNUSED_PAD src0_sel:WORD_1 src1_sel:DWORD
	v_add3_u32 v93, v157, v93, s28
	v_add3_u32 v96, v155, v96, s28
	v_add3_u32 v92, v156, v92, s28
	v_and_b32_e32 v93, 0xffff0000, v93
	v_and_b32_e32 v96, 0xffff0000, v96
	v_or_b32_sdwa v93, v93, v92 dst_sel:DWORD dst_unused:UNUSED_PAD src0_sel:DWORD src1_sel:WORD_1
	v_or_b32_sdwa v92, v96, v95 dst_sel:DWORD dst_unused:UNUSED_PAD src0_sel:DWORD src1_sel:WORD_1
	global_store_dwordx2 v[90:91], v[92:93], off offset:32
	v_and_b32_sdwa v93, v150, v177 dst_sel:DWORD dst_unused:UNUSED_PAD src0_sel:WORD_1 src1_sel:DWORD
	v_add3_u32 v95, v150, v93, s28
	v_and_b32_sdwa v93, v153, v177 dst_sel:DWORD dst_unused:UNUSED_PAD src0_sel:WORD_1 src1_sel:DWORD
	v_and_b32_sdwa v96, v151, v177 dst_sel:DWORD dst_unused:UNUSED_PAD src0_sel:WORD_1 src1_sel:DWORD
	v_and_b32_sdwa v92, v152, v177 dst_sel:DWORD dst_unused:UNUSED_PAD src0_sel:WORD_1 src1_sel:DWORD
	v_add3_u32 v93, v153, v93, s28
	v_add3_u32 v96, v151, v96, s28
	v_add3_u32 v92, v152, v92, s28
	v_and_b32_e32 v93, 0xffff0000, v93
	v_and_b32_e32 v96, 0xffff0000, v96
	v_or_b32_sdwa v93, v93, v92 dst_sel:DWORD dst_unused:UNUSED_PAD src0_sel:DWORD src1_sel:WORD_1
	v_or_b32_sdwa v92, v96, v95 dst_sel:DWORD dst_unused:UNUSED_PAD src0_sel:DWORD src1_sel:WORD_1
	global_store_dwordx2 v[90:91], v[92:93], off offset:64
	v_and_b32_sdwa v93, v146, v177 dst_sel:DWORD dst_unused:UNUSED_PAD src0_sel:WORD_1 src1_sel:DWORD
	v_add3_u32 v95, v146, v93, s28
	v_and_b32_sdwa v93, v149, v177 dst_sel:DWORD dst_unused:UNUSED_PAD src0_sel:WORD_1 src1_sel:DWORD
	v_and_b32_sdwa v96, v147, v177 dst_sel:DWORD dst_unused:UNUSED_PAD src0_sel:WORD_1 src1_sel:DWORD
	v_and_b32_sdwa v92, v148, v177 dst_sel:DWORD dst_unused:UNUSED_PAD src0_sel:WORD_1 src1_sel:DWORD
	v_add3_u32 v93, v149, v93, s28
	v_add3_u32 v96, v147, v96, s28
	v_add3_u32 v92, v148, v92, s28
	v_and_b32_e32 v93, 0xffff0000, v93
	v_and_b32_e32 v96, 0xffff0000, v96
	v_or_b32_sdwa v93, v93, v92 dst_sel:DWORD dst_unused:UNUSED_PAD src0_sel:DWORD src1_sel:WORD_1
	v_or_b32_sdwa v92, v96, v95 dst_sel:DWORD dst_unused:UNUSED_PAD src0_sel:DWORD src1_sel:WORD_1
	global_store_dwordx2 v[90:91], v[92:93], off offset:96
	v_and_b32_sdwa v93, v142, v177 dst_sel:DWORD dst_unused:UNUSED_PAD src0_sel:WORD_1 src1_sel:DWORD
	v_add3_u32 v95, v142, v93, s28
	v_and_b32_sdwa v93, v145, v177 dst_sel:DWORD dst_unused:UNUSED_PAD src0_sel:WORD_1 src1_sel:DWORD
	v_and_b32_sdwa v96, v143, v177 dst_sel:DWORD dst_unused:UNUSED_PAD src0_sel:WORD_1 src1_sel:DWORD
	v_and_b32_sdwa v92, v144, v177 dst_sel:DWORD dst_unused:UNUSED_PAD src0_sel:WORD_1 src1_sel:DWORD
	v_add3_u32 v93, v145, v93, s28
	v_add3_u32 v96, v143, v96, s28
	v_add3_u32 v92, v144, v92, s28
	v_and_b32_e32 v93, 0xffff0000, v93
	v_and_b32_e32 v96, 0xffff0000, v96
	v_or_b32_sdwa v93, v93, v92 dst_sel:DWORD dst_unused:UNUSED_PAD src0_sel:DWORD src1_sel:WORD_1
	v_or_b32_sdwa v92, v96, v95 dst_sel:DWORD dst_unused:UNUSED_PAD src0_sel:DWORD src1_sel:WORD_1
	global_store_dwordx2 v[90:91], v[92:93], off offset:128
	v_and_b32_sdwa v93, v138, v177 dst_sel:DWORD dst_unused:UNUSED_PAD src0_sel:WORD_1 src1_sel:DWORD
	v_add3_u32 v95, v138, v93, s28
	v_and_b32_sdwa v93, v141, v177 dst_sel:DWORD dst_unused:UNUSED_PAD src0_sel:WORD_1 src1_sel:DWORD
	v_and_b32_sdwa v96, v139, v177 dst_sel:DWORD dst_unused:UNUSED_PAD src0_sel:WORD_1 src1_sel:DWORD
	v_and_b32_sdwa v92, v140, v177 dst_sel:DWORD dst_unused:UNUSED_PAD src0_sel:WORD_1 src1_sel:DWORD
	v_add3_u32 v93, v141, v93, s28
	v_add3_u32 v96, v139, v96, s28
	v_add3_u32 v92, v140, v92, s28
	v_and_b32_e32 v93, 0xffff0000, v93
	v_and_b32_e32 v96, 0xffff0000, v96
	v_or_b32_sdwa v93, v93, v92 dst_sel:DWORD dst_unused:UNUSED_PAD src0_sel:DWORD src1_sel:WORD_1
	v_or_b32_sdwa v92, v96, v95 dst_sel:DWORD dst_unused:UNUSED_PAD src0_sel:DWORD src1_sel:WORD_1
	global_store_dwordx2 v[90:91], v[92:93], off offset:160
	v_and_b32_sdwa v93, v134, v177 dst_sel:DWORD dst_unused:UNUSED_PAD src0_sel:WORD_1 src1_sel:DWORD
	v_add3_u32 v95, v134, v93, s28
	v_and_b32_sdwa v93, v137, v177 dst_sel:DWORD dst_unused:UNUSED_PAD src0_sel:WORD_1 src1_sel:DWORD
	v_and_b32_sdwa v96, v135, v177 dst_sel:DWORD dst_unused:UNUSED_PAD src0_sel:WORD_1 src1_sel:DWORD
	v_and_b32_sdwa v92, v136, v177 dst_sel:DWORD dst_unused:UNUSED_PAD src0_sel:WORD_1 src1_sel:DWORD
	v_add3_u32 v93, v137, v93, s28
	v_add3_u32 v96, v135, v96, s28
	v_add3_u32 v92, v136, v92, s28
	v_and_b32_e32 v93, 0xffff0000, v93
	v_and_b32_e32 v96, 0xffff0000, v96
	v_or_b32_sdwa v93, v93, v92 dst_sel:DWORD dst_unused:UNUSED_PAD src0_sel:DWORD src1_sel:WORD_1
	v_or_b32_sdwa v92, v96, v95 dst_sel:DWORD dst_unused:UNUSED_PAD src0_sel:DWORD src1_sel:WORD_1
	global_store_dwordx2 v[90:91], v[92:93], off offset:192
	v_and_b32_sdwa v93, v126, v177 dst_sel:DWORD dst_unused:UNUSED_PAD src0_sel:WORD_1 src1_sel:DWORD
	v_add3_u32 v95, v126, v93, s28
	v_and_b32_sdwa v93, v129, v177 dst_sel:DWORD dst_unused:UNUSED_PAD src0_sel:WORD_1 src1_sel:DWORD
	v_and_b32_sdwa v96, v127, v177 dst_sel:DWORD dst_unused:UNUSED_PAD src0_sel:WORD_1 src1_sel:DWORD
	v_and_b32_sdwa v92, v128, v177 dst_sel:DWORD dst_unused:UNUSED_PAD src0_sel:WORD_1 src1_sel:DWORD
	v_add3_u32 v93, v129, v93, s28
	v_add3_u32 v96, v127, v96, s28
	v_add3_u32 v92, v128, v92, s28
	v_and_b32_e32 v93, 0xffff0000, v93
	v_and_b32_e32 v96, 0xffff0000, v96
	v_or_b32_sdwa v93, v93, v92 dst_sel:DWORD dst_unused:UNUSED_PAD src0_sel:DWORD src1_sel:WORD_1
	v_or_b32_sdwa v92, v96, v95 dst_sel:DWORD dst_unused:UNUSED_PAD src0_sel:DWORD src1_sel:WORD_1
	global_store_dwordx2 v[90:91], v[92:93], off offset:224
	v_and_b32_sdwa v93, v130, v177 dst_sel:DWORD dst_unused:UNUSED_PAD src0_sel:WORD_1 src1_sel:DWORD
	v_add3_u32 v95, v130, v93, s28
	v_and_b32_sdwa v93, v133, v177 dst_sel:DWORD dst_unused:UNUSED_PAD src0_sel:WORD_1 src1_sel:DWORD
	v_and_b32_sdwa v96, v131, v177 dst_sel:DWORD dst_unused:UNUSED_PAD src0_sel:WORD_1 src1_sel:DWORD
	v_or_b32_e32 v90, 16, v94
	v_and_b32_sdwa v92, v132, v177 dst_sel:DWORD dst_unused:UNUSED_PAD src0_sel:WORD_1 src1_sel:DWORD
	v_add3_u32 v93, v133, v93, s28
	v_add3_u32 v96, v131, v96, s28
	v_mad_i64_i32 v[90:91], s[6:7], v90, s8, v[86:87]
	v_add3_u32 v92, v132, v92, s28
	v_and_b32_e32 v93, 0xffff0000, v93
	v_and_b32_e32 v96, 0xffff0000, v96
	v_lshl_add_u64 v[90:91], v[90:91], 0, v[88:89]
	v_or_b32_sdwa v93, v93, v92 dst_sel:DWORD dst_unused:UNUSED_PAD src0_sel:DWORD src1_sel:WORD_1
	v_or_b32_sdwa v92, v96, v95 dst_sel:DWORD dst_unused:UNUSED_PAD src0_sel:DWORD src1_sel:WORD_1
	global_store_dwordx2 v[90:91], v[92:93], off
	v_and_b32_sdwa v93, v122, v177 dst_sel:DWORD dst_unused:UNUSED_PAD src0_sel:WORD_1 src1_sel:DWORD
	v_add3_u32 v95, v122, v93, s28
	v_and_b32_sdwa v93, v125, v177 dst_sel:DWORD dst_unused:UNUSED_PAD src0_sel:WORD_1 src1_sel:DWORD
	v_and_b32_sdwa v96, v123, v177 dst_sel:DWORD dst_unused:UNUSED_PAD src0_sel:WORD_1 src1_sel:DWORD
	v_and_b32_sdwa v92, v124, v177 dst_sel:DWORD dst_unused:UNUSED_PAD src0_sel:WORD_1 src1_sel:DWORD
	v_add3_u32 v93, v125, v93, s28
	v_add3_u32 v96, v123, v96, s28
	v_add3_u32 v92, v124, v92, s28
	v_and_b32_e32 v93, 0xffff0000, v93
	v_and_b32_e32 v96, 0xffff0000, v96
	v_or_b32_sdwa v93, v93, v92 dst_sel:DWORD dst_unused:UNUSED_PAD src0_sel:DWORD src1_sel:WORD_1
	v_or_b32_sdwa v92, v96, v95 dst_sel:DWORD dst_unused:UNUSED_PAD src0_sel:DWORD src1_sel:WORD_1
	global_store_dwordx2 v[90:91], v[92:93], off offset:32
	v_and_b32_sdwa v93, v114, v177 dst_sel:DWORD dst_unused:UNUSED_PAD src0_sel:WORD_1 src1_sel:DWORD
	v_add3_u32 v95, v114, v93, s28
	v_and_b32_sdwa v93, v117, v177 dst_sel:DWORD dst_unused:UNUSED_PAD src0_sel:WORD_1 src1_sel:DWORD
	v_and_b32_sdwa v96, v115, v177 dst_sel:DWORD dst_unused:UNUSED_PAD src0_sel:WORD_1 src1_sel:DWORD
	v_and_b32_sdwa v92, v116, v177 dst_sel:DWORD dst_unused:UNUSED_PAD src0_sel:WORD_1 src1_sel:DWORD
	v_add3_u32 v93, v117, v93, s28
	v_add3_u32 v96, v115, v96, s28
	v_add3_u32 v92, v116, v92, s28
	v_and_b32_e32 v93, 0xffff0000, v93
	v_and_b32_e32 v96, 0xffff0000, v96
	v_or_b32_sdwa v93, v93, v92 dst_sel:DWORD dst_unused:UNUSED_PAD src0_sel:DWORD src1_sel:WORD_1
	v_or_b32_sdwa v92, v96, v95 dst_sel:DWORD dst_unused:UNUSED_PAD src0_sel:DWORD src1_sel:WORD_1
	global_store_dwordx2 v[90:91], v[92:93], off offset:64
	v_and_b32_sdwa v92, v84, v177 dst_sel:DWORD dst_unused:UNUSED_PAD src0_sel:WORD_1 src1_sel:DWORD
	v_and_b32_sdwa v93, v82, v177 dst_sel:DWORD dst_unused:UNUSED_PAD src0_sel:WORD_1 src1_sel:DWORD
	v_add3_u32 v82, v82, v93, s28
	v_add3_u32 v84, v84, v92, s28
	v_and_b32_sdwa v92, v85, v177 dst_sel:DWORD dst_unused:UNUSED_PAD src0_sel:WORD_1 src1_sel:DWORD
	v_and_b32_sdwa v93, v83, v177 dst_sel:DWORD dst_unused:UNUSED_PAD src0_sel:WORD_1 src1_sel:DWORD
	v_add3_u32 v85, v85, v92, s28
	v_add3_u32 v83, v83, v93, s28
	v_and_b32_e32 v85, 0xffff0000, v85
	v_and_b32_e32 v92, 0xffff0000, v83
	v_or_b32_sdwa v83, v85, v84 dst_sel:DWORD dst_unused:UNUSED_PAD src0_sel:DWORD src1_sel:WORD_1
	v_or_b32_sdwa v82, v92, v82 dst_sel:DWORD dst_unused:UNUSED_PAD src0_sel:DWORD src1_sel:WORD_1
	global_store_dwordx2 v[90:91], v[82:83], off offset:96
	v_and_b32_sdwa v82, v80, v177 dst_sel:DWORD dst_unused:UNUSED_PAD src0_sel:WORD_1 src1_sel:DWORD
	v_and_b32_sdwa v83, v78, v177 dst_sel:DWORD dst_unused:UNUSED_PAD src0_sel:WORD_1 src1_sel:DWORD
	v_add3_u32 v78, v78, v83, s28
	v_add3_u32 v80, v80, v82, s28
	v_and_b32_sdwa v82, v81, v177 dst_sel:DWORD dst_unused:UNUSED_PAD src0_sel:WORD_1 src1_sel:DWORD
	v_and_b32_sdwa v83, v79, v177 dst_sel:DWORD dst_unused:UNUSED_PAD src0_sel:WORD_1 src1_sel:DWORD
	v_add3_u32 v81, v81, v82, s28
	v_add3_u32 v79, v79, v83, s28
	v_and_b32_e32 v81, 0xffff0000, v81
	v_and_b32_e32 v82, 0xffff0000, v79
	v_or_b32_sdwa v79, v81, v80 dst_sel:DWORD dst_unused:UNUSED_PAD src0_sel:DWORD src1_sel:WORD_1
	v_or_b32_sdwa v78, v82, v78 dst_sel:DWORD dst_unused:UNUSED_PAD src0_sel:DWORD src1_sel:WORD_1
	global_store_dwordx2 v[90:91], v[78:79], off offset:128
	v_and_b32_sdwa v78, v76, v177 dst_sel:DWORD dst_unused:UNUSED_PAD src0_sel:WORD_1 src1_sel:DWORD
	v_and_b32_sdwa v79, v74, v177 dst_sel:DWORD dst_unused:UNUSED_PAD src0_sel:WORD_1 src1_sel:DWORD
	v_add3_u32 v74, v74, v79, s28
	v_add3_u32 v76, v76, v78, s28
	v_and_b32_sdwa v78, v77, v177 dst_sel:DWORD dst_unused:UNUSED_PAD src0_sel:WORD_1 src1_sel:DWORD
	v_and_b32_sdwa v79, v75, v177 dst_sel:DWORD dst_unused:UNUSED_PAD src0_sel:WORD_1 src1_sel:DWORD
	v_add3_u32 v77, v77, v78, s28
	v_add3_u32 v75, v75, v79, s28
	v_and_b32_e32 v77, 0xffff0000, v77
	v_and_b32_e32 v78, 0xffff0000, v75
	v_or_b32_sdwa v75, v77, v76 dst_sel:DWORD dst_unused:UNUSED_PAD src0_sel:DWORD src1_sel:WORD_1
	v_or_b32_sdwa v74, v78, v74 dst_sel:DWORD dst_unused:UNUSED_PAD src0_sel:DWORD src1_sel:WORD_1
	global_store_dwordx2 v[90:91], v[74:75], off offset:160
	v_and_b32_sdwa v74, v72, v177 dst_sel:DWORD dst_unused:UNUSED_PAD src0_sel:WORD_1 src1_sel:DWORD
	v_and_b32_sdwa v75, v70, v177 dst_sel:DWORD dst_unused:UNUSED_PAD src0_sel:WORD_1 src1_sel:DWORD
	v_add3_u32 v70, v70, v75, s28
	v_add3_u32 v72, v72, v74, s28
	v_and_b32_sdwa v74, v73, v177 dst_sel:DWORD dst_unused:UNUSED_PAD src0_sel:WORD_1 src1_sel:DWORD
	v_and_b32_sdwa v75, v71, v177 dst_sel:DWORD dst_unused:UNUSED_PAD src0_sel:WORD_1 src1_sel:DWORD
	v_add3_u32 v73, v73, v74, s28
	v_add3_u32 v71, v71, v75, s28
	v_and_b32_e32 v73, 0xffff0000, v73
	v_and_b32_e32 v74, 0xffff0000, v71
	v_or_b32_sdwa v71, v73, v72 dst_sel:DWORD dst_unused:UNUSED_PAD src0_sel:DWORD src1_sel:WORD_1
	v_or_b32_sdwa v70, v74, v70 dst_sel:DWORD dst_unused:UNUSED_PAD src0_sel:DWORD src1_sel:WORD_1
	global_store_dwordx2 v[90:91], v[70:71], off offset:192
	v_and_b32_sdwa v70, v64, v177 dst_sel:DWORD dst_unused:UNUSED_PAD src0_sel:WORD_1 src1_sel:DWORD
	v_and_b32_sdwa v71, v62, v177 dst_sel:DWORD dst_unused:UNUSED_PAD src0_sel:WORD_1 src1_sel:DWORD
	v_add3_u32 v64, v64, v70, s28
	v_and_b32_sdwa v70, v65, v177 dst_sel:DWORD dst_unused:UNUSED_PAD src0_sel:WORD_1 src1_sel:DWORD
	v_add3_u32 v62, v62, v71, s28
	v_and_b32_sdwa v71, v63, v177 dst_sel:DWORD dst_unused:UNUSED_PAD src0_sel:WORD_1 src1_sel:DWORD
	v_add3_u32 v65, v65, v70, s28
	v_add3_u32 v63, v63, v71, s28
	v_and_b32_e32 v65, 0xffff0000, v65
	v_and_b32_e32 v70, 0xffff0000, v63
	v_or_b32_sdwa v63, v65, v64 dst_sel:DWORD dst_unused:UNUSED_PAD src0_sel:DWORD src1_sel:WORD_1
	v_and_b32_sdwa v64, v68, v177 dst_sel:DWORD dst_unused:UNUSED_PAD src0_sel:WORD_1 src1_sel:DWORD
	v_and_b32_sdwa v65, v66, v177 dst_sel:DWORD dst_unused:UNUSED_PAD src0_sel:WORD_1 src1_sel:DWORD
	v_or_b32_sdwa v62, v70, v62 dst_sel:DWORD dst_unused:UNUSED_PAD src0_sel:DWORD src1_sel:WORD_1
	v_add3_u32 v66, v66, v65, s28
	v_add3_u32 v64, v68, v64, s28
	v_and_b32_sdwa v65, v69, v177 dst_sel:DWORD dst_unused:UNUSED_PAD src0_sel:WORD_1 src1_sel:DWORD
	v_and_b32_sdwa v68, v67, v177 dst_sel:DWORD dst_unused:UNUSED_PAD src0_sel:WORD_1 src1_sel:DWORD
	global_store_dwordx2 v[90:91], v[62:63], off offset:224
	v_or_b32_e32 v62, 32, v94
	v_add3_u32 v65, v69, v65, s28
	v_add3_u32 v67, v67, v68, s28
	v_mad_i64_i32 v[62:63], s[6:7], v62, s8, v[86:87]
	v_and_b32_e32 v65, 0xffff0000, v65
	v_and_b32_e32 v67, 0xffff0000, v67
	v_lshl_add_u64 v[62:63], v[62:63], 0, v[88:89]
	v_or_b32_sdwa v65, v65, v64 dst_sel:DWORD dst_unused:UNUSED_PAD src0_sel:DWORD src1_sel:WORD_1
	v_or_b32_sdwa v64, v67, v66 dst_sel:DWORD dst_unused:UNUSED_PAD src0_sel:DWORD src1_sel:WORD_1
	global_store_dwordx2 v[62:63], v[64:65], off
	v_and_b32_sdwa v64, v60, v177 dst_sel:DWORD dst_unused:UNUSED_PAD src0_sel:WORD_1 src1_sel:DWORD
	v_and_b32_sdwa v65, v58, v177 dst_sel:DWORD dst_unused:UNUSED_PAD src0_sel:WORD_1 src1_sel:DWORD
	v_add3_u32 v58, v58, v65, s28
	v_add3_u32 v60, v60, v64, s28
	v_and_b32_sdwa v64, v61, v177 dst_sel:DWORD dst_unused:UNUSED_PAD src0_sel:WORD_1 src1_sel:DWORD
	v_and_b32_sdwa v65, v59, v177 dst_sel:DWORD dst_unused:UNUSED_PAD src0_sel:WORD_1 src1_sel:DWORD
	v_add3_u32 v61, v61, v64, s28
	v_add3_u32 v59, v59, v65, s28
	v_and_b32_e32 v61, 0xffff0000, v61
	v_and_b32_e32 v64, 0xffff0000, v59
	v_or_b32_sdwa v59, v61, v60 dst_sel:DWORD dst_unused:UNUSED_PAD src0_sel:DWORD src1_sel:WORD_1
	v_or_b32_sdwa v58, v64, v58 dst_sel:DWORD dst_unused:UNUSED_PAD src0_sel:DWORD src1_sel:WORD_1
	global_store_dwordx2 v[62:63], v[58:59], off offset:32
	v_and_b32_sdwa v58, v56, v177 dst_sel:DWORD dst_unused:UNUSED_PAD src0_sel:WORD_1 src1_sel:DWORD
	v_and_b32_sdwa v59, v54, v177 dst_sel:DWORD dst_unused:UNUSED_PAD src0_sel:WORD_1 src1_sel:DWORD
	v_add3_u32 v54, v54, v59, s28
	v_add3_u32 v56, v56, v58, s28
	v_and_b32_sdwa v58, v57, v177 dst_sel:DWORD dst_unused:UNUSED_PAD src0_sel:WORD_1 src1_sel:DWORD
	v_and_b32_sdwa v59, v55, v177 dst_sel:DWORD dst_unused:UNUSED_PAD src0_sel:WORD_1 src1_sel:DWORD
	v_add3_u32 v57, v57, v58, s28
	v_add3_u32 v55, v55, v59, s28
	v_and_b32_e32 v57, 0xffff0000, v57
	v_and_b32_e32 v58, 0xffff0000, v55
	v_or_b32_sdwa v55, v57, v56 dst_sel:DWORD dst_unused:UNUSED_PAD src0_sel:DWORD src1_sel:WORD_1
	v_or_b32_sdwa v54, v58, v54 dst_sel:DWORD dst_unused:UNUSED_PAD src0_sel:DWORD src1_sel:WORD_1
	global_store_dwordx2 v[62:63], v[54:55], off offset:64
	v_and_b32_sdwa v54, v52, v177 dst_sel:DWORD dst_unused:UNUSED_PAD src0_sel:WORD_1 src1_sel:DWORD
	v_and_b32_sdwa v55, v50, v177 dst_sel:DWORD dst_unused:UNUSED_PAD src0_sel:WORD_1 src1_sel:DWORD
	v_add3_u32 v50, v50, v55, s28
	v_add3_u32 v52, v52, v54, s28
	v_and_b32_sdwa v54, v53, v177 dst_sel:DWORD dst_unused:UNUSED_PAD src0_sel:WORD_1 src1_sel:DWORD
	v_and_b32_sdwa v55, v51, v177 dst_sel:DWORD dst_unused:UNUSED_PAD src0_sel:WORD_1 src1_sel:DWORD
	v_add3_u32 v53, v53, v54, s28
	v_add3_u32 v51, v51, v55, s28
	v_and_b32_e32 v53, 0xffff0000, v53
	v_and_b32_e32 v54, 0xffff0000, v51
	v_or_b32_sdwa v51, v53, v52 dst_sel:DWORD dst_unused:UNUSED_PAD src0_sel:DWORD src1_sel:WORD_1
	v_or_b32_sdwa v50, v54, v50 dst_sel:DWORD dst_unused:UNUSED_PAD src0_sel:DWORD src1_sel:WORD_1
	global_store_dwordx2 v[62:63], v[50:51], off offset:96
	v_and_b32_sdwa v50, v48, v177 dst_sel:DWORD dst_unused:UNUSED_PAD src0_sel:WORD_1 src1_sel:DWORD
	v_and_b32_sdwa v51, v46, v177 dst_sel:DWORD dst_unused:UNUSED_PAD src0_sel:WORD_1 src1_sel:DWORD
	v_add3_u32 v46, v46, v51, s28
	v_add3_u32 v48, v48, v50, s28
	v_and_b32_sdwa v50, v49, v177 dst_sel:DWORD dst_unused:UNUSED_PAD src0_sel:WORD_1 src1_sel:DWORD
	v_and_b32_sdwa v51, v47, v177 dst_sel:DWORD dst_unused:UNUSED_PAD src0_sel:WORD_1 src1_sel:DWORD
	v_add3_u32 v49, v49, v50, s28
	v_add3_u32 v47, v47, v51, s28
	v_and_b32_e32 v49, 0xffff0000, v49
	v_and_b32_e32 v50, 0xffff0000, v47
	v_or_b32_sdwa v47, v49, v48 dst_sel:DWORD dst_unused:UNUSED_PAD src0_sel:DWORD src1_sel:WORD_1
	v_or_b32_sdwa v46, v50, v46 dst_sel:DWORD dst_unused:UNUSED_PAD src0_sel:DWORD src1_sel:WORD_1
	global_store_dwordx2 v[62:63], v[46:47], off offset:128
	v_and_b32_sdwa v46, v44, v177 dst_sel:DWORD dst_unused:UNUSED_PAD src0_sel:WORD_1 src1_sel:DWORD
	v_and_b32_sdwa v47, v42, v177 dst_sel:DWORD dst_unused:UNUSED_PAD src0_sel:WORD_1 src1_sel:DWORD
	v_add3_u32 v42, v42, v47, s28
	v_add3_u32 v44, v44, v46, s28
	v_and_b32_sdwa v46, v45, v177 dst_sel:DWORD dst_unused:UNUSED_PAD src0_sel:WORD_1 src1_sel:DWORD
	v_and_b32_sdwa v47, v43, v177 dst_sel:DWORD dst_unused:UNUSED_PAD src0_sel:WORD_1 src1_sel:DWORD
	v_add3_u32 v45, v45, v46, s28
	v_add3_u32 v43, v43, v47, s28
	v_and_b32_e32 v45, 0xffff0000, v45
	v_and_b32_e32 v46, 0xffff0000, v43
	v_or_b32_sdwa v43, v45, v44 dst_sel:DWORD dst_unused:UNUSED_PAD src0_sel:DWORD src1_sel:WORD_1
	v_or_b32_sdwa v42, v46, v42 dst_sel:DWORD dst_unused:UNUSED_PAD src0_sel:DWORD src1_sel:WORD_1
	global_store_dwordx2 v[62:63], v[42:43], off offset:160
	v_and_b32_sdwa v42, v40, v177 dst_sel:DWORD dst_unused:UNUSED_PAD src0_sel:WORD_1 src1_sel:DWORD
	v_and_b32_sdwa v43, v38, v177 dst_sel:DWORD dst_unused:UNUSED_PAD src0_sel:WORD_1 src1_sel:DWORD
	v_add3_u32 v38, v38, v43, s28
	v_add3_u32 v40, v40, v42, s28
	v_and_b32_sdwa v42, v41, v177 dst_sel:DWORD dst_unused:UNUSED_PAD src0_sel:WORD_1 src1_sel:DWORD
	v_and_b32_sdwa v43, v39, v177 dst_sel:DWORD dst_unused:UNUSED_PAD src0_sel:WORD_1 src1_sel:DWORD
	v_add3_u32 v41, v41, v42, s28
	v_add3_u32 v39, v39, v43, s28
	v_and_b32_e32 v41, 0xffff0000, v41
	v_and_b32_e32 v42, 0xffff0000, v39
	v_or_b32_sdwa v39, v41, v40 dst_sel:DWORD dst_unused:UNUSED_PAD src0_sel:DWORD src1_sel:WORD_1
	v_or_b32_sdwa v38, v42, v38 dst_sel:DWORD dst_unused:UNUSED_PAD src0_sel:DWORD src1_sel:WORD_1
	global_store_dwordx2 v[62:63], v[38:39], off offset:192
	v_and_b32_sdwa v38, v32, v177 dst_sel:DWORD dst_unused:UNUSED_PAD src0_sel:WORD_1 src1_sel:DWORD
	v_and_b32_sdwa v39, v30, v177 dst_sel:DWORD dst_unused:UNUSED_PAD src0_sel:WORD_1 src1_sel:DWORD
	v_add3_u32 v32, v32, v38, s28
	v_and_b32_sdwa v38, v33, v177 dst_sel:DWORD dst_unused:UNUSED_PAD src0_sel:WORD_1 src1_sel:DWORD
	v_add3_u32 v30, v30, v39, s28
	v_and_b32_sdwa v39, v31, v177 dst_sel:DWORD dst_unused:UNUSED_PAD src0_sel:WORD_1 src1_sel:DWORD
	v_add3_u32 v33, v33, v38, s28
	v_add3_u32 v31, v31, v39, s28
	v_and_b32_e32 v33, 0xffff0000, v33
	v_and_b32_e32 v38, 0xffff0000, v31
	v_or_b32_sdwa v31, v33, v32 dst_sel:DWORD dst_unused:UNUSED_PAD src0_sel:DWORD src1_sel:WORD_1
	v_and_b32_sdwa v32, v36, v177 dst_sel:DWORD dst_unused:UNUSED_PAD src0_sel:WORD_1 src1_sel:DWORD
	v_and_b32_sdwa v33, v34, v177 dst_sel:DWORD dst_unused:UNUSED_PAD src0_sel:WORD_1 src1_sel:DWORD
	v_or_b32_sdwa v30, v38, v30 dst_sel:DWORD dst_unused:UNUSED_PAD src0_sel:DWORD src1_sel:WORD_1
	v_add3_u32 v34, v34, v33, s28
	v_add3_u32 v32, v36, v32, s28
	v_and_b32_sdwa v33, v37, v177 dst_sel:DWORD dst_unused:UNUSED_PAD src0_sel:WORD_1 src1_sel:DWORD
	v_and_b32_sdwa v36, v35, v177 dst_sel:DWORD dst_unused:UNUSED_PAD src0_sel:WORD_1 src1_sel:DWORD
	global_store_dwordx2 v[62:63], v[30:31], off offset:224
	v_or_b32_e32 v30, 48, v94
	v_add3_u32 v33, v37, v33, s28
	v_add3_u32 v35, v35, v36, s28
	v_mad_i64_i32 v[30:31], s[6:7], v30, s8, v[86:87]
	v_and_b32_e32 v33, 0xffff0000, v33
	v_and_b32_e32 v35, 0xffff0000, v35
	v_lshl_add_u64 v[30:31], v[30:31], 0, v[88:89]
	v_or_b32_sdwa v33, v33, v32 dst_sel:DWORD dst_unused:UNUSED_PAD src0_sel:DWORD src1_sel:WORD_1
	v_or_b32_sdwa v32, v35, v34 dst_sel:DWORD dst_unused:UNUSED_PAD src0_sel:DWORD src1_sel:WORD_1
	global_store_dwordx2 v[30:31], v[32:33], off
	v_and_b32_sdwa v32, v28, v177 dst_sel:DWORD dst_unused:UNUSED_PAD src0_sel:WORD_1 src1_sel:DWORD
	v_and_b32_sdwa v33, v26, v177 dst_sel:DWORD dst_unused:UNUSED_PAD src0_sel:WORD_1 src1_sel:DWORD
	v_add3_u32 v26, v26, v33, s28
	v_add3_u32 v28, v28, v32, s28
	v_and_b32_sdwa v32, v29, v177 dst_sel:DWORD dst_unused:UNUSED_PAD src0_sel:WORD_1 src1_sel:DWORD
	v_and_b32_sdwa v33, v27, v177 dst_sel:DWORD dst_unused:UNUSED_PAD src0_sel:WORD_1 src1_sel:DWORD
	v_add3_u32 v29, v29, v32, s28
	v_add3_u32 v27, v27, v33, s28
	v_and_b32_e32 v29, 0xffff0000, v29
	v_and_b32_e32 v32, 0xffff0000, v27
	v_or_b32_sdwa v27, v29, v28 dst_sel:DWORD dst_unused:UNUSED_PAD src0_sel:DWORD src1_sel:WORD_1
	v_or_b32_sdwa v26, v32, v26 dst_sel:DWORD dst_unused:UNUSED_PAD src0_sel:DWORD src1_sel:WORD_1
	global_store_dwordx2 v[30:31], v[26:27], off offset:32
	v_and_b32_sdwa v26, v24, v177 dst_sel:DWORD dst_unused:UNUSED_PAD src0_sel:WORD_1 src1_sel:DWORD
	v_and_b32_sdwa v27, v22, v177 dst_sel:DWORD dst_unused:UNUSED_PAD src0_sel:WORD_1 src1_sel:DWORD
	v_add3_u32 v22, v22, v27, s28
	v_add3_u32 v24, v24, v26, s28
	v_and_b32_sdwa v26, v25, v177 dst_sel:DWORD dst_unused:UNUSED_PAD src0_sel:WORD_1 src1_sel:DWORD
	v_and_b32_sdwa v27, v23, v177 dst_sel:DWORD dst_unused:UNUSED_PAD src0_sel:WORD_1 src1_sel:DWORD
	v_add3_u32 v25, v25, v26, s28
	v_add3_u32 v23, v23, v27, s28
	v_and_b32_e32 v25, 0xffff0000, v25
	v_and_b32_e32 v26, 0xffff0000, v23
	v_or_b32_sdwa v23, v25, v24 dst_sel:DWORD dst_unused:UNUSED_PAD src0_sel:DWORD src1_sel:WORD_1
	v_or_b32_sdwa v22, v26, v22 dst_sel:DWORD dst_unused:UNUSED_PAD src0_sel:DWORD src1_sel:WORD_1
	global_store_dwordx2 v[30:31], v[22:23], off offset:64
	v_and_b32_sdwa v22, v20, v177 dst_sel:DWORD dst_unused:UNUSED_PAD src0_sel:WORD_1 src1_sel:DWORD
	v_and_b32_sdwa v23, v18, v177 dst_sel:DWORD dst_unused:UNUSED_PAD src0_sel:WORD_1 src1_sel:DWORD
	v_add3_u32 v18, v18, v23, s28
	v_add3_u32 v20, v20, v22, s28
	v_and_b32_sdwa v22, v21, v177 dst_sel:DWORD dst_unused:UNUSED_PAD src0_sel:WORD_1 src1_sel:DWORD
	v_and_b32_sdwa v23, v19, v177 dst_sel:DWORD dst_unused:UNUSED_PAD src0_sel:WORD_1 src1_sel:DWORD
	v_add3_u32 v21, v21, v22, s28
	v_add3_u32 v19, v19, v23, s28
	v_and_b32_e32 v21, 0xffff0000, v21
	v_and_b32_e32 v22, 0xffff0000, v19
	v_or_b32_sdwa v19, v21, v20 dst_sel:DWORD dst_unused:UNUSED_PAD src0_sel:DWORD src1_sel:WORD_1
	v_or_b32_sdwa v18, v22, v18 dst_sel:DWORD dst_unused:UNUSED_PAD src0_sel:DWORD src1_sel:WORD_1
	global_store_dwordx2 v[30:31], v[18:19], off offset:96
	v_and_b32_sdwa v18, v16, v177 dst_sel:DWORD dst_unused:UNUSED_PAD src0_sel:WORD_1 src1_sel:DWORD
	v_and_b32_sdwa v19, v14, v177 dst_sel:DWORD dst_unused:UNUSED_PAD src0_sel:WORD_1 src1_sel:DWORD
	v_add3_u32 v14, v14, v19, s28
	v_add3_u32 v16, v16, v18, s28
	v_and_b32_sdwa v18, v17, v177 dst_sel:DWORD dst_unused:UNUSED_PAD src0_sel:WORD_1 src1_sel:DWORD
	v_and_b32_sdwa v19, v15, v177 dst_sel:DWORD dst_unused:UNUSED_PAD src0_sel:WORD_1 src1_sel:DWORD
	v_add3_u32 v17, v17, v18, s28
	v_add3_u32 v15, v15, v19, s28
	v_and_b32_e32 v17, 0xffff0000, v17
	v_and_b32_e32 v18, 0xffff0000, v15
	v_or_b32_sdwa v15, v17, v16 dst_sel:DWORD dst_unused:UNUSED_PAD src0_sel:DWORD src1_sel:WORD_1
	v_or_b32_sdwa v14, v18, v14 dst_sel:DWORD dst_unused:UNUSED_PAD src0_sel:DWORD src1_sel:WORD_1
	global_store_dwordx2 v[30:31], v[14:15], off offset:128
	v_and_b32_sdwa v14, v12, v177 dst_sel:DWORD dst_unused:UNUSED_PAD src0_sel:WORD_1 src1_sel:DWORD
	v_and_b32_sdwa v15, v10, v177 dst_sel:DWORD dst_unused:UNUSED_PAD src0_sel:WORD_1 src1_sel:DWORD
	v_add3_u32 v10, v10, v15, s28
	v_add3_u32 v12, v12, v14, s28
	v_and_b32_sdwa v14, v13, v177 dst_sel:DWORD dst_unused:UNUSED_PAD src0_sel:WORD_1 src1_sel:DWORD
	v_and_b32_sdwa v15, v11, v177 dst_sel:DWORD dst_unused:UNUSED_PAD src0_sel:WORD_1 src1_sel:DWORD
	v_add3_u32 v13, v13, v14, s28
	v_add3_u32 v11, v11, v15, s28
	v_and_b32_e32 v13, 0xffff0000, v13
	v_and_b32_e32 v14, 0xffff0000, v11
	v_or_b32_sdwa v11, v13, v12 dst_sel:DWORD dst_unused:UNUSED_PAD src0_sel:DWORD src1_sel:WORD_1
	v_or_b32_sdwa v10, v14, v10 dst_sel:DWORD dst_unused:UNUSED_PAD src0_sel:DWORD src1_sel:WORD_1
	global_store_dwordx2 v[30:31], v[10:11], off offset:160
	v_and_b32_sdwa v10, v8, v177 dst_sel:DWORD dst_unused:UNUSED_PAD src0_sel:WORD_1 src1_sel:DWORD
	v_and_b32_sdwa v11, v6, v177 dst_sel:DWORD dst_unused:UNUSED_PAD src0_sel:WORD_1 src1_sel:DWORD
	v_add3_u32 v6, v6, v11, s28
	v_add3_u32 v8, v8, v10, s28
	v_and_b32_sdwa v10, v9, v177 dst_sel:DWORD dst_unused:UNUSED_PAD src0_sel:WORD_1 src1_sel:DWORD
	v_and_b32_sdwa v11, v7, v177 dst_sel:DWORD dst_unused:UNUSED_PAD src0_sel:WORD_1 src1_sel:DWORD
	v_add3_u32 v9, v9, v10, s28
	v_add3_u32 v7, v7, v11, s28
	v_and_b32_e32 v9, 0xffff0000, v9
	v_and_b32_e32 v10, 0xffff0000, v7
	v_or_b32_sdwa v7, v9, v8 dst_sel:DWORD dst_unused:UNUSED_PAD src0_sel:DWORD src1_sel:WORD_1
	v_or_b32_sdwa v6, v10, v6 dst_sel:DWORD dst_unused:UNUSED_PAD src0_sel:DWORD src1_sel:WORD_1
	global_store_dwordx2 v[30:31], v[6:7], off offset:192
	v_and_b32_sdwa v6, v4, v177 dst_sel:DWORD dst_unused:UNUSED_PAD src0_sel:WORD_1 src1_sel:DWORD
	v_and_b32_sdwa v7, v2, v177 dst_sel:DWORD dst_unused:UNUSED_PAD src0_sel:WORD_1 src1_sel:DWORD
	v_add3_u32 v2, v2, v7, s28
	v_add3_u32 v4, v4, v6, s28
	v_and_b32_sdwa v6, v5, v177 dst_sel:DWORD dst_unused:UNUSED_PAD src0_sel:WORD_1 src1_sel:DWORD
	v_and_b32_sdwa v7, v3, v177 dst_sel:DWORD dst_unused:UNUSED_PAD src0_sel:WORD_1 src1_sel:DWORD
	v_add3_u32 v5, v5, v6, s28
	v_add3_u32 v3, v3, v7, s28
	v_and_b32_e32 v5, 0xffff0000, v5
	v_and_b32_e32 v6, 0xffff0000, v3
	s_add_i32 s11, s11, s10
	v_or_b32_sdwa v3, v5, v4 dst_sel:DWORD dst_unused:UNUSED_PAD src0_sel:DWORD src1_sel:WORD_1
	v_or_b32_sdwa v2, v6, v2 dst_sel:DWORD dst_unused:UNUSED_PAD src0_sel:DWORD src1_sel:WORD_1
	s_cmpk_gt_i32 s11, 0x3ef
	global_store_dwordx2 v[30:31], v[2:3], off offset:224
	s_cbranch_scc0 .LBB0_664

.LBB0_1308:
	s_bitcmp1_b32 s4, 0
	s_cselect_b32 s2, 0x12000, 0
	v_or_b32_e32 v218, s2, v207
	v_add_u32_e32 v214, v218, v0
	v_add_u32_e32 v246, v218, v167
	ds_read_b128 v[184:187], v214
	ds_read_b128 v[218:221], v246 offset:32768
	ds_read_b128 v[198:201], v214 offset:2048
	ds_read_b128 v[210:213], v214 offset:4096
	ds_read_b128 v[214:217], v214 offset:6144
	ds_read_b128 v[222:225], v246 offset:34816
	ds_read_b128 v[226:229], v246 offset:36864
	ds_read_b128 v[230:233], v246 offset:38912
	ds_read_b128 v[234:237], v246 offset:40960
	ds_read_b128 v[238:241], v246 offset:43008
	ds_read_b128 v[242:245], v246 offset:45056
	ds_read_b128 v[246:249], v246 offset:47104
	s_add_i32 s10, s4, 1
	s_bitcmp1_b32 s10, 0
	s_cselect_b32 s3, 0x12000, 0
	v_add_u32_e32 v171, s3, v166
	v_xor_b32_e32 v169, 64, v207
	v_add3_u32 v169, s2, v167, v169
	s_waitcnt lgkmcnt(10)
	v_mfma_f32_16x16x32_bf16 v[158:161], v[218:221], v[184:187], v[158:161]
	s_waitcnt lgkmcnt(9)
	v_mfma_f32_16x16x32_bf16 v[98:101], v[218:221], v[198:201], v[98:101]
	s_waitcnt lgkmcnt(8)
	v_mfma_f32_16x16x32_bf16 v[66:69], v[218:221], v[210:213], v[66:69]
	s_waitcnt lgkmcnt(7)
	v_mfma_f32_16x16x32_bf16 v[34:37], v[218:221], v[214:217], v[34:37]
	ds_read_b128 v[218:221], v169 offset:32768
	s_waitcnt lgkmcnt(7)
	v_mfma_f32_16x16x32_bf16 v[154:157], v[222:225], v[184:187], v[154:157]
	v_mfma_f32_16x16x32_bf16 v[90:93], v[222:225], v[198:201], v[90:93]
	v_mfma_f32_16x16x32_bf16 v[58:61], v[222:225], v[210:213], v[58:61]
	v_mfma_f32_16x16x32_bf16 v[26:29], v[222:225], v[214:217], v[26:29]
	ds_read_b128 v[222:225], v169 offset:34816
	s_waitcnt lgkmcnt(7)
	v_mfma_f32_16x16x32_bf16 v[150:153], v[226:229], v[184:187], v[150:153]
	v_mfma_f32_16x16x32_bf16 v[86:89], v[226:229], v[198:201], v[86:89]
	v_mfma_f32_16x16x32_bf16 v[54:57], v[226:229], v[210:213], v[54:57]
	v_mfma_f32_16x16x32_bf16 v[22:25], v[226:229], v[214:217], v[22:25]
	ds_read_b128 v[226:229], v169 offset:36864
	s_waitcnt lgkmcnt(7)
	v_mfma_f32_16x16x32_bf16 v[146:149], v[230:233], v[184:187], v[146:149]
	v_mfma_f32_16x16x32_bf16 v[82:85], v[230:233], v[198:201], v[82:85]
	v_mfma_f32_16x16x32_bf16 v[50:53], v[230:233], v[210:213], v[50:53]
	v_mfma_f32_16x16x32_bf16 v[18:21], v[230:233], v[214:217], v[18:21]
	ds_read_b128 v[230:233], v169 offset:38912
	s_waitcnt lgkmcnt(7)
	v_mfma_f32_16x16x32_bf16 v[142:145], v[234:237], v[184:187], v[142:145]
	v_mfma_f32_16x16x32_bf16 v[78:81], v[234:237], v[198:201], v[78:81]
	v_mfma_f32_16x16x32_bf16 v[46:49], v[234:237], v[210:213], v[46:49]
	v_mfma_f32_16x16x32_bf16 v[14:17], v[234:237], v[214:217], v[14:17]
	ds_read_b128 v[234:237], v169 offset:40960
	s_waitcnt lgkmcnt(7)
	v_mfma_f32_16x16x32_bf16 v[106:109], v[238:241], v[184:187], v[106:109]
	v_mfma_f32_16x16x32_bf16 v[74:77], v[238:241], v[198:201], v[74:77]
	v_mfma_f32_16x16x32_bf16 v[42:45], v[238:241], v[210:213], v[42:45]
	v_mfma_f32_16x16x32_bf16 v[10:13], v[238:241], v[214:217], v[10:13]
	ds_read_b128 v[238:241], v169 offset:43008
	s_waitcnt lgkmcnt(7)
	v_mfma_f32_16x16x32_bf16 v[102:105], v[242:245], v[184:187], v[102:105]
	v_mfma_f32_16x16x32_bf16 v[70:73], v[242:245], v[198:201], v[70:73]
	v_mfma_f32_16x16x32_bf16 v[38:41], v[242:245], v[210:213], v[38:41]
	v_mfma_f32_16x16x32_bf16 v[6:9], v[242:245], v[214:217], v[6:9]
	ds_read_b128 v[242:245], v169 offset:45056
	s_waitcnt lgkmcnt(7)
	v_mfma_f32_16x16x32_bf16 v[94:97], v[246:249], v[184:187], v[94:97]
	v_mfma_f32_16x16x32_bf16 v[62:65], v[246:249], v[198:201], v[62:65]
	v_xor_b32_e32 v169, 64, v207
	v_add3_u32 v169, s2, v0, v169
	ds_read_b128 v[184:187], v169
	ds_read_b128 v[198:201], v169 offset:2048
	v_mfma_f32_16x16x32_bf16 v[30:33], v[246:249], v[210:213], v[30:33]
	ds_read_b128 v[210:213], v169 offset:4096
	v_mfma_f32_16x16x32_bf16 v[2:5], v[246:249], v[214:217], v[2:5]
	ds_read_b128 v[214:217], v169 offset:6144
	v_xor_b32_e32 v169, 64, v207
	v_add3_u32 v169, s2, v167, v169
	ds_read_b128 v[246:249], v169 offset:47104
	s_waitcnt lgkmcnt(4)
	v_mfma_f32_16x16x32_bf16 v[158:161], v[218:221], v[184:187], v[158:161]
	s_waitcnt lgkmcnt(3)
	v_mfma_f32_16x16x32_bf16 v[98:101], v[218:221], v[198:201], v[98:101]
	s_waitcnt lgkmcnt(2)
	v_mfma_f32_16x16x32_bf16 v[66:69], v[218:221], v[210:213], v[66:69]
	s_waitcnt lgkmcnt(1)
	v_mfma_f32_16x16x32_bf16 v[34:37], v[218:221], v[214:217], v[34:37]
	s_waitcnt vmcnt(7)
	ds_write_b128 v171, v[118:121]
	v_mfma_f32_16x16x32_bf16 v[154:157], v[222:225], v[184:187], v[154:157]
	v_mfma_f32_16x16x32_bf16 v[90:93], v[222:225], v[198:201], v[90:93]
	global_load_dwordx4 v[118:121], v168, vcc offset:256
	v_mfma_f32_16x16x32_bf16 v[58:61], v[222:225], v[210:213], v[58:61]
	v_mfma_f32_16x16x32_bf16 v[26:29], v[222:225], v[214:217], v[26:29]
	s_waitcnt vmcnt(7)
	ds_write_b128 v171, v[110:113] offset:8192
	v_mfma_f32_16x16x32_bf16 v[150:153], v[226:229], v[184:187], v[150:153]
	v_mfma_f32_16x16x32_bf16 v[86:89], v[226:229], v[198:201], v[86:89]
	v_add_u32_e32 v110, s34, v168
	global_load_dwordx4 v[110:113], v110, vcc offset:256
	v_mfma_f32_16x16x32_bf16 v[54:57], v[226:229], v[210:213], v[54:57]
	v_mfma_f32_16x16x32_bf16 v[22:25], v[226:229], v[214:217], v[22:25]
	s_waitcnt vmcnt(7)
	ds_write_b128 v171, v[114:117] offset:16384
	v_mfma_f32_16x16x32_bf16 v[146:149], v[230:233], v[184:187], v[146:149]
	v_mfma_f32_16x16x32_bf16 v[82:85], v[230:233], v[198:201], v[82:85]
	v_add_u32_e32 v114, s35, v168
	global_load_dwordx4 v[114:117], v114, vcc offset:256
	v_mfma_f32_16x16x32_bf16 v[50:53], v[230:233], v[210:213], v[50:53]
	v_mfma_f32_16x16x32_bf16 v[18:21], v[230:233], v[214:217], v[18:21]
	s_waitcnt vmcnt(7)
	ds_write_b128 v171, v[130:133] offset:24576
	v_mfma_f32_16x16x32_bf16 v[142:145], v[234:237], v[184:187], v[142:145]
	v_mfma_f32_16x16x32_bf16 v[78:81], v[234:237], v[198:201], v[78:81]
	v_add_u32_e32 v130, s36, v168
	global_load_dwordx4 v[130:133], v130, vcc offset:256
	v_mfma_f32_16x16x32_bf16 v[46:49], v[234:237], v[210:213], v[46:49]
	v_mfma_f32_16x16x32_bf16 v[14:17], v[234:237], v[214:217], v[14:17]
	s_waitcnt vmcnt(7)
	ds_write_b128 v171, v[126:129] offset:32768
	v_mfma_f32_16x16x32_bf16 v[106:109], v[238:241], v[184:187], v[106:109]
	v_mfma_f32_16x16x32_bf16 v[74:77], v[238:241], v[198:201], v[74:77]
	global_load_dwordx4 v[126:129], v170, s[100:101] offset:256
	v_mfma_f32_16x16x32_bf16 v[42:45], v[238:241], v[210:213], v[42:45]
	v_mfma_f32_16x16x32_bf16 v[10:13], v[238:241], v[214:217], v[10:13]
	s_waitcnt vmcnt(7)
	ds_write_b128 v171, v[122:125] offset:40960
	v_mfma_f32_16x16x32_bf16 v[102:105], v[242:245], v[184:187], v[102:105]
	v_mfma_f32_16x16x32_bf16 v[70:73], v[242:245], v[198:201], v[70:73]
	v_add_u32_e32 v122, s34, v170
	global_load_dwordx4 v[122:125], v122, s[100:101] offset:256
	v_mfma_f32_16x16x32_bf16 v[38:41], v[242:245], v[210:213], v[38:41]
	v_mfma_f32_16x16x32_bf16 v[6:9], v[242:245], v[214:217], v[6:9]
	s_waitcnt vmcnt(7)
	ds_write_b128 v171, v[138:141] offset:49152
	s_waitcnt lgkmcnt(7)
	v_mfma_f32_16x16x32_bf16 v[94:97], v[246:249], v[184:187], v[94:97]
	v_mfma_f32_16x16x32_bf16 v[62:65], v[246:249], v[198:201], v[62:65]
	v_add_u32_e32 v138, s35, v170
	global_load_dwordx4 v[138:141], v138, s[100:101] offset:256
	v_mfma_f32_16x16x32_bf16 v[30:33], v[246:249], v[210:213], v[30:33]
	v_mfma_f32_16x16x32_bf16 v[2:5], v[246:249], v[214:217], v[2:5]
	s_waitcnt vmcnt(7)
	ds_write_b128 v171, v[134:137] offset:57344
	v_add_u32_e32 v134, s36, v170
	global_load_dwordx4 v[134:137], v134, s[100:101] offset:256
	v_add_u32_e32 v168, 0x80, v168
	v_add_u32_e32 v170, 0x80, v170
	s_waitcnt lgkmcnt(0)
	s_barrier
	s_cmp_eq_u32 s10, 16
	s_mov_b32 s4, s10
	s_cbranch_scc0 .LBB0_1308
	s_waitcnt vmcnt(4)
	v_add_u32_e32 v110, s7, v206
	s_waitcnt vmcnt(3)
	v_or_b32_e32 v114, v110, v205
	v_cmp_lt_i32_e32 vcc, s97, v114
	v_ashrrev_i32_e32 v112, 31, v114
	v_add_u32_e32 v116, 0xffffc000, v114
	v_ashrrev_i32_e32 v115, 11, v110
	v_cndmask_b32_e64 v113, v112, 0, vcc
	v_cndmask_b32_e32 v112, v114, v116, vcc
	v_mov_b32_e32 v116, s45
	v_mov_b32_e32 v117, s13
	v_mov_b32_e32 v118, s44
	v_mov_b32_e32 v119, s12
	v_or_b32_e32 v110, s6, v208
	s_waitcnt vmcnt(2)
	v_cndmask_b32_e64 v122, v115, 8, vcc
	v_cndmask_b32_e32 v121, v116, v117, vcc
	v_cndmask_b32_e32 v120, v118, v119, vcc
	v_lshlrev_b64 v[112:113], 12, v[112:113]
	v_ashrrev_i32_e32 v111, 31, v110
	v_lshl_add_u64 v[112:113], v[120:121], 0, v[112:113]
	v_mul_hi_i32_i24_e32 v121, 0x9000, v122
	v_mul_i32_i24_e32 v120, 0x9000, v122
	v_lshl_add_u64 v[120:121], s[14:15], 0, v[120:121]
	v_lshlrev_b64 v[110:111], 2, v[110:111]
	s_waitcnt vmcnt(0)
	v_lshl_add_u64 v[128:129], v[120:121], 0, v[110:111]
	v_lshl_add_u64 v[112:113], v[112:113], 0, v[110:111]
	global_load_dwordx4 v[120:123], v[128:129], off
	global_load_dwordx4 v[124:127], v[112:113], off
	s_waitcnt vmcnt(0)
	v_pk_fma_f32 v[120:121], v[158:159], v[120:121], v[124:125]
	v_pk_fma_f32 v[122:123], v[160:161], v[122:123], v[126:127]
	global_store_dwordx4 v[112:113], v[120:123], off
	global_load_dwordx4 v[120:123], v[128:129], off offset:64
	s_nop 0
	global_load_dwordx4 v[124:127], v[112:113], off offset:64
	s_waitcnt vmcnt(0)
	v_pk_fma_f32 v[120:121], v[154:155], v[120:121], v[124:125]
	v_pk_fma_f32 v[122:123], v[156:157], v[122:123], v[126:127]
	global_store_dwordx4 v[112:113], v[120:123], off offset:64
	global_load_dwordx4 v[120:123], v[128:129], off offset:128
	s_nop 0
	global_load_dwordx4 v[124:127], v[112:113], off offset:128
	s_waitcnt vmcnt(0)
	v_pk_fma_f32 v[120:121], v[150:151], v[120:121], v[124:125]
	v_pk_fma_f32 v[122:123], v[152:153], v[122:123], v[126:127]
	global_store_dwordx4 v[112:113], v[120:123], off offset:128
	global_load_dwordx4 v[120:123], v[128:129], off offset:192
	s_nop 0
	global_load_dwordx4 v[124:127], v[112:113], off offset:192
	s_waitcnt vmcnt(0)
	v_pk_fma_f32 v[120:121], v[146:147], v[120:121], v[124:125]
	v_pk_fma_f32 v[122:123], v[148:149], v[122:123], v[126:127]
	global_store_dwordx4 v[112:113], v[120:123], off offset:192
	global_load_dwordx4 v[120:123], v[128:129], off offset:256
	s_nop 0
	global_load_dwordx4 v[124:127], v[112:113], off offset:256
	s_waitcnt vmcnt(0)
	v_pk_fma_f32 v[120:121], v[142:143], v[120:121], v[124:125]
	v_pk_fma_f32 v[122:123], v[144:145], v[122:123], v[126:127]
	global_store_dwordx4 v[112:113], v[120:123], off offset:256
	global_load_dwordx4 v[120:123], v[128:129], off offset:320
	s_nop 0
	global_load_dwordx4 v[124:127], v[112:113], off offset:320
	s_waitcnt vmcnt(0)
	v_pk_fma_f32 v[106:107], v[106:107], v[120:121], v[124:125]
	v_pk_fma_f32 v[108:109], v[108:109], v[122:123], v[126:127]
	global_store_dwordx4 v[112:113], v[106:109], off offset:320
	global_load_dwordx4 v[106:109], v[128:129], off offset:384
	s_nop 0
	global_load_dwordx4 v[120:123], v[112:113], off offset:384
	s_waitcnt vmcnt(0)
	v_pk_fma_f32 v[102:103], v[102:103], v[106:107], v[120:121]
	v_pk_fma_f32 v[104:105], v[104:105], v[108:109], v[122:123]
	global_store_dwordx4 v[112:113], v[102:105], off offset:384
	global_load_dwordx4 v[102:105], v[128:129], off offset:448
	s_nop 0
	global_load_dwordx4 v[106:109], v[112:113], off offset:448
	s_waitcnt vmcnt(0)
	v_pk_fma_f32 v[94:95], v[94:95], v[102:103], v[106:107]
	v_pk_fma_f32 v[96:97], v[96:97], v[104:105], v[108:109]
	global_store_dwordx4 v[112:113], v[94:97], off offset:448
	s_nop 1
	v_or_b32_e32 v94, 16, v114
	v_cmp_lt_i32_e32 vcc, s97, v94
	v_add_u32_e32 v96, 0xffffc010, v114
	v_ashrrev_i32_e32 v95, 31, v94
	v_cndmask_b32_e64 v95, v95, 0, vcc
	v_cndmask_b32_e32 v94, v94, v96, vcc
	v_cndmask_b32_e64 v102, v115, 8, vcc
	v_cndmask_b32_e32 v97, v116, v117, vcc
	v_cndmask_b32_e32 v96, v118, v119, vcc
	v_lshlrev_b64 v[94:95], 12, v[94:95]
	v_lshl_add_u64 v[94:95], v[96:97], 0, v[94:95]
	v_mul_hi_i32_i24_e32 v97, 0x9000, v102
	v_mul_i32_i24_e32 v96, 0x9000, v102
	v_lshl_add_u64 v[96:97], s[14:15], 0, v[96:97]
	v_lshl_add_u64 v[112:113], v[96:97], 0, v[110:111]
	v_lshl_add_u64 v[94:95], v[94:95], 0, v[110:111]
	global_load_dwordx4 v[102:105], v[112:113], off
	global_load_dwordx4 v[106:109], v[94:95], off
	s_waitcnt vmcnt(0)
	v_pk_fma_f32 v[96:97], v[98:99], v[102:103], v[106:107]
	v_pk_fma_f32 v[98:99], v[100:101], v[104:105], v[108:109]
	global_store_dwordx4 v[94:95], v[96:99], off
	global_load_dwordx4 v[96:99], v[112:113], off offset:64
	s_nop 0
	global_load_dwordx4 v[100:103], v[94:95], off offset:64
	s_waitcnt vmcnt(0)
	v_pk_fma_f32 v[90:91], v[90:91], v[96:97], v[100:101]
	v_pk_fma_f32 v[92:93], v[92:93], v[98:99], v[102:103]
	global_store_dwordx4 v[94:95], v[90:93], off offset:64
	global_load_dwordx4 v[90:93], v[112:113], off offset:128
	s_nop 0
	global_load_dwordx4 v[96:99], v[94:95], off offset:128
	s_waitcnt vmcnt(0)
	v_pk_fma_f32 v[86:87], v[86:87], v[90:91], v[96:97]
	v_pk_fma_f32 v[88:89], v[88:89], v[92:93], v[98:99]
	global_store_dwordx4 v[94:95], v[86:89], off offset:128
	global_load_dwordx4 v[86:89], v[112:113], off offset:192
	s_nop 0
	global_load_dwordx4 v[90:93], v[94:95], off offset:192
	s_waitcnt vmcnt(0)
	v_pk_fma_f32 v[82:83], v[82:83], v[86:87], v[90:91]
	v_pk_fma_f32 v[84:85], v[84:85], v[88:89], v[92:93]
	global_store_dwordx4 v[94:95], v[82:85], off offset:192
	global_load_dwordx4 v[82:85], v[112:113], off offset:256
	s_nop 0
	global_load_dwordx4 v[86:89], v[94:95], off offset:256
	s_waitcnt vmcnt(0)
	v_pk_fma_f32 v[78:79], v[78:79], v[82:83], v[86:87]
	v_pk_fma_f32 v[80:81], v[80:81], v[84:85], v[88:89]
	global_store_dwordx4 v[94:95], v[78:81], off offset:256
	global_load_dwordx4 v[78:81], v[112:113], off offset:320
	s_nop 0
	global_load_dwordx4 v[82:85], v[94:95], off offset:320
	s_waitcnt vmcnt(0)
	v_pk_fma_f32 v[74:75], v[74:75], v[78:79], v[82:83]
	v_pk_fma_f32 v[76:77], v[76:77], v[80:81], v[84:85]
	global_store_dwordx4 v[94:95], v[74:77], off offset:320
	global_load_dwordx4 v[74:77], v[112:113], off offset:384
	s_nop 0
	global_load_dwordx4 v[78:81], v[94:95], off offset:384
	s_waitcnt vmcnt(0)
	v_pk_fma_f32 v[70:71], v[70:71], v[74:75], v[78:79]
	v_pk_fma_f32 v[72:73], v[72:73], v[76:77], v[80:81]
	global_store_dwordx4 v[94:95], v[70:73], off offset:384
	global_load_dwordx4 v[70:73], v[112:113], off offset:448
	s_nop 0
	global_load_dwordx4 v[74:77], v[94:95], off offset:448
	s_waitcnt vmcnt(0)
	v_pk_fma_f32 v[62:63], v[62:63], v[70:71], v[74:75]
	v_pk_fma_f32 v[64:65], v[64:65], v[72:73], v[76:77]
	global_store_dwordx4 v[94:95], v[62:65], off offset:448
	s_nop 1
	v_or_b32_e32 v62, 32, v114
	v_cmp_lt_i32_e32 vcc, s97, v62
	v_add_u32_e32 v64, 0xffffc020, v114
	v_ashrrev_i32_e32 v63, 31, v62
	v_cndmask_b32_e64 v63, v63, 0, vcc
	v_cndmask_b32_e32 v62, v62, v64, vcc
	v_cndmask_b32_e64 v70, v115, 8, vcc
	v_cndmask_b32_e32 v65, v116, v117, vcc
	v_cndmask_b32_e32 v64, v118, v119, vcc
	v_lshlrev_b64 v[62:63], 12, v[62:63]
	v_lshl_add_u64 v[62:63], v[64:65], 0, v[62:63]
	v_mul_hi_i32_i24_e32 v65, 0x9000, v70
	v_mul_i32_i24_e32 v64, 0x9000, v70
	v_lshl_add_u64 v[64:65], s[14:15], 0, v[64:65]
	v_lshl_add_u64 v[78:79], v[64:65], 0, v[110:111]
	v_lshl_add_u64 v[62:63], v[62:63], 0, v[110:111]
	global_load_dwordx4 v[70:73], v[78:79], off
	global_load_dwordx4 v[74:77], v[62:63], off
	s_waitcnt vmcnt(0)
	v_pk_fma_f32 v[64:65], v[66:67], v[70:71], v[74:75]
	v_pk_fma_f32 v[66:67], v[68:69], v[72:73], v[76:77]
	global_store_dwordx4 v[62:63], v[64:67], off
	global_load_dwordx4 v[64:67], v[78:79], off offset:64
	s_nop 0
	global_load_dwordx4 v[68:71], v[62:63], off offset:64
	s_waitcnt vmcnt(0)
	v_pk_fma_f32 v[58:59], v[58:59], v[64:65], v[68:69]
	v_pk_fma_f32 v[60:61], v[60:61], v[66:67], v[70:71]
	global_store_dwordx4 v[62:63], v[58:61], off offset:64
	global_load_dwordx4 v[58:61], v[78:79], off offset:128
	s_nop 0
	global_load_dwordx4 v[64:67], v[62:63], off offset:128
	s_waitcnt vmcnt(0)
	v_pk_fma_f32 v[54:55], v[54:55], v[58:59], v[64:65]
	v_pk_fma_f32 v[56:57], v[56:57], v[60:61], v[66:67]
	global_store_dwordx4 v[62:63], v[54:57], off offset:128
	global_load_dwordx4 v[54:57], v[78:79], off offset:192
	s_nop 0
	global_load_dwordx4 v[58:61], v[62:63], off offset:192
	s_waitcnt vmcnt(0)
	v_pk_fma_f32 v[50:51], v[50:51], v[54:55], v[58:59]
	v_pk_fma_f32 v[52:53], v[52:53], v[56:57], v[60:61]
	global_store_dwordx4 v[62:63], v[50:53], off offset:192
	global_load_dwordx4 v[50:53], v[78:79], off offset:256
	s_nop 0
	global_load_dwordx4 v[54:57], v[62:63], off offset:256
	s_waitcnt vmcnt(0)
	v_pk_fma_f32 v[46:47], v[46:47], v[50:51], v[54:55]
	v_pk_fma_f32 v[48:49], v[48:49], v[52:53], v[56:57]
	global_store_dwordx4 v[62:63], v[46:49], off offset:256
	global_load_dwordx4 v[46:49], v[78:79], off offset:320
	s_nop 0
	global_load_dwordx4 v[50:53], v[62:63], off offset:320
	s_waitcnt vmcnt(0)
	v_pk_fma_f32 v[42:43], v[42:43], v[46:47], v[50:51]
	v_pk_fma_f32 v[44:45], v[44:45], v[48:49], v[52:53]
	global_store_dwordx4 v[62:63], v[42:45], off offset:320
	global_load_dwordx4 v[42:45], v[78:79], off offset:384
	s_nop 0
	global_load_dwordx4 v[46:49], v[62:63], off offset:384
	s_waitcnt vmcnt(0)
	v_pk_fma_f32 v[38:39], v[38:39], v[42:43], v[46:47]
	v_pk_fma_f32 v[40:41], v[40:41], v[44:45], v[48:49]
	global_store_dwordx4 v[62:63], v[38:41], off offset:384
	global_load_dwordx4 v[38:41], v[78:79], off offset:448
	s_nop 0
	global_load_dwordx4 v[42:45], v[62:63], off offset:448
	s_waitcnt vmcnt(0)
	v_pk_fma_f32 v[30:31], v[30:31], v[38:39], v[42:43]
	v_pk_fma_f32 v[32:33], v[32:33], v[40:41], v[44:45]
	global_store_dwordx4 v[62:63], v[30:33], off offset:448
	s_nop 1
	v_or_b32_e32 v30, 48, v114
	v_cmp_lt_i32_e32 vcc, s97, v30
	v_add_u32_e32 v32, 0xffffc030, v114
	v_ashrrev_i32_e32 v31, 31, v30
	v_cndmask_b32_e64 v31, v31, 0, vcc
	v_cndmask_b32_e32 v30, v30, v32, vcc
	v_cndmask_b32_e64 v38, v115, 8, vcc
	v_cndmask_b32_e32 v33, v116, v117, vcc
	v_cndmask_b32_e32 v32, v118, v119, vcc
	v_lshlrev_b64 v[30:31], 12, v[30:31]
	v_lshl_add_u64 v[30:31], v[32:33], 0, v[30:31]
	v_mul_hi_i32_i24_e32 v33, 0x9000, v38
	v_mul_i32_i24_e32 v32, 0x9000, v38
	v_lshl_add_u64 v[32:33], s[14:15], 0, v[32:33]
	v_lshl_add_u64 v[46:47], v[32:33], 0, v[110:111]
	v_lshl_add_u64 v[30:31], v[30:31], 0, v[110:111]
	global_load_dwordx4 v[38:41], v[46:47], off
	global_load_dwordx4 v[42:45], v[30:31], off
	s_waitcnt vmcnt(0)
	v_pk_fma_f32 v[32:33], v[34:35], v[38:39], v[42:43]
	v_pk_fma_f32 v[34:35], v[36:37], v[40:41], v[44:45]
	global_store_dwordx4 v[30:31], v[32:35], off
	global_load_dwordx4 v[32:35], v[46:47], off offset:64
	s_nop 0
	global_load_dwordx4 v[36:39], v[30:31], off offset:64
	s_waitcnt vmcnt(0)
	v_pk_fma_f32 v[26:27], v[26:27], v[32:33], v[36:37]
	v_pk_fma_f32 v[28:29], v[28:29], v[34:35], v[38:39]
	global_store_dwordx4 v[30:31], v[26:29], off offset:64
	global_load_dwordx4 v[26:29], v[46:47], off offset:128
	s_nop 0
	global_load_dwordx4 v[32:35], v[30:31], off offset:128
	s_waitcnt vmcnt(0)
	v_pk_fma_f32 v[22:23], v[22:23], v[26:27], v[32:33]
	v_pk_fma_f32 v[24:25], v[24:25], v[28:29], v[34:35]
	global_store_dwordx4 v[30:31], v[22:25], off offset:128
	global_load_dwordx4 v[22:25], v[46:47], off offset:192
	s_nop 0
	global_load_dwordx4 v[26:29], v[30:31], off offset:192
	s_waitcnt vmcnt(0)
	v_pk_fma_f32 v[18:19], v[18:19], v[22:23], v[26:27]
	v_pk_fma_f32 v[20:21], v[20:21], v[24:25], v[28:29]
	global_store_dwordx4 v[30:31], v[18:21], off offset:192
	global_load_dwordx4 v[18:21], v[46:47], off offset:256
	s_nop 0
	global_load_dwordx4 v[22:25], v[30:31], off offset:256
	s_waitcnt vmcnt(0)
	v_pk_fma_f32 v[14:15], v[14:15], v[18:19], v[22:23]
	v_pk_fma_f32 v[16:17], v[16:17], v[20:21], v[24:25]
	global_store_dwordx4 v[30:31], v[14:17], off offset:256
	global_load_dwordx4 v[14:17], v[46:47], off offset:320
	s_nop 0
	global_load_dwordx4 v[18:21], v[30:31], off offset:320
	s_waitcnt vmcnt(0)
	v_pk_fma_f32 v[10:11], v[10:11], v[14:15], v[18:19]
	v_pk_fma_f32 v[12:13], v[12:13], v[16:17], v[20:21]
	global_store_dwordx4 v[30:31], v[10:13], off offset:320
	global_load_dwordx4 v[10:13], v[46:47], off offset:384
	s_nop 0
	global_load_dwordx4 v[14:17], v[30:31], off offset:384
	s_waitcnt vmcnt(0)
	v_pk_fma_f32 v[6:7], v[6:7], v[10:11], v[14:15]
	v_pk_fma_f32 v[8:9], v[8:9], v[12:13], v[16:17]
	global_store_dwordx4 v[30:31], v[6:9], off offset:384
	global_load_dwordx4 v[6:9], v[46:47], off offset:448
	s_nop 0
	global_load_dwordx4 v[10:13], v[30:31], off offset:448
	s_waitcnt vmcnt(0)
	v_pk_fma_f32 v[2:3], v[2:3], v[6:7], v[10:11]
	v_pk_fma_f32 v[4:5], v[4:5], v[8:9], v[12:13]
	global_store_dwordx4 v[30:31], v[2:5], off offset:448
	s_add_i32 s19, s19, s18
	s_cmpk_gt_i32 s19, 0xff
	s_cbranch_scc0 .LBB0_1307

.LBB0_1441:
	s_bitcmp1_b32 s4, 0
	s_cselect_b32 s2, 0x12000, 0
	v_or_b32_e32 v218, s2, v206
	v_add_u32_e32 v214, v218, v0
	v_add_u32_e32 v246, v218, v167
	ds_read_b128 v[184:187], v214
	ds_read_b128 v[218:221], v246 offset:32768
	ds_read_b128 v[198:201], v214 offset:2048
	ds_read_b128 v[210:213], v214 offset:4096
	ds_read_b128 v[214:217], v214 offset:6144
	ds_read_b128 v[222:225], v246 offset:34816
	ds_read_b128 v[226:229], v246 offset:36864
	ds_read_b128 v[230:233], v246 offset:38912
	ds_read_b128 v[234:237], v246 offset:40960
	ds_read_b128 v[238:241], v246 offset:43008
	ds_read_b128 v[242:245], v246 offset:45056
	ds_read_b128 v[246:249], v246 offset:47104
	s_add_i32 s10, s4, 1
	s_bitcmp1_b32 s10, 0
	s_cselect_b32 s3, 0x12000, 0
	v_add_u32_e32 v171, s3, v166
	v_xor_b32_e32 v169, 64, v206
	v_add3_u32 v169, s2, v167, v169
	s_waitcnt lgkmcnt(10)
	v_mfma_f32_16x16x32_bf16 v[158:161], v[218:221], v[184:187], v[158:161]
	s_waitcnt lgkmcnt(9)
	v_mfma_f32_16x16x32_bf16 v[94:97], v[218:221], v[198:201], v[94:97]
	s_waitcnt lgkmcnt(8)
	v_mfma_f32_16x16x32_bf16 v[62:65], v[218:221], v[210:213], v[62:65]
	s_waitcnt lgkmcnt(7)
	v_mfma_f32_16x16x32_bf16 v[30:33], v[218:221], v[214:217], v[30:33]
	ds_read_b128 v[218:221], v169 offset:32768
	s_waitcnt lgkmcnt(7)
	v_mfma_f32_16x16x32_bf16 v[154:157], v[222:225], v[184:187], v[154:157]
	v_mfma_f32_16x16x32_bf16 v[90:93], v[222:225], v[198:201], v[90:93]
	v_mfma_f32_16x16x32_bf16 v[58:61], v[222:225], v[210:213], v[58:61]
	v_mfma_f32_16x16x32_bf16 v[26:29], v[222:225], v[214:217], v[26:29]
	ds_read_b128 v[222:225], v169 offset:34816
	s_waitcnt lgkmcnt(7)
	v_mfma_f32_16x16x32_bf16 v[150:153], v[226:229], v[184:187], v[150:153]
	v_mfma_f32_16x16x32_bf16 v[86:89], v[226:229], v[198:201], v[86:89]
	v_mfma_f32_16x16x32_bf16 v[54:57], v[226:229], v[210:213], v[54:57]
	v_mfma_f32_16x16x32_bf16 v[22:25], v[226:229], v[214:217], v[22:25]
	ds_read_b128 v[226:229], v169 offset:36864
	s_waitcnt lgkmcnt(7)
	v_mfma_f32_16x16x32_bf16 v[146:149], v[230:233], v[184:187], v[146:149]
	v_mfma_f32_16x16x32_bf16 v[82:85], v[230:233], v[198:201], v[82:85]
	v_mfma_f32_16x16x32_bf16 v[50:53], v[230:233], v[210:213], v[50:53]
	v_mfma_f32_16x16x32_bf16 v[18:21], v[230:233], v[214:217], v[18:21]
	ds_read_b128 v[230:233], v169 offset:38912
	s_waitcnt lgkmcnt(7)
	v_mfma_f32_16x16x32_bf16 v[142:145], v[234:237], v[184:187], v[142:145]
	v_mfma_f32_16x16x32_bf16 v[78:81], v[234:237], v[198:201], v[78:81]
	v_mfma_f32_16x16x32_bf16 v[46:49], v[234:237], v[210:213], v[46:49]
	v_mfma_f32_16x16x32_bf16 v[14:17], v[234:237], v[214:217], v[14:17]
	ds_read_b128 v[234:237], v169 offset:40960
	s_waitcnt lgkmcnt(7)
	v_mfma_f32_16x16x32_bf16 v[138:141], v[238:241], v[184:187], v[138:141]
	v_mfma_f32_16x16x32_bf16 v[74:77], v[238:241], v[198:201], v[74:77]
	v_mfma_f32_16x16x32_bf16 v[42:45], v[238:241], v[210:213], v[42:45]
	v_mfma_f32_16x16x32_bf16 v[10:13], v[238:241], v[214:217], v[10:13]
	ds_read_b128 v[238:241], v169 offset:43008
	s_waitcnt lgkmcnt(7)
	v_mfma_f32_16x16x32_bf16 v[102:105], v[242:245], v[184:187], v[102:105]
	v_mfma_f32_16x16x32_bf16 v[70:73], v[242:245], v[198:201], v[70:73]
	v_mfma_f32_16x16x32_bf16 v[38:41], v[242:245], v[210:213], v[38:41]
	v_mfma_f32_16x16x32_bf16 v[6:9], v[242:245], v[214:217], v[6:9]
	ds_read_b128 v[242:245], v169 offset:45056
	s_waitcnt lgkmcnt(7)
	v_mfma_f32_16x16x32_bf16 v[98:101], v[246:249], v[184:187], v[98:101]
	v_mfma_f32_16x16x32_bf16 v[66:69], v[246:249], v[198:201], v[66:69]
	v_xor_b32_e32 v169, 64, v206
	v_add3_u32 v169, s2, v0, v169
	ds_read_b128 v[184:187], v169
	ds_read_b128 v[198:201], v169 offset:2048
	v_mfma_f32_16x16x32_bf16 v[34:37], v[246:249], v[210:213], v[34:37]
	ds_read_b128 v[210:213], v169 offset:4096
	v_mfma_f32_16x16x32_bf16 v[2:5], v[246:249], v[214:217], v[2:5]
	ds_read_b128 v[214:217], v169 offset:6144
	v_xor_b32_e32 v169, 64, v206
	v_add3_u32 v169, s2, v167, v169
	ds_read_b128 v[246:249], v169 offset:47104
	s_waitcnt lgkmcnt(4)
	v_mfma_f32_16x16x32_bf16 v[158:161], v[218:221], v[184:187], v[158:161]
	s_waitcnt lgkmcnt(3)
	v_mfma_f32_16x16x32_bf16 v[94:97], v[218:221], v[198:201], v[94:97]
	s_waitcnt lgkmcnt(2)
	v_mfma_f32_16x16x32_bf16 v[62:65], v[218:221], v[210:213], v[62:65]
	s_waitcnt lgkmcnt(1)
	v_mfma_f32_16x16x32_bf16 v[30:33], v[218:221], v[214:217], v[30:33]
	s_waitcnt vmcnt(7)
	ds_write_b128 v171, v[114:117]
	v_mfma_f32_16x16x32_bf16 v[154:157], v[222:225], v[184:187], v[154:157]
	v_mfma_f32_16x16x32_bf16 v[90:93], v[222:225], v[198:201], v[90:93]
	global_load_dwordx4 v[114:117], v168, vcc offset:256
	v_mfma_f32_16x16x32_bf16 v[58:61], v[222:225], v[210:213], v[58:61]
	v_mfma_f32_16x16x32_bf16 v[26:29], v[222:225], v[214:217], v[26:29]
	s_waitcnt vmcnt(7)
	ds_write_b128 v171, v[106:109] offset:8192
	v_mfma_f32_16x16x32_bf16 v[150:153], v[226:229], v[184:187], v[150:153]
	v_mfma_f32_16x16x32_bf16 v[86:89], v[226:229], v[198:201], v[86:89]
	v_add_u32_e32 v106, s34, v168
	global_load_dwordx4 v[106:109], v106, vcc offset:256
	v_mfma_f32_16x16x32_bf16 v[54:57], v[226:229], v[210:213], v[54:57]
	v_mfma_f32_16x16x32_bf16 v[22:25], v[226:229], v[214:217], v[22:25]
	s_waitcnt vmcnt(7)
	ds_write_b128 v171, v[110:113] offset:16384
	v_mfma_f32_16x16x32_bf16 v[146:149], v[230:233], v[184:187], v[146:149]
	v_mfma_f32_16x16x32_bf16 v[82:85], v[230:233], v[198:201], v[82:85]
	v_add_u32_e32 v110, s35, v168
	global_load_dwordx4 v[110:113], v110, vcc offset:256
	v_mfma_f32_16x16x32_bf16 v[50:53], v[230:233], v[210:213], v[50:53]
	v_mfma_f32_16x16x32_bf16 v[18:21], v[230:233], v[214:217], v[18:21]
	s_waitcnt vmcnt(7)
	ds_write_b128 v171, v[126:129] offset:24576
	v_mfma_f32_16x16x32_bf16 v[142:145], v[234:237], v[184:187], v[142:145]
	v_mfma_f32_16x16x32_bf16 v[78:81], v[234:237], v[198:201], v[78:81]
	v_add_u32_e32 v126, s36, v168
	global_load_dwordx4 v[126:129], v126, vcc offset:256
	v_mfma_f32_16x16x32_bf16 v[46:49], v[234:237], v[210:213], v[46:49]
	v_mfma_f32_16x16x32_bf16 v[14:17], v[234:237], v[214:217], v[14:17]
	s_waitcnt vmcnt(7)
	ds_write_b128 v171, v[122:125] offset:32768
	v_mfma_f32_16x16x32_bf16 v[138:141], v[238:241], v[184:187], v[138:141]
	v_mfma_f32_16x16x32_bf16 v[74:77], v[238:241], v[198:201], v[74:77]
	global_load_dwordx4 v[122:125], v170, s[100:101] offset:256
	v_mfma_f32_16x16x32_bf16 v[42:45], v[238:241], v[210:213], v[42:45]
	v_mfma_f32_16x16x32_bf16 v[10:13], v[238:241], v[214:217], v[10:13]
	s_waitcnt vmcnt(7)
	ds_write_b128 v171, v[118:121] offset:40960
	v_mfma_f32_16x16x32_bf16 v[102:105], v[242:245], v[184:187], v[102:105]
	v_mfma_f32_16x16x32_bf16 v[70:73], v[242:245], v[198:201], v[70:73]
	v_add_u32_e32 v118, s34, v170
	global_load_dwordx4 v[118:121], v118, s[100:101] offset:256
	v_mfma_f32_16x16x32_bf16 v[38:41], v[242:245], v[210:213], v[38:41]
	v_mfma_f32_16x16x32_bf16 v[6:9], v[242:245], v[214:217], v[6:9]
	s_waitcnt vmcnt(7)
	ds_write_b128 v171, v[134:137] offset:49152
	s_waitcnt lgkmcnt(7)
	v_mfma_f32_16x16x32_bf16 v[98:101], v[246:249], v[184:187], v[98:101]
	v_mfma_f32_16x16x32_bf16 v[66:69], v[246:249], v[198:201], v[66:69]
	v_add_u32_e32 v134, s35, v170
	global_load_dwordx4 v[134:137], v134, s[100:101] offset:256
	v_mfma_f32_16x16x32_bf16 v[34:37], v[246:249], v[210:213], v[34:37]
	v_mfma_f32_16x16x32_bf16 v[2:5], v[246:249], v[214:217], v[2:5]
	s_waitcnt vmcnt(7)
	ds_write_b128 v171, v[130:133] offset:57344
	v_add_u32_e32 v130, s36, v170
	global_load_dwordx4 v[130:133], v130, s[100:101] offset:256
	v_add_u32_e32 v168, 0x80, v168
	v_add_u32_e32 v170, 0x80, v170
	s_waitcnt lgkmcnt(0)
	s_barrier
	s_cmp_eq_u32 s10, 16
	s_mov_b32 s4, s10
	s_cbranch_scc0 .LBB0_1441
	s_waitcnt vmcnt(4)
	v_mul_f32_e32 v109, 0xbfb8aa3b, v158
	v_exp_f32_e32 v109, v109
	s_waitcnt vmcnt(3)
	v_mul_f32_e32 v111, 0xbfb8aa3b, v159
	v_exp_f32_e32 v111, v111
	v_mul_f32_e32 v115, 0xbfb8aa3b, v161
	v_add_f32_e32 v109, 1.0, v109
	v_rcp_f32_e32 v114, v109
	v_add_f32_e32 v109, 1.0, v111
	v_mul_f32_e32 v111, 0xbfb8aa3b, v160
	v_exp_f32_e32 v111, v111
	v_exp_f32_e32 v117, v115
	v_rcp_f32_e32 v116, v109
	s_waitcnt vmcnt(2)
	v_mov_b32_e32 v118, v158
	v_add_f32_e32 v109, 1.0, v111
	v_rcp_f32_e32 v115, v109
	v_add_f32_e32 v109, 1.0, v117
	v_rcp_f32_e32 v117, v109
	v_mov_b32_e32 v119, v160
	v_pk_mul_f32 v[114:115], v[118:119], v[114:115]
	v_mov_b32_e32 v118, v154
	v_mov_b32_e32 v119, v156
	v_mov_b32_e32 v160, v159
	v_pk_mul_f32 v[114:115], v[118:119], v[114:115]
	v_pk_mul_f32 v[116:117], v[160:161], v[116:117]
	v_mov_b32_e32 v156, v155
	v_pk_mul_f32 v[116:117], v[156:157], v[116:117]
	v_and_b32_sdwa v111, v115, v177 dst_sel:DWORD dst_unused:UNUSED_PAD src0_sel:WORD_1 src1_sel:DWORD
	v_and_b32_sdwa v118, v114, v177 dst_sel:DWORD dst_unused:UNUSED_PAD src0_sel:WORD_1 src1_sel:DWORD
	v_add3_u32 v111, v115, v111, s28
	v_and_b32_sdwa v115, v117, v177 dst_sel:DWORD dst_unused:UNUSED_PAD src0_sel:WORD_1 src1_sel:DWORD
	v_add3_u32 v114, v114, v118, s28
	v_and_b32_sdwa v118, v116, v177 dst_sel:DWORD dst_unused:UNUSED_PAD src0_sel:WORD_1 src1_sel:DWORD
	v_add3_u32 v115, v117, v115, s28
	v_or_b32_e32 v106, s7, v207
	v_add3_u32 v116, v116, v118, s28
	v_and_b32_e32 v115, 0xffff0000, v115
	v_ashrrev_i32_e32 v106, 1, v106
	v_and_b32_e32 v116, 0xffff0000, v116
	v_or_b32_sdwa v115, v115, v111 dst_sel:DWORD dst_unused:UNUSED_PAD src0_sel:DWORD src1_sel:WORD_1
	v_mul_f32_e32 v111, 0xbfb8aa3b, v150
	v_or_b32_e32 v108, v106, v208
	v_or_b32_sdwa v114, v116, v114 dst_sel:DWORD dst_unused:UNUSED_PAD src0_sel:DWORD src1_sel:WORD_1
	v_exp_f32_e32 v111, v111
	v_mul_f32_e32 v116, 0xbfb8aa3b, v151
	v_add_u32_e32 v110, s6, v205
	v_mov_b64_e32 v[106:107], s[12:13]
	v_ashrrev_i32_e32 v109, 31, v108
	v_exp_f32_e32 v116, v116
	v_mad_i64_i32 v[112:113], s[6:7], v110, s52, v[106:107]
	v_lshlrev_b64 v[108:109], 1, v[108:109]
	v_lshl_add_u64 v[112:113], v[112:113], 0, v[108:109]
	s_waitcnt vmcnt(0)
	global_store_dwordx2 v[112:113], v[114:115], off
	v_add_f32_e32 v111, 1.0, v111
	v_mul_f32_e32 v115, 0xbfb8aa3b, v152
	v_rcp_f32_e32 v114, v111
	v_add_f32_e32 v111, 1.0, v116
	v_exp_f32_e32 v115, v115
	v_mul_f32_e32 v116, 0xbfb8aa3b, v153
	v_exp_f32_e32 v117, v116
	v_rcp_f32_e32 v116, v111
	v_add_f32_e32 v111, 1.0, v115
	v_rcp_f32_e32 v115, v111
	v_add_f32_e32 v111, 1.0, v117
	v_rcp_f32_e32 v117, v111
	v_mov_b32_e32 v118, v150
	v_mov_b32_e32 v119, v152
	v_pk_mul_f32 v[114:115], v[118:119], v[114:115]
	v_mov_b32_e32 v118, v146
	v_mov_b32_e32 v119, v148
	v_mov_b32_e32 v152, v151
	v_pk_mul_f32 v[114:115], v[118:119], v[114:115]
	v_pk_mul_f32 v[116:117], v[152:153], v[116:117]
	v_mov_b32_e32 v148, v147
	v_pk_mul_f32 v[116:117], v[148:149], v[116:117]
	v_and_b32_sdwa v111, v115, v177 dst_sel:DWORD dst_unused:UNUSED_PAD src0_sel:WORD_1 src1_sel:DWORD
	v_and_b32_sdwa v118, v114, v177 dst_sel:DWORD dst_unused:UNUSED_PAD src0_sel:WORD_1 src1_sel:DWORD
	v_add3_u32 v111, v115, v111, s28
	v_and_b32_sdwa v115, v117, v177 dst_sel:DWORD dst_unused:UNUSED_PAD src0_sel:WORD_1 src1_sel:DWORD
	v_add3_u32 v114, v114, v118, s28
	v_and_b32_sdwa v118, v116, v177 dst_sel:DWORD dst_unused:UNUSED_PAD src0_sel:WORD_1 src1_sel:DWORD
	v_add3_u32 v115, v117, v115, s28
	v_add3_u32 v116, v116, v118, s28
	v_and_b32_e32 v115, 0xffff0000, v115
	v_and_b32_e32 v116, 0xffff0000, v116
	v_or_b32_sdwa v115, v115, v111 dst_sel:DWORD dst_unused:UNUSED_PAD src0_sel:DWORD src1_sel:WORD_1
	v_mul_f32_e32 v111, 0xbfb8aa3b, v142
	v_or_b32_sdwa v114, v116, v114 dst_sel:DWORD dst_unused:UNUSED_PAD src0_sel:DWORD src1_sel:WORD_1
	v_exp_f32_e32 v111, v111
	v_mul_f32_e32 v116, 0xbfb8aa3b, v143
	v_exp_f32_e32 v116, v116
	global_store_dwordx2 v[112:113], v[114:115], off offset:32
	v_add_f32_e32 v111, 1.0, v111
	v_mul_f32_e32 v115, 0xbfb8aa3b, v144
	v_rcp_f32_e32 v114, v111
	v_add_f32_e32 v111, 1.0, v116
	v_exp_f32_e32 v115, v115
	v_mul_f32_e32 v116, 0xbfb8aa3b, v145
	v_exp_f32_e32 v117, v116
	v_rcp_f32_e32 v116, v111
	v_add_f32_e32 v111, 1.0, v115
	v_rcp_f32_e32 v115, v111
	v_add_f32_e32 v111, 1.0, v117
	v_rcp_f32_e32 v117, v111
	v_mov_b32_e32 v118, v142
	v_mov_b32_e32 v119, v144
	v_pk_mul_f32 v[114:115], v[118:119], v[114:115]
	v_mov_b32_e32 v118, v138
	v_mov_b32_e32 v119, v140
	v_mov_b32_e32 v144, v143
	v_pk_mul_f32 v[114:115], v[118:119], v[114:115]
	v_pk_mul_f32 v[116:117], v[144:145], v[116:117]
	v_mov_b32_e32 v140, v139
	v_pk_mul_f32 v[116:117], v[140:141], v[116:117]
	v_and_b32_sdwa v111, v115, v177 dst_sel:DWORD dst_unused:UNUSED_PAD src0_sel:WORD_1 src1_sel:DWORD
	v_and_b32_sdwa v118, v114, v177 dst_sel:DWORD dst_unused:UNUSED_PAD src0_sel:WORD_1 src1_sel:DWORD
	v_add3_u32 v111, v115, v111, s28
	v_and_b32_sdwa v115, v117, v177 dst_sel:DWORD dst_unused:UNUSED_PAD src0_sel:WORD_1 src1_sel:DWORD
	v_add3_u32 v114, v114, v118, s28
	v_and_b32_sdwa v118, v116, v177 dst_sel:DWORD dst_unused:UNUSED_PAD src0_sel:WORD_1 src1_sel:DWORD
	v_add3_u32 v115, v117, v115, s28
	v_add3_u32 v116, v116, v118, s28
	v_and_b32_e32 v115, 0xffff0000, v115
	v_and_b32_e32 v116, 0xffff0000, v116
	v_or_b32_sdwa v115, v115, v111 dst_sel:DWORD dst_unused:UNUSED_PAD src0_sel:DWORD src1_sel:WORD_1
	v_mul_f32_e32 v111, 0xbfb8aa3b, v102
	v_or_b32_sdwa v114, v116, v114 dst_sel:DWORD dst_unused:UNUSED_PAD src0_sel:DWORD src1_sel:WORD_1
	v_exp_f32_e32 v111, v111
	v_mul_f32_e32 v116, 0xbfb8aa3b, v103
	v_exp_f32_e32 v116, v116
	global_store_dwordx2 v[112:113], v[114:115], off offset:64
	v_add_f32_e32 v111, 1.0, v111
	v_mul_f32_e32 v115, 0xbfb8aa3b, v104
	v_rcp_f32_e32 v114, v111
	v_add_f32_e32 v111, 1.0, v116
	v_exp_f32_e32 v115, v115
	v_mul_f32_e32 v116, 0xbfb8aa3b, v105
	v_exp_f32_e32 v117, v116
	v_rcp_f32_e32 v116, v111
	v_add_f32_e32 v111, 1.0, v115
	v_rcp_f32_e32 v115, v111
	v_add_f32_e32 v111, 1.0, v117
	v_rcp_f32_e32 v117, v111
	v_mov_b32_e32 v118, v102
	v_mov_b32_e32 v119, v104
	v_mov_b32_e32 v104, v103
	v_pk_mul_f32 v[114:115], v[118:119], v[114:115]
	v_mov_b32_e32 v119, v100
	v_pk_mul_f32 v[102:103], v[104:105], v[116:117]
	v_mov_b32_e32 v100, v99
	v_mov_b32_e32 v118, v98
	v_pk_mul_f32 v[98:99], v[100:101], v[102:103]
	v_pk_mul_f32 v[114:115], v[118:119], v[114:115]
	v_and_b32_sdwa v102, v99, v177 dst_sel:DWORD dst_unused:UNUSED_PAD src0_sel:WORD_1 src1_sel:DWORD
	v_and_b32_sdwa v103, v98, v177 dst_sel:DWORD dst_unused:UNUSED_PAD src0_sel:WORD_1 src1_sel:DWORD
	v_and_b32_sdwa v100, v115, v177 dst_sel:DWORD dst_unused:UNUSED_PAD src0_sel:WORD_1 src1_sel:DWORD
	v_and_b32_sdwa v101, v114, v177 dst_sel:DWORD dst_unused:UNUSED_PAD src0_sel:WORD_1 src1_sel:DWORD
	v_add3_u32 v99, v99, v102, s28
	v_add3_u32 v98, v98, v103, s28
	v_add3_u32 v101, v114, v101, s28
	v_add3_u32 v100, v115, v100, s28
	v_and_b32_e32 v99, 0xffff0000, v99
	v_and_b32_e32 v98, 0xffff0000, v98
	v_or_b32_sdwa v99, v99, v100 dst_sel:DWORD dst_unused:UNUSED_PAD src0_sel:DWORD src1_sel:WORD_1
	v_or_b32_sdwa v98, v98, v101 dst_sel:DWORD dst_unused:UNUSED_PAD src0_sel:DWORD src1_sel:WORD_1
	global_store_dwordx2 v[112:113], v[98:99], off offset:96
	v_mul_f32_e32 v99, 0xbfb8aa3b, v94
	v_exp_f32_e32 v100, v99
	v_mul_f32_e32 v99, 0xbfb8aa3b, v95
	v_mul_f32_e32 v102, 0xbfb8aa3b, v96
	v_exp_f32_e32 v101, v99
	v_exp_f32_e32 v103, v102
	v_mul_f32_e32 v102, 0xbfb8aa3b, v97
	v_exp_f32_e32 v104, v102
	v_add_f32_e32 v101, 1.0, v101
	v_add_f32_e32 v100, 1.0, v100
	v_rcp_f32_e32 v102, v101
	v_add_f32_e32 v101, 1.0, v103
	v_add_f32_e32 v103, 1.0, v104
	v_rcp_f32_e32 v100, v100
	v_rcp_f32_e32 v101, v101
	v_rcp_f32_e32 v103, v103
	v_mov_b32_e32 v104, v94
	v_mov_b32_e32 v105, v96
	v_mov_b32_e32 v96, v95
	v_pk_mul_f32 v[100:101], v[104:105], v[100:101]
	v_mov_b32_e32 v105, v92
	v_pk_mul_f32 v[94:95], v[96:97], v[102:103]
	v_mov_b32_e32 v92, v91
	v_mov_b32_e32 v104, v90
	v_pk_mul_f32 v[90:91], v[92:93], v[94:95]
	v_pk_mul_f32 v[100:101], v[104:105], v[100:101]
	v_and_b32_sdwa v94, v91, v177 dst_sel:DWORD dst_unused:UNUSED_PAD src0_sel:WORD_1 src1_sel:DWORD
	v_and_b32_sdwa v92, v101, v177 dst_sel:DWORD dst_unused:UNUSED_PAD src0_sel:WORD_1 src1_sel:DWORD
	v_and_b32_sdwa v95, v90, v177 dst_sel:DWORD dst_unused:UNUSED_PAD src0_sel:WORD_1 src1_sel:DWORD
	v_add3_u32 v91, v91, v94, s28
	v_and_b32_sdwa v93, v100, v177 dst_sel:DWORD dst_unused:UNUSED_PAD src0_sel:WORD_1 src1_sel:DWORD
	v_add3_u32 v92, v101, v92, s28
	v_add3_u32 v90, v90, v95, s28
	v_and_b32_e32 v91, 0xffff0000, v91
	v_add3_u32 v93, v100, v93, s28
	v_and_b32_e32 v90, 0xffff0000, v90
	v_or_b32_sdwa v91, v91, v92 dst_sel:DWORD dst_unused:UNUSED_PAD src0_sel:DWORD src1_sel:WORD_1
	v_mul_f32_e32 v92, 0xbfb8aa3b, v86
	v_or_b32_sdwa v90, v90, v93 dst_sel:DWORD dst_unused:UNUSED_PAD src0_sel:DWORD src1_sel:WORD_1
	v_exp_f32_e32 v92, v92
	v_mul_f32_e32 v93, 0xbfb8aa3b, v87
	v_or_b32_e32 v98, 16, v110
	v_exp_f32_e32 v93, v93
	v_mad_i64_i32 v[98:99], s[6:7], v98, s52, v[106:107]
	v_lshl_add_u64 v[98:99], v[98:99], 0, v[108:109]
	global_store_dwordx2 v[98:99], v[90:91], off
	v_add_f32_e32 v90, 1.0, v92
	v_mul_f32_e32 v92, 0xbfb8aa3b, v88
	v_add_f32_e32 v91, 1.0, v93
	v_exp_f32_e32 v93, v92
	v_mul_f32_e32 v92, 0xbfb8aa3b, v89
	v_exp_f32_e32 v94, v92
	v_rcp_f32_e32 v92, v91
	v_add_f32_e32 v91, 1.0, v93
	v_rcp_f32_e32 v90, v90
	v_add_f32_e32 v93, 1.0, v94
	v_rcp_f32_e32 v91, v91
	v_rcp_f32_e32 v93, v93
	v_mov_b32_e32 v94, v86
	v_mov_b32_e32 v95, v88
	v_mov_b32_e32 v88, v87
	v_pk_mul_f32 v[90:91], v[94:95], v[90:91]
	v_mov_b32_e32 v95, v84
	v_pk_mul_f32 v[86:87], v[88:89], v[92:93]
	v_mov_b32_e32 v84, v83
	v_mov_b32_e32 v94, v82
	v_pk_mul_f32 v[82:83], v[84:85], v[86:87]
	v_pk_mul_f32 v[90:91], v[94:95], v[90:91]
	v_and_b32_sdwa v86, v83, v177 dst_sel:DWORD dst_unused:UNUSED_PAD src0_sel:WORD_1 src1_sel:DWORD
	v_and_b32_sdwa v84, v91, v177 dst_sel:DWORD dst_unused:UNUSED_PAD src0_sel:WORD_1 src1_sel:DWORD
	v_and_b32_sdwa v87, v82, v177 dst_sel:DWORD dst_unused:UNUSED_PAD src0_sel:WORD_1 src1_sel:DWORD
	v_add3_u32 v83, v83, v86, s28
	v_and_b32_sdwa v85, v90, v177 dst_sel:DWORD dst_unused:UNUSED_PAD src0_sel:WORD_1 src1_sel:DWORD
	v_add3_u32 v84, v91, v84, s28
	v_add3_u32 v82, v82, v87, s28
	v_and_b32_e32 v83, 0xffff0000, v83
	v_add3_u32 v85, v90, v85, s28
	v_and_b32_e32 v82, 0xffff0000, v82
	v_or_b32_sdwa v83, v83, v84 dst_sel:DWORD dst_unused:UNUSED_PAD src0_sel:DWORD src1_sel:WORD_1
	v_mul_f32_e32 v84, 0xbfb8aa3b, v78
	v_or_b32_sdwa v82, v82, v85 dst_sel:DWORD dst_unused:UNUSED_PAD src0_sel:DWORD src1_sel:WORD_1
	v_exp_f32_e32 v84, v84
	v_mul_f32_e32 v85, 0xbfb8aa3b, v79
	v_exp_f32_e32 v85, v85
	global_store_dwordx2 v[98:99], v[82:83], off offset:32
	v_add_f32_e32 v82, 1.0, v84
	v_mul_f32_e32 v84, 0xbfb8aa3b, v80
	v_add_f32_e32 v83, 1.0, v85
	v_exp_f32_e32 v85, v84
	v_mul_f32_e32 v84, 0xbfb8aa3b, v81
	v_exp_f32_e32 v86, v84
	v_rcp_f32_e32 v84, v83
	v_add_f32_e32 v83, 1.0, v85
	v_rcp_f32_e32 v82, v82
	v_add_f32_e32 v85, 1.0, v86
	v_rcp_f32_e32 v83, v83
	v_rcp_f32_e32 v85, v85
	v_mov_b32_e32 v86, v78
	v_mov_b32_e32 v87, v80
	v_mov_b32_e32 v80, v79
	v_pk_mul_f32 v[82:83], v[86:87], v[82:83]
	v_mov_b32_e32 v87, v76
	v_pk_mul_f32 v[78:79], v[80:81], v[84:85]
	v_mov_b32_e32 v76, v75
	v_mov_b32_e32 v86, v74
	v_pk_mul_f32 v[74:75], v[76:77], v[78:79]
	v_pk_mul_f32 v[82:83], v[86:87], v[82:83]
	v_and_b32_sdwa v78, v75, v177 dst_sel:DWORD dst_unused:UNUSED_PAD src0_sel:WORD_1 src1_sel:DWORD
	v_and_b32_sdwa v76, v83, v177 dst_sel:DWORD dst_unused:UNUSED_PAD src0_sel:WORD_1 src1_sel:DWORD
	v_and_b32_sdwa v79, v74, v177 dst_sel:DWORD dst_unused:UNUSED_PAD src0_sel:WORD_1 src1_sel:DWORD
	v_add3_u32 v75, v75, v78, s28
	v_and_b32_sdwa v77, v82, v177 dst_sel:DWORD dst_unused:UNUSED_PAD src0_sel:WORD_1 src1_sel:DWORD
	v_add3_u32 v76, v83, v76, s28
	v_add3_u32 v74, v74, v79, s28
	v_and_b32_e32 v75, 0xffff0000, v75
	v_add3_u32 v77, v82, v77, s28
	v_and_b32_e32 v74, 0xffff0000, v74
	v_or_b32_sdwa v75, v75, v76 dst_sel:DWORD dst_unused:UNUSED_PAD src0_sel:DWORD src1_sel:WORD_1
	v_mul_f32_e32 v76, 0xbfb8aa3b, v70
	v_or_b32_sdwa v74, v74, v77 dst_sel:DWORD dst_unused:UNUSED_PAD src0_sel:DWORD src1_sel:WORD_1
	v_exp_f32_e32 v76, v76
	v_mul_f32_e32 v77, 0xbfb8aa3b, v71
	v_exp_f32_e32 v77, v77
	global_store_dwordx2 v[98:99], v[74:75], off offset:64
	v_add_f32_e32 v74, 1.0, v76
	v_mul_f32_e32 v76, 0xbfb8aa3b, v72
	v_add_f32_e32 v75, 1.0, v77
	v_exp_f32_e32 v77, v76
	v_mul_f32_e32 v76, 0xbfb8aa3b, v73
	v_exp_f32_e32 v78, v76
	v_rcp_f32_e32 v76, v75
	v_add_f32_e32 v75, 1.0, v77
	v_rcp_f32_e32 v74, v74
	v_add_f32_e32 v77, 1.0, v78
	v_rcp_f32_e32 v75, v75
	v_rcp_f32_e32 v77, v77
	v_mov_b32_e32 v78, v70
	v_mov_b32_e32 v79, v72
	v_mov_b32_e32 v72, v71
	v_pk_mul_f32 v[74:75], v[78:79], v[74:75]
	v_mov_b32_e32 v79, v68
	v_pk_mul_f32 v[70:71], v[72:73], v[76:77]
	v_mov_b32_e32 v68, v67
	v_mov_b32_e32 v78, v66
	v_pk_mul_f32 v[66:67], v[68:69], v[70:71]
	v_pk_mul_f32 v[74:75], v[78:79], v[74:75]
	v_and_b32_sdwa v70, v67, v177 dst_sel:DWORD dst_unused:UNUSED_PAD src0_sel:WORD_1 src1_sel:DWORD
	v_and_b32_sdwa v71, v66, v177 dst_sel:DWORD dst_unused:UNUSED_PAD src0_sel:WORD_1 src1_sel:DWORD
	v_and_b32_sdwa v68, v75, v177 dst_sel:DWORD dst_unused:UNUSED_PAD src0_sel:WORD_1 src1_sel:DWORD
	v_and_b32_sdwa v69, v74, v177 dst_sel:DWORD dst_unused:UNUSED_PAD src0_sel:WORD_1 src1_sel:DWORD
	v_add3_u32 v67, v67, v70, s28
	v_add3_u32 v66, v66, v71, s28
	v_add3_u32 v69, v74, v69, s28
	v_add3_u32 v68, v75, v68, s28
	v_and_b32_e32 v67, 0xffff0000, v67
	v_and_b32_e32 v66, 0xffff0000, v66
	v_or_b32_sdwa v67, v67, v68 dst_sel:DWORD dst_unused:UNUSED_PAD src0_sel:DWORD src1_sel:WORD_1
	v_or_b32_sdwa v66, v66, v69 dst_sel:DWORD dst_unused:UNUSED_PAD src0_sel:DWORD src1_sel:WORD_1
	global_store_dwordx2 v[98:99], v[66:67], off offset:96
	v_mul_f32_e32 v67, 0xbfb8aa3b, v62
	v_exp_f32_e32 v68, v67
	v_mul_f32_e32 v67, 0xbfb8aa3b, v63
	v_mul_f32_e32 v70, 0xbfb8aa3b, v64
	v_exp_f32_e32 v69, v67
	v_exp_f32_e32 v71, v70
	v_mul_f32_e32 v70, 0xbfb8aa3b, v65
	v_exp_f32_e32 v72, v70
	v_add_f32_e32 v69, 1.0, v69
	v_add_f32_e32 v68, 1.0, v68
	v_rcp_f32_e32 v70, v69
	v_add_f32_e32 v69, 1.0, v71
	v_add_f32_e32 v71, 1.0, v72
	v_rcp_f32_e32 v68, v68
	v_rcp_f32_e32 v69, v69
	v_rcp_f32_e32 v71, v71
	v_mov_b32_e32 v72, v62
	v_mov_b32_e32 v73, v64
	v_mov_b32_e32 v64, v63
	v_pk_mul_f32 v[68:69], v[72:73], v[68:69]
	v_mov_b32_e32 v73, v60
	v_pk_mul_f32 v[62:63], v[64:65], v[70:71]
	v_mov_b32_e32 v60, v59
	v_mov_b32_e32 v72, v58
	v_pk_mul_f32 v[58:59], v[60:61], v[62:63]
	v_pk_mul_f32 v[68:69], v[72:73], v[68:69]
	v_and_b32_sdwa v62, v59, v177 dst_sel:DWORD dst_unused:UNUSED_PAD src0_sel:WORD_1 src1_sel:DWORD
	v_and_b32_sdwa v60, v69, v177 dst_sel:DWORD dst_unused:UNUSED_PAD src0_sel:WORD_1 src1_sel:DWORD
	v_and_b32_sdwa v63, v58, v177 dst_sel:DWORD dst_unused:UNUSED_PAD src0_sel:WORD_1 src1_sel:DWORD
	v_add3_u32 v59, v59, v62, s28
	v_and_b32_sdwa v61, v68, v177 dst_sel:DWORD dst_unused:UNUSED_PAD src0_sel:WORD_1 src1_sel:DWORD
	v_add3_u32 v60, v69, v60, s28
	v_add3_u32 v58, v58, v63, s28
	v_and_b32_e32 v59, 0xffff0000, v59
	v_add3_u32 v61, v68, v61, s28
	v_and_b32_e32 v58, 0xffff0000, v58
	v_or_b32_sdwa v59, v59, v60 dst_sel:DWORD dst_unused:UNUSED_PAD src0_sel:DWORD src1_sel:WORD_1
	v_mul_f32_e32 v60, 0xbfb8aa3b, v54
	v_or_b32_sdwa v58, v58, v61 dst_sel:DWORD dst_unused:UNUSED_PAD src0_sel:DWORD src1_sel:WORD_1
	v_exp_f32_e32 v60, v60
	v_mul_f32_e32 v61, 0xbfb8aa3b, v55
	v_or_b32_e32 v66, 32, v110
	v_exp_f32_e32 v61, v61
	v_mad_i64_i32 v[66:67], s[6:7], v66, s52, v[106:107]
	v_lshl_add_u64 v[66:67], v[66:67], 0, v[108:109]
	global_store_dwordx2 v[66:67], v[58:59], off
	v_add_f32_e32 v58, 1.0, v60
	v_mul_f32_e32 v60, 0xbfb8aa3b, v56
	v_add_f32_e32 v59, 1.0, v61
	v_exp_f32_e32 v61, v60
	v_mul_f32_e32 v60, 0xbfb8aa3b, v57
	v_exp_f32_e32 v62, v60
	v_rcp_f32_e32 v60, v59
	v_add_f32_e32 v59, 1.0, v61
	v_rcp_f32_e32 v58, v58
	v_add_f32_e32 v61, 1.0, v62
	v_rcp_f32_e32 v59, v59
	v_rcp_f32_e32 v61, v61
	v_mov_b32_e32 v62, v54
	v_mov_b32_e32 v63, v56
	v_mov_b32_e32 v56, v55
	v_pk_mul_f32 v[58:59], v[62:63], v[58:59]
	v_mov_b32_e32 v63, v52
	v_pk_mul_f32 v[54:55], v[56:57], v[60:61]
	v_mov_b32_e32 v52, v51
	v_mov_b32_e32 v62, v50
	v_pk_mul_f32 v[50:51], v[52:53], v[54:55]
	v_pk_mul_f32 v[58:59], v[62:63], v[58:59]
	v_and_b32_sdwa v54, v51, v177 dst_sel:DWORD dst_unused:UNUSED_PAD src0_sel:WORD_1 src1_sel:DWORD
	v_and_b32_sdwa v52, v59, v177 dst_sel:DWORD dst_unused:UNUSED_PAD src0_sel:WORD_1 src1_sel:DWORD
	v_and_b32_sdwa v55, v50, v177 dst_sel:DWORD dst_unused:UNUSED_PAD src0_sel:WORD_1 src1_sel:DWORD
	v_add3_u32 v51, v51, v54, s28
	v_and_b32_sdwa v53, v58, v177 dst_sel:DWORD dst_unused:UNUSED_PAD src0_sel:WORD_1 src1_sel:DWORD
	v_add3_u32 v52, v59, v52, s28
	v_add3_u32 v50, v50, v55, s28
	v_and_b32_e32 v51, 0xffff0000, v51
	v_add3_u32 v53, v58, v53, s28
	v_and_b32_e32 v50, 0xffff0000, v50
	v_or_b32_sdwa v51, v51, v52 dst_sel:DWORD dst_unused:UNUSED_PAD src0_sel:DWORD src1_sel:WORD_1
	v_mul_f32_e32 v52, 0xbfb8aa3b, v46
	v_or_b32_sdwa v50, v50, v53 dst_sel:DWORD dst_unused:UNUSED_PAD src0_sel:DWORD src1_sel:WORD_1
	v_exp_f32_e32 v52, v52
	v_mul_f32_e32 v53, 0xbfb8aa3b, v47
	v_exp_f32_e32 v53, v53
	global_store_dwordx2 v[66:67], v[50:51], off offset:32
	v_add_f32_e32 v50, 1.0, v52
	v_mul_f32_e32 v52, 0xbfb8aa3b, v48
	v_add_f32_e32 v51, 1.0, v53
	v_exp_f32_e32 v53, v52
	v_mul_f32_e32 v52, 0xbfb8aa3b, v49
	v_exp_f32_e32 v54, v52
	v_rcp_f32_e32 v52, v51
	v_add_f32_e32 v51, 1.0, v53
	v_rcp_f32_e32 v50, v50
	v_add_f32_e32 v53, 1.0, v54
	v_rcp_f32_e32 v51, v51
	v_rcp_f32_e32 v53, v53
	v_mov_b32_e32 v54, v46
	v_mov_b32_e32 v55, v48
	v_mov_b32_e32 v48, v47
	v_pk_mul_f32 v[50:51], v[54:55], v[50:51]
	v_mov_b32_e32 v55, v44
	v_pk_mul_f32 v[46:47], v[48:49], v[52:53]
	v_mov_b32_e32 v44, v43
	v_mov_b32_e32 v54, v42
	v_pk_mul_f32 v[42:43], v[44:45], v[46:47]
	v_pk_mul_f32 v[50:51], v[54:55], v[50:51]
	v_and_b32_sdwa v46, v43, v177 dst_sel:DWORD dst_unused:UNUSED_PAD src0_sel:WORD_1 src1_sel:DWORD
	v_and_b32_sdwa v44, v51, v177 dst_sel:DWORD dst_unused:UNUSED_PAD src0_sel:WORD_1 src1_sel:DWORD
	v_and_b32_sdwa v47, v42, v177 dst_sel:DWORD dst_unused:UNUSED_PAD src0_sel:WORD_1 src1_sel:DWORD
	v_add3_u32 v43, v43, v46, s28
	v_and_b32_sdwa v45, v50, v177 dst_sel:DWORD dst_unused:UNUSED_PAD src0_sel:WORD_1 src1_sel:DWORD
	v_add3_u32 v44, v51, v44, s28
	v_add3_u32 v42, v42, v47, s28
	v_and_b32_e32 v43, 0xffff0000, v43
	v_add3_u32 v45, v50, v45, s28
	v_and_b32_e32 v42, 0xffff0000, v42
	v_or_b32_sdwa v43, v43, v44 dst_sel:DWORD dst_unused:UNUSED_PAD src0_sel:DWORD src1_sel:WORD_1
	v_mul_f32_e32 v44, 0xbfb8aa3b, v38
	v_or_b32_sdwa v42, v42, v45 dst_sel:DWORD dst_unused:UNUSED_PAD src0_sel:DWORD src1_sel:WORD_1
	v_exp_f32_e32 v44, v44
	v_mul_f32_e32 v45, 0xbfb8aa3b, v39
	v_exp_f32_e32 v45, v45
	global_store_dwordx2 v[66:67], v[42:43], off offset:64
	v_add_f32_e32 v42, 1.0, v44
	v_mul_f32_e32 v44, 0xbfb8aa3b, v40
	v_add_f32_e32 v43, 1.0, v45
	v_exp_f32_e32 v45, v44
	v_mul_f32_e32 v44, 0xbfb8aa3b, v41
	v_exp_f32_e32 v46, v44
	v_rcp_f32_e32 v44, v43
	v_add_f32_e32 v43, 1.0, v45
	v_rcp_f32_e32 v42, v42
	v_add_f32_e32 v45, 1.0, v46
	v_rcp_f32_e32 v43, v43
	v_rcp_f32_e32 v45, v45
	v_mov_b32_e32 v46, v38
	v_mov_b32_e32 v47, v40
	v_mov_b32_e32 v40, v39
	v_pk_mul_f32 v[42:43], v[46:47], v[42:43]
	v_mov_b32_e32 v47, v36
	v_pk_mul_f32 v[38:39], v[40:41], v[44:45]
	v_mov_b32_e32 v36, v35
	v_mov_b32_e32 v46, v34
	v_pk_mul_f32 v[34:35], v[36:37], v[38:39]
	v_pk_mul_f32 v[42:43], v[46:47], v[42:43]
	v_and_b32_sdwa v38, v35, v177 dst_sel:DWORD dst_unused:UNUSED_PAD src0_sel:WORD_1 src1_sel:DWORD
	v_and_b32_sdwa v39, v34, v177 dst_sel:DWORD dst_unused:UNUSED_PAD src0_sel:WORD_1 src1_sel:DWORD
	v_and_b32_sdwa v36, v43, v177 dst_sel:DWORD dst_unused:UNUSED_PAD src0_sel:WORD_1 src1_sel:DWORD
	v_and_b32_sdwa v37, v42, v177 dst_sel:DWORD dst_unused:UNUSED_PAD src0_sel:WORD_1 src1_sel:DWORD
	v_add3_u32 v35, v35, v38, s28
	v_add3_u32 v34, v34, v39, s28
	v_add3_u32 v37, v42, v37, s28
	v_add3_u32 v36, v43, v36, s28
	v_and_b32_e32 v35, 0xffff0000, v35
	v_and_b32_e32 v34, 0xffff0000, v34
	v_or_b32_sdwa v35, v35, v36 dst_sel:DWORD dst_unused:UNUSED_PAD src0_sel:DWORD src1_sel:WORD_1
	v_or_b32_sdwa v34, v34, v37 dst_sel:DWORD dst_unused:UNUSED_PAD src0_sel:DWORD src1_sel:WORD_1
	global_store_dwordx2 v[66:67], v[34:35], off offset:96
	v_mul_f32_e32 v35, 0xbfb8aa3b, v30
	v_exp_f32_e32 v36, v35
	v_mul_f32_e32 v35, 0xbfb8aa3b, v31
	v_mul_f32_e32 v38, 0xbfb8aa3b, v32
	v_exp_f32_e32 v37, v35
	v_exp_f32_e32 v39, v38
	v_mul_f32_e32 v38, 0xbfb8aa3b, v33
	v_exp_f32_e32 v40, v38
	v_add_f32_e32 v37, 1.0, v37
	v_add_f32_e32 v36, 1.0, v36
	v_rcp_f32_e32 v38, v37
	v_add_f32_e32 v37, 1.0, v39
	v_add_f32_e32 v39, 1.0, v40
	v_rcp_f32_e32 v36, v36
	v_rcp_f32_e32 v37, v37
	v_rcp_f32_e32 v39, v39
	v_mov_b32_e32 v40, v30
	v_mov_b32_e32 v41, v32
	v_mov_b32_e32 v32, v31
	v_pk_mul_f32 v[36:37], v[40:41], v[36:37]
	v_mov_b32_e32 v41, v28
	v_pk_mul_f32 v[30:31], v[32:33], v[38:39]
	v_mov_b32_e32 v28, v27
	v_mov_b32_e32 v40, v26
	v_pk_mul_f32 v[26:27], v[28:29], v[30:31]
	v_pk_mul_f32 v[36:37], v[40:41], v[36:37]
	v_and_b32_sdwa v30, v27, v177 dst_sel:DWORD dst_unused:UNUSED_PAD src0_sel:WORD_1 src1_sel:DWORD
	v_and_b32_sdwa v28, v37, v177 dst_sel:DWORD dst_unused:UNUSED_PAD src0_sel:WORD_1 src1_sel:DWORD
	v_and_b32_sdwa v31, v26, v177 dst_sel:DWORD dst_unused:UNUSED_PAD src0_sel:WORD_1 src1_sel:DWORD
	v_add3_u32 v27, v27, v30, s28
	v_and_b32_sdwa v29, v36, v177 dst_sel:DWORD dst_unused:UNUSED_PAD src0_sel:WORD_1 src1_sel:DWORD
	v_add3_u32 v28, v37, v28, s28
	v_add3_u32 v26, v26, v31, s28
	v_and_b32_e32 v27, 0xffff0000, v27
	v_add3_u32 v29, v36, v29, s28
	v_and_b32_e32 v26, 0xffff0000, v26
	v_or_b32_sdwa v27, v27, v28 dst_sel:DWORD dst_unused:UNUSED_PAD src0_sel:DWORD src1_sel:WORD_1
	v_mul_f32_e32 v28, 0xbfb8aa3b, v22
	v_or_b32_sdwa v26, v26, v29 dst_sel:DWORD dst_unused:UNUSED_PAD src0_sel:DWORD src1_sel:WORD_1
	v_exp_f32_e32 v28, v28
	v_mul_f32_e32 v29, 0xbfb8aa3b, v23
	v_or_b32_e32 v34, 48, v110
	v_exp_f32_e32 v29, v29
	v_mad_i64_i32 v[34:35], s[6:7], v34, s52, v[106:107]
	v_lshl_add_u64 v[34:35], v[34:35], 0, v[108:109]
	global_store_dwordx2 v[34:35], v[26:27], off
	v_add_f32_e32 v26, 1.0, v28
	v_mul_f32_e32 v28, 0xbfb8aa3b, v24
	v_add_f32_e32 v27, 1.0, v29
	v_exp_f32_e32 v29, v28
	v_mul_f32_e32 v28, 0xbfb8aa3b, v25
	v_exp_f32_e32 v30, v28
	v_rcp_f32_e32 v28, v27
	v_add_f32_e32 v27, 1.0, v29
	v_rcp_f32_e32 v26, v26
	v_add_f32_e32 v29, 1.0, v30
	v_rcp_f32_e32 v27, v27
	v_rcp_f32_e32 v29, v29
	v_mov_b32_e32 v30, v22
	v_mov_b32_e32 v31, v24
	v_mov_b32_e32 v24, v23
	v_pk_mul_f32 v[26:27], v[30:31], v[26:27]
	v_mov_b32_e32 v31, v20
	v_pk_mul_f32 v[22:23], v[24:25], v[28:29]
	v_mov_b32_e32 v20, v19
	v_mov_b32_e32 v30, v18
	v_pk_mul_f32 v[18:19], v[20:21], v[22:23]
	v_pk_mul_f32 v[26:27], v[30:31], v[26:27]
	v_and_b32_sdwa v22, v19, v177 dst_sel:DWORD dst_unused:UNUSED_PAD src0_sel:WORD_1 src1_sel:DWORD
	v_and_b32_sdwa v20, v27, v177 dst_sel:DWORD dst_unused:UNUSED_PAD src0_sel:WORD_1 src1_sel:DWORD
	v_and_b32_sdwa v23, v18, v177 dst_sel:DWORD dst_unused:UNUSED_PAD src0_sel:WORD_1 src1_sel:DWORD
	v_add3_u32 v19, v19, v22, s28
	v_and_b32_sdwa v21, v26, v177 dst_sel:DWORD dst_unused:UNUSED_PAD src0_sel:WORD_1 src1_sel:DWORD
	v_add3_u32 v20, v27, v20, s28
	v_add3_u32 v18, v18, v23, s28
	v_and_b32_e32 v19, 0xffff0000, v19
	v_add3_u32 v21, v26, v21, s28
	v_and_b32_e32 v18, 0xffff0000, v18
	v_or_b32_sdwa v19, v19, v20 dst_sel:DWORD dst_unused:UNUSED_PAD src0_sel:DWORD src1_sel:WORD_1
	v_mul_f32_e32 v20, 0xbfb8aa3b, v14
	v_or_b32_sdwa v18, v18, v21 dst_sel:DWORD dst_unused:UNUSED_PAD src0_sel:DWORD src1_sel:WORD_1
	v_exp_f32_e32 v20, v20
	v_mul_f32_e32 v21, 0xbfb8aa3b, v15
	v_exp_f32_e32 v21, v21
	global_store_dwordx2 v[34:35], v[18:19], off offset:32
	v_add_f32_e32 v18, 1.0, v20
	v_mul_f32_e32 v20, 0xbfb8aa3b, v16
	v_add_f32_e32 v19, 1.0, v21
	v_exp_f32_e32 v21, v20
	v_mul_f32_e32 v20, 0xbfb8aa3b, v17
	v_exp_f32_e32 v22, v20
	v_rcp_f32_e32 v20, v19
	v_add_f32_e32 v19, 1.0, v21
	v_rcp_f32_e32 v18, v18
	v_add_f32_e32 v21, 1.0, v22
	v_rcp_f32_e32 v19, v19
	v_rcp_f32_e32 v21, v21
	v_mov_b32_e32 v22, v14
	v_mov_b32_e32 v23, v16
	v_mov_b32_e32 v16, v15
	v_pk_mul_f32 v[18:19], v[22:23], v[18:19]
	v_mov_b32_e32 v23, v12
	v_pk_mul_f32 v[14:15], v[16:17], v[20:21]
	v_mov_b32_e32 v12, v11
	v_mov_b32_e32 v22, v10
	v_pk_mul_f32 v[10:11], v[12:13], v[14:15]
	v_pk_mul_f32 v[18:19], v[22:23], v[18:19]
	v_and_b32_sdwa v14, v11, v177 dst_sel:DWORD dst_unused:UNUSED_PAD src0_sel:WORD_1 src1_sel:DWORD
	v_and_b32_sdwa v12, v19, v177 dst_sel:DWORD dst_unused:UNUSED_PAD src0_sel:WORD_1 src1_sel:DWORD
	v_and_b32_sdwa v15, v10, v177 dst_sel:DWORD dst_unused:UNUSED_PAD src0_sel:WORD_1 src1_sel:DWORD
	v_add3_u32 v11, v11, v14, s28
	v_and_b32_sdwa v13, v18, v177 dst_sel:DWORD dst_unused:UNUSED_PAD src0_sel:WORD_1 src1_sel:DWORD
	v_add3_u32 v12, v19, v12, s28
	v_add3_u32 v10, v10, v15, s28
	v_and_b32_e32 v11, 0xffff0000, v11
	v_add3_u32 v13, v18, v13, s28
	v_and_b32_e32 v10, 0xffff0000, v10
	v_or_b32_sdwa v11, v11, v12 dst_sel:DWORD dst_unused:UNUSED_PAD src0_sel:DWORD src1_sel:WORD_1
	v_mul_f32_e32 v12, 0xbfb8aa3b, v6
	v_or_b32_sdwa v10, v10, v13 dst_sel:DWORD dst_unused:UNUSED_PAD src0_sel:DWORD src1_sel:WORD_1
	v_exp_f32_e32 v12, v12
	v_mul_f32_e32 v13, 0xbfb8aa3b, v7
	v_exp_f32_e32 v13, v13
	global_store_dwordx2 v[34:35], v[10:11], off offset:64
	v_add_f32_e32 v10, 1.0, v12
	v_mul_f32_e32 v12, 0xbfb8aa3b, v8
	v_add_f32_e32 v11, 1.0, v13
	v_exp_f32_e32 v13, v12
	v_mul_f32_e32 v12, 0xbfb8aa3b, v9
	v_exp_f32_e32 v14, v12
	v_rcp_f32_e32 v12, v11
	v_add_f32_e32 v11, 1.0, v13
	v_rcp_f32_e32 v10, v10
	v_add_f32_e32 v13, 1.0, v14
	v_rcp_f32_e32 v11, v11
	v_rcp_f32_e32 v13, v13
	v_mov_b32_e32 v14, v6
	v_mov_b32_e32 v15, v8
	v_mov_b32_e32 v8, v7
	v_pk_mul_f32 v[10:11], v[14:15], v[10:11]
	v_mov_b32_e32 v15, v4
	v_pk_mul_f32 v[6:7], v[8:9], v[12:13]
	v_mov_b32_e32 v4, v3
	v_mov_b32_e32 v14, v2
	v_pk_mul_f32 v[2:3], v[4:5], v[6:7]
	v_pk_mul_f32 v[10:11], v[14:15], v[10:11]
	v_and_b32_sdwa v6, v3, v177 dst_sel:DWORD dst_unused:UNUSED_PAD src0_sel:WORD_1 src1_sel:DWORD
	v_and_b32_sdwa v7, v2, v177 dst_sel:DWORD dst_unused:UNUSED_PAD src0_sel:WORD_1 src1_sel:DWORD
	v_and_b32_sdwa v4, v11, v177 dst_sel:DWORD dst_unused:UNUSED_PAD src0_sel:WORD_1 src1_sel:DWORD
	v_and_b32_sdwa v5, v10, v177 dst_sel:DWORD dst_unused:UNUSED_PAD src0_sel:WORD_1 src1_sel:DWORD
	v_add3_u32 v3, v3, v6, s28
	v_add3_u32 v2, v2, v7, s28
	v_add3_u32 v5, v10, v5, s28
	v_add3_u32 v4, v11, v4, s28
	v_and_b32_e32 v3, 0xffff0000, v3
	v_and_b32_e32 v2, 0xffff0000, v2
	s_add_i32 s14, s14, s11
	v_or_b32_sdwa v3, v3, v4 dst_sel:DWORD dst_unused:UNUSED_PAD src0_sel:DWORD src1_sel:WORD_1
	v_or_b32_sdwa v2, v2, v5 dst_sel:DWORD dst_unused:UNUSED_PAD src0_sel:DWORD src1_sel:WORD_1
	s_cmpk_gt_i32 s14, 0x4ff
	global_store_dwordx2 v[34:35], v[2:3], off offset:96
	s_cbranch_scc0 .LBB0_1440

.LBB0_1462:
	s_bitcmp1_b32 s4, 0
	s_cselect_b32 s2, 0x12000, 0
	v_or_b32_e32 v218, s2, v206
	v_add_u32_e32 v214, v218, v0
	v_add_u32_e32 v246, v218, v167
	ds_read_b128 v[184:187], v214
	ds_read_b128 v[218:221], v246 offset:32768
	ds_read_b128 v[198:201], v214 offset:2048
	ds_read_b128 v[210:213], v214 offset:4096
	ds_read_b128 v[214:217], v214 offset:6144
	ds_read_b128 v[222:225], v246 offset:34816
	ds_read_b128 v[226:229], v246 offset:36864
	ds_read_b128 v[230:233], v246 offset:38912
	ds_read_b128 v[234:237], v246 offset:40960
	ds_read_b128 v[238:241], v246 offset:43008
	ds_read_b128 v[242:245], v246 offset:45056
	ds_read_b128 v[246:249], v246 offset:47104
	s_add_i32 s10, s4, 1
	s_bitcmp1_b32 s10, 0
	s_cselect_b32 s3, 0x12000, 0
	v_add_u32_e32 v171, s3, v166
	v_xor_b32_e32 v169, 64, v206
	v_add3_u32 v169, s2, v167, v169
	s_waitcnt lgkmcnt(10)
	v_mfma_f32_16x16x32_bf16 v[158:161], v[218:221], v[184:187], v[158:161]
	s_waitcnt lgkmcnt(9)
	v_mfma_f32_16x16x32_bf16 v[94:97], v[218:221], v[198:201], v[94:97]
	s_waitcnt lgkmcnt(8)
	v_mfma_f32_16x16x32_bf16 v[62:65], v[218:221], v[210:213], v[62:65]
	s_waitcnt lgkmcnt(7)
	v_mfma_f32_16x16x32_bf16 v[30:33], v[218:221], v[214:217], v[30:33]
	ds_read_b128 v[218:221], v169 offset:32768
	s_waitcnt lgkmcnt(7)
	v_mfma_f32_16x16x32_bf16 v[154:157], v[222:225], v[184:187], v[154:157]
	v_mfma_f32_16x16x32_bf16 v[90:93], v[222:225], v[198:201], v[90:93]
	v_mfma_f32_16x16x32_bf16 v[58:61], v[222:225], v[210:213], v[58:61]
	v_mfma_f32_16x16x32_bf16 v[26:29], v[222:225], v[214:217], v[26:29]
	ds_read_b128 v[222:225], v169 offset:34816
	s_waitcnt lgkmcnt(7)
	v_mfma_f32_16x16x32_bf16 v[150:153], v[226:229], v[184:187], v[150:153]
	v_mfma_f32_16x16x32_bf16 v[86:89], v[226:229], v[198:201], v[86:89]
	v_mfma_f32_16x16x32_bf16 v[54:57], v[226:229], v[210:213], v[54:57]
	v_mfma_f32_16x16x32_bf16 v[22:25], v[226:229], v[214:217], v[22:25]
	ds_read_b128 v[226:229], v169 offset:36864
	s_waitcnt lgkmcnt(7)
	v_mfma_f32_16x16x32_bf16 v[146:149], v[230:233], v[184:187], v[146:149]
	v_mfma_f32_16x16x32_bf16 v[82:85], v[230:233], v[198:201], v[82:85]
	v_mfma_f32_16x16x32_bf16 v[50:53], v[230:233], v[210:213], v[50:53]
	v_mfma_f32_16x16x32_bf16 v[18:21], v[230:233], v[214:217], v[18:21]
	ds_read_b128 v[230:233], v169 offset:38912
	s_waitcnt lgkmcnt(7)
	v_mfma_f32_16x16x32_bf16 v[142:145], v[234:237], v[184:187], v[142:145]
	v_mfma_f32_16x16x32_bf16 v[78:81], v[234:237], v[198:201], v[78:81]
	v_mfma_f32_16x16x32_bf16 v[46:49], v[234:237], v[210:213], v[46:49]
	v_mfma_f32_16x16x32_bf16 v[14:17], v[234:237], v[214:217], v[14:17]
	ds_read_b128 v[234:237], v169 offset:40960
	s_waitcnt lgkmcnt(7)
	v_mfma_f32_16x16x32_bf16 v[138:141], v[238:241], v[184:187], v[138:141]
	v_mfma_f32_16x16x32_bf16 v[74:77], v[238:241], v[198:201], v[74:77]
	v_mfma_f32_16x16x32_bf16 v[42:45], v[238:241], v[210:213], v[42:45]
	v_mfma_f32_16x16x32_bf16 v[10:13], v[238:241], v[214:217], v[10:13]
	ds_read_b128 v[238:241], v169 offset:43008
	s_waitcnt lgkmcnt(7)
	v_mfma_f32_16x16x32_bf16 v[102:105], v[242:245], v[184:187], v[102:105]
	v_mfma_f32_16x16x32_bf16 v[70:73], v[242:245], v[198:201], v[70:73]
	v_mfma_f32_16x16x32_bf16 v[38:41], v[242:245], v[210:213], v[38:41]
	v_mfma_f32_16x16x32_bf16 v[6:9], v[242:245], v[214:217], v[6:9]
	ds_read_b128 v[242:245], v169 offset:45056
	s_waitcnt lgkmcnt(7)
	v_mfma_f32_16x16x32_bf16 v[98:101], v[246:249], v[184:187], v[98:101]
	v_mfma_f32_16x16x32_bf16 v[66:69], v[246:249], v[198:201], v[66:69]
	v_xor_b32_e32 v169, 64, v206
	v_add3_u32 v169, s2, v0, v169
	ds_read_b128 v[184:187], v169
	ds_read_b128 v[198:201], v169 offset:2048
	v_mfma_f32_16x16x32_bf16 v[34:37], v[246:249], v[210:213], v[34:37]
	ds_read_b128 v[210:213], v169 offset:4096
	v_mfma_f32_16x16x32_bf16 v[2:5], v[246:249], v[214:217], v[2:5]
	ds_read_b128 v[214:217], v169 offset:6144
	v_xor_b32_e32 v169, 64, v206
	v_add3_u32 v169, s2, v167, v169
	ds_read_b128 v[246:249], v169 offset:47104
	s_waitcnt lgkmcnt(4)
	v_mfma_f32_16x16x32_bf16 v[158:161], v[218:221], v[184:187], v[158:161]
	s_waitcnt lgkmcnt(3)
	v_mfma_f32_16x16x32_bf16 v[94:97], v[218:221], v[198:201], v[94:97]
	s_waitcnt lgkmcnt(2)
	v_mfma_f32_16x16x32_bf16 v[62:65], v[218:221], v[210:213], v[62:65]
	s_waitcnt lgkmcnt(1)
	v_mfma_f32_16x16x32_bf16 v[30:33], v[218:221], v[214:217], v[30:33]
	s_waitcnt vmcnt(7)
	ds_write_b128 v171, v[114:117]
	v_mfma_f32_16x16x32_bf16 v[154:157], v[222:225], v[184:187], v[154:157]
	v_mfma_f32_16x16x32_bf16 v[90:93], v[222:225], v[198:201], v[90:93]
	global_load_dwordx4 v[114:117], v168, vcc offset:256
	v_mfma_f32_16x16x32_bf16 v[58:61], v[222:225], v[210:213], v[58:61]
	v_mfma_f32_16x16x32_bf16 v[26:29], v[222:225], v[214:217], v[26:29]
	s_waitcnt vmcnt(7)
	ds_write_b128 v171, v[106:109] offset:8192
	v_mfma_f32_16x16x32_bf16 v[150:153], v[226:229], v[184:187], v[150:153]
	v_mfma_f32_16x16x32_bf16 v[86:89], v[226:229], v[198:201], v[86:89]
	v_add_u32_e32 v106, s34, v168
	global_load_dwordx4 v[106:109], v106, vcc offset:256
	v_mfma_f32_16x16x32_bf16 v[54:57], v[226:229], v[210:213], v[54:57]
	v_mfma_f32_16x16x32_bf16 v[22:25], v[226:229], v[214:217], v[22:25]
	s_waitcnt vmcnt(7)
	ds_write_b128 v171, v[110:113] offset:16384
	v_mfma_f32_16x16x32_bf16 v[146:149], v[230:233], v[184:187], v[146:149]
	v_mfma_f32_16x16x32_bf16 v[82:85], v[230:233], v[198:201], v[82:85]
	v_add_u32_e32 v110, s35, v168
	global_load_dwordx4 v[110:113], v110, vcc offset:256
	v_mfma_f32_16x16x32_bf16 v[50:53], v[230:233], v[210:213], v[50:53]
	v_mfma_f32_16x16x32_bf16 v[18:21], v[230:233], v[214:217], v[18:21]
	s_waitcnt vmcnt(7)
	ds_write_b128 v171, v[126:129] offset:24576
	v_mfma_f32_16x16x32_bf16 v[142:145], v[234:237], v[184:187], v[142:145]
	v_mfma_f32_16x16x32_bf16 v[78:81], v[234:237], v[198:201], v[78:81]
	v_add_u32_e32 v126, s36, v168
	global_load_dwordx4 v[126:129], v126, vcc offset:256
	v_mfma_f32_16x16x32_bf16 v[46:49], v[234:237], v[210:213], v[46:49]
	v_mfma_f32_16x16x32_bf16 v[14:17], v[234:237], v[214:217], v[14:17]
	s_waitcnt vmcnt(7)
	ds_write_b128 v171, v[122:125] offset:32768
	v_mfma_f32_16x16x32_bf16 v[138:141], v[238:241], v[184:187], v[138:141]
	v_mfma_f32_16x16x32_bf16 v[74:77], v[238:241], v[198:201], v[74:77]
	global_load_dwordx4 v[122:125], v170, s[100:101] offset:256
	v_mfma_f32_16x16x32_bf16 v[42:45], v[238:241], v[210:213], v[42:45]
	v_mfma_f32_16x16x32_bf16 v[10:13], v[238:241], v[214:217], v[10:13]
	s_waitcnt vmcnt(7)
	ds_write_b128 v171, v[118:121] offset:40960
	v_mfma_f32_16x16x32_bf16 v[102:105], v[242:245], v[184:187], v[102:105]
	v_mfma_f32_16x16x32_bf16 v[70:73], v[242:245], v[198:201], v[70:73]
	v_add_u32_e32 v118, s34, v170
	global_load_dwordx4 v[118:121], v118, s[100:101] offset:256
	v_mfma_f32_16x16x32_bf16 v[38:41], v[242:245], v[210:213], v[38:41]
	v_mfma_f32_16x16x32_bf16 v[6:9], v[242:245], v[214:217], v[6:9]
	s_waitcnt vmcnt(7)
	ds_write_b128 v171, v[134:137] offset:49152
	s_waitcnt lgkmcnt(7)
	v_mfma_f32_16x16x32_bf16 v[98:101], v[246:249], v[184:187], v[98:101]
	v_mfma_f32_16x16x32_bf16 v[66:69], v[246:249], v[198:201], v[66:69]
	v_add_u32_e32 v134, s35, v170
	global_load_dwordx4 v[134:137], v134, s[100:101] offset:256
	v_mfma_f32_16x16x32_bf16 v[34:37], v[246:249], v[210:213], v[34:37]
	v_mfma_f32_16x16x32_bf16 v[2:5], v[246:249], v[214:217], v[2:5]
	s_waitcnt vmcnt(7)
	ds_write_b128 v171, v[130:133] offset:57344
	v_add_u32_e32 v130, s36, v170
	global_load_dwordx4 v[130:133], v130, s[100:101] offset:256
	v_add_u32_e32 v168, 0x80, v168
	v_add_u32_e32 v170, 0x80, v170
	s_waitcnt lgkmcnt(0)
	s_barrier
	s_cmp_eq_u32 s10, 16
	s_mov_b32 s4, s10
	s_cbranch_scc0 .LBB0_1462
	s_waitcnt vmcnt(4)
	v_mul_f32_e32 v109, 0xbfb8aa3b, v158
	v_exp_f32_e32 v109, v109
	s_waitcnt vmcnt(3)
	v_mul_f32_e32 v111, 0xbfb8aa3b, v159
	v_exp_f32_e32 v111, v111
	v_mul_f32_e32 v115, 0xbfb8aa3b, v161
	v_add_f32_e32 v109, 1.0, v109
	v_rcp_f32_e32 v114, v109
	v_add_f32_e32 v109, 1.0, v111
	v_mul_f32_e32 v111, 0xbfb8aa3b, v160
	v_exp_f32_e32 v111, v111
	v_exp_f32_e32 v117, v115
	v_rcp_f32_e32 v116, v109
	s_waitcnt vmcnt(2)
	v_mov_b32_e32 v118, v158
	v_add_f32_e32 v109, 1.0, v111
	v_rcp_f32_e32 v115, v109
	v_add_f32_e32 v109, 1.0, v117
	v_rcp_f32_e32 v117, v109
	v_mov_b32_e32 v119, v160
	v_pk_mul_f32 v[114:115], v[118:119], v[114:115]
	v_mov_b32_e32 v118, v154
	v_mov_b32_e32 v119, v156
	v_mov_b32_e32 v160, v159
	v_pk_mul_f32 v[114:115], v[118:119], v[114:115]
	v_pk_mul_f32 v[116:117], v[160:161], v[116:117]
	v_mov_b32_e32 v156, v155
	v_pk_mul_f32 v[116:117], v[156:157], v[116:117]
	v_and_b32_sdwa v111, v115, v177 dst_sel:DWORD dst_unused:UNUSED_PAD src0_sel:WORD_1 src1_sel:DWORD
	v_and_b32_sdwa v118, v114, v177 dst_sel:DWORD dst_unused:UNUSED_PAD src0_sel:WORD_1 src1_sel:DWORD
	v_add3_u32 v111, v115, v111, s28
	v_and_b32_sdwa v115, v117, v177 dst_sel:DWORD dst_unused:UNUSED_PAD src0_sel:WORD_1 src1_sel:DWORD
	v_add3_u32 v114, v114, v118, s28
	v_and_b32_sdwa v118, v116, v177 dst_sel:DWORD dst_unused:UNUSED_PAD src0_sel:WORD_1 src1_sel:DWORD
	v_add3_u32 v115, v117, v115, s28
	v_or_b32_e32 v106, s7, v207
	v_add3_u32 v116, v116, v118, s28
	v_and_b32_e32 v115, 0xffff0000, v115
	v_ashrrev_i32_e32 v106, 1, v106
	v_and_b32_e32 v116, 0xffff0000, v116
	v_or_b32_sdwa v115, v115, v111 dst_sel:DWORD dst_unused:UNUSED_PAD src0_sel:DWORD src1_sel:WORD_1
	v_mul_f32_e32 v111, 0xbfb8aa3b, v150
	v_or_b32_e32 v108, v106, v208
	v_or_b32_sdwa v114, v116, v114 dst_sel:DWORD dst_unused:UNUSED_PAD src0_sel:DWORD src1_sel:WORD_1
	v_exp_f32_e32 v111, v111
	v_mul_f32_e32 v116, 0xbfb8aa3b, v151
	v_add_u32_e32 v110, s6, v205
	v_mov_b64_e32 v[106:107], s[12:13]
	v_ashrrev_i32_e32 v109, 31, v108
	v_exp_f32_e32 v116, v116
	v_mad_i64_i32 v[112:113], s[6:7], v110, s52, v[106:107]
	v_lshlrev_b64 v[108:109], 1, v[108:109]
	v_lshl_add_u64 v[112:113], v[112:113], 0, v[108:109]
	s_waitcnt vmcnt(0)
	global_store_dwordx2 v[112:113], v[114:115], off
	v_add_f32_e32 v111, 1.0, v111
	v_mul_f32_e32 v115, 0xbfb8aa3b, v152
	v_rcp_f32_e32 v114, v111
	v_add_f32_e32 v111, 1.0, v116
	v_exp_f32_e32 v115, v115
	v_mul_f32_e32 v116, 0xbfb8aa3b, v153
	v_exp_f32_e32 v117, v116
	v_rcp_f32_e32 v116, v111
	v_add_f32_e32 v111, 1.0, v115
	v_rcp_f32_e32 v115, v111
	v_add_f32_e32 v111, 1.0, v117
	v_rcp_f32_e32 v117, v111
	v_mov_b32_e32 v118, v150
	v_mov_b32_e32 v119, v152
	v_pk_mul_f32 v[114:115], v[118:119], v[114:115]
	v_mov_b32_e32 v118, v146
	v_mov_b32_e32 v119, v148
	v_mov_b32_e32 v152, v151
	v_pk_mul_f32 v[114:115], v[118:119], v[114:115]
	v_pk_mul_f32 v[116:117], v[152:153], v[116:117]
	v_mov_b32_e32 v148, v147
	v_pk_mul_f32 v[116:117], v[148:149], v[116:117]
	v_and_b32_sdwa v111, v115, v177 dst_sel:DWORD dst_unused:UNUSED_PAD src0_sel:WORD_1 src1_sel:DWORD
	v_and_b32_sdwa v118, v114, v177 dst_sel:DWORD dst_unused:UNUSED_PAD src0_sel:WORD_1 src1_sel:DWORD
	v_add3_u32 v111, v115, v111, s28
	v_and_b32_sdwa v115, v117, v177 dst_sel:DWORD dst_unused:UNUSED_PAD src0_sel:WORD_1 src1_sel:DWORD
	v_add3_u32 v114, v114, v118, s28
	v_and_b32_sdwa v118, v116, v177 dst_sel:DWORD dst_unused:UNUSED_PAD src0_sel:WORD_1 src1_sel:DWORD
	v_add3_u32 v115, v117, v115, s28
	v_add3_u32 v116, v116, v118, s28
	v_and_b32_e32 v115, 0xffff0000, v115
	v_and_b32_e32 v116, 0xffff0000, v116
	v_or_b32_sdwa v115, v115, v111 dst_sel:DWORD dst_unused:UNUSED_PAD src0_sel:DWORD src1_sel:WORD_1
	v_mul_f32_e32 v111, 0xbfb8aa3b, v142
	v_or_b32_sdwa v114, v116, v114 dst_sel:DWORD dst_unused:UNUSED_PAD src0_sel:DWORD src1_sel:WORD_1
	v_exp_f32_e32 v111, v111
	v_mul_f32_e32 v116, 0xbfb8aa3b, v143
	v_exp_f32_e32 v116, v116
	global_store_dwordx2 v[112:113], v[114:115], off offset:32
	v_add_f32_e32 v111, 1.0, v111
	v_mul_f32_e32 v115, 0xbfb8aa3b, v144
	v_rcp_f32_e32 v114, v111
	v_add_f32_e32 v111, 1.0, v116
	v_exp_f32_e32 v115, v115
	v_mul_f32_e32 v116, 0xbfb8aa3b, v145
	v_exp_f32_e32 v117, v116
	v_rcp_f32_e32 v116, v111
	v_add_f32_e32 v111, 1.0, v115
	v_rcp_f32_e32 v115, v111
	v_add_f32_e32 v111, 1.0, v117
	v_rcp_f32_e32 v117, v111
	v_mov_b32_e32 v118, v142
	v_mov_b32_e32 v119, v144
	v_pk_mul_f32 v[114:115], v[118:119], v[114:115]
	v_mov_b32_e32 v118, v138
	v_mov_b32_e32 v119, v140
	v_mov_b32_e32 v144, v143
	v_pk_mul_f32 v[114:115], v[118:119], v[114:115]
	v_pk_mul_f32 v[116:117], v[144:145], v[116:117]
	v_mov_b32_e32 v140, v139
	v_pk_mul_f32 v[116:117], v[140:141], v[116:117]
	v_and_b32_sdwa v111, v115, v177 dst_sel:DWORD dst_unused:UNUSED_PAD src0_sel:WORD_1 src1_sel:DWORD
	v_and_b32_sdwa v118, v114, v177 dst_sel:DWORD dst_unused:UNUSED_PAD src0_sel:WORD_1 src1_sel:DWORD
	v_add3_u32 v111, v115, v111, s28
	v_and_b32_sdwa v115, v117, v177 dst_sel:DWORD dst_unused:UNUSED_PAD src0_sel:WORD_1 src1_sel:DWORD
	v_add3_u32 v114, v114, v118, s28
	v_and_b32_sdwa v118, v116, v177 dst_sel:DWORD dst_unused:UNUSED_PAD src0_sel:WORD_1 src1_sel:DWORD
	v_add3_u32 v115, v117, v115, s28
	v_add3_u32 v116, v116, v118, s28
	v_and_b32_e32 v115, 0xffff0000, v115
	v_and_b32_e32 v116, 0xffff0000, v116
	v_or_b32_sdwa v115, v115, v111 dst_sel:DWORD dst_unused:UNUSED_PAD src0_sel:DWORD src1_sel:WORD_1
	v_mul_f32_e32 v111, 0xbfb8aa3b, v102
	v_or_b32_sdwa v114, v116, v114 dst_sel:DWORD dst_unused:UNUSED_PAD src0_sel:DWORD src1_sel:WORD_1
	v_exp_f32_e32 v111, v111
	v_mul_f32_e32 v116, 0xbfb8aa3b, v103
	v_exp_f32_e32 v116, v116
	global_store_dwordx2 v[112:113], v[114:115], off offset:64
	v_add_f32_e32 v111, 1.0, v111
	v_mul_f32_e32 v115, 0xbfb8aa3b, v104
	v_rcp_f32_e32 v114, v111
	v_add_f32_e32 v111, 1.0, v116
	v_exp_f32_e32 v115, v115
	v_mul_f32_e32 v116, 0xbfb8aa3b, v105
	v_exp_f32_e32 v117, v116
	v_rcp_f32_e32 v116, v111
	v_add_f32_e32 v111, 1.0, v115
	v_rcp_f32_e32 v115, v111
	v_add_f32_e32 v111, 1.0, v117
	v_rcp_f32_e32 v117, v111
	v_mov_b32_e32 v118, v102
	v_mov_b32_e32 v119, v104
	v_mov_b32_e32 v104, v103
	v_pk_mul_f32 v[114:115], v[118:119], v[114:115]
	v_mov_b32_e32 v119, v100
	v_pk_mul_f32 v[102:103], v[104:105], v[116:117]
	v_mov_b32_e32 v100, v99
	v_mov_b32_e32 v118, v98
	v_pk_mul_f32 v[98:99], v[100:101], v[102:103]
	v_pk_mul_f32 v[114:115], v[118:119], v[114:115]
	v_and_b32_sdwa v102, v99, v177 dst_sel:DWORD dst_unused:UNUSED_PAD src0_sel:WORD_1 src1_sel:DWORD
	v_and_b32_sdwa v103, v98, v177 dst_sel:DWORD dst_unused:UNUSED_PAD src0_sel:WORD_1 src1_sel:DWORD
	v_and_b32_sdwa v100, v115, v177 dst_sel:DWORD dst_unused:UNUSED_PAD src0_sel:WORD_1 src1_sel:DWORD
	v_and_b32_sdwa v101, v114, v177 dst_sel:DWORD dst_unused:UNUSED_PAD src0_sel:WORD_1 src1_sel:DWORD
	v_add3_u32 v99, v99, v102, s28
	v_add3_u32 v98, v98, v103, s28
	v_add3_u32 v101, v114, v101, s28
	v_add3_u32 v100, v115, v100, s28
	v_and_b32_e32 v99, 0xffff0000, v99
	v_and_b32_e32 v98, 0xffff0000, v98
	v_or_b32_sdwa v99, v99, v100 dst_sel:DWORD dst_unused:UNUSED_PAD src0_sel:DWORD src1_sel:WORD_1
	v_or_b32_sdwa v98, v98, v101 dst_sel:DWORD dst_unused:UNUSED_PAD src0_sel:DWORD src1_sel:WORD_1
	global_store_dwordx2 v[112:113], v[98:99], off offset:96
	v_mul_f32_e32 v99, 0xbfb8aa3b, v94
	v_exp_f32_e32 v100, v99
	v_mul_f32_e32 v99, 0xbfb8aa3b, v95
	v_mul_f32_e32 v102, 0xbfb8aa3b, v96
	v_exp_f32_e32 v101, v99
	v_exp_f32_e32 v103, v102
	v_mul_f32_e32 v102, 0xbfb8aa3b, v97
	v_exp_f32_e32 v104, v102
	v_add_f32_e32 v101, 1.0, v101
	v_add_f32_e32 v100, 1.0, v100
	v_rcp_f32_e32 v102, v101
	v_add_f32_e32 v101, 1.0, v103
	v_add_f32_e32 v103, 1.0, v104
	v_rcp_f32_e32 v100, v100
	v_rcp_f32_e32 v101, v101
	v_rcp_f32_e32 v103, v103
	v_mov_b32_e32 v104, v94
	v_mov_b32_e32 v105, v96
	v_mov_b32_e32 v96, v95
	v_pk_mul_f32 v[100:101], v[104:105], v[100:101]
	v_mov_b32_e32 v105, v92
	v_pk_mul_f32 v[94:95], v[96:97], v[102:103]
	v_mov_b32_e32 v92, v91
	v_mov_b32_e32 v104, v90
	v_pk_mul_f32 v[90:91], v[92:93], v[94:95]
	v_pk_mul_f32 v[100:101], v[104:105], v[100:101]
	v_and_b32_sdwa v94, v91, v177 dst_sel:DWORD dst_unused:UNUSED_PAD src0_sel:WORD_1 src1_sel:DWORD
	v_and_b32_sdwa v92, v101, v177 dst_sel:DWORD dst_unused:UNUSED_PAD src0_sel:WORD_1 src1_sel:DWORD
	v_and_b32_sdwa v95, v90, v177 dst_sel:DWORD dst_unused:UNUSED_PAD src0_sel:WORD_1 src1_sel:DWORD
	v_add3_u32 v91, v91, v94, s28
	v_and_b32_sdwa v93, v100, v177 dst_sel:DWORD dst_unused:UNUSED_PAD src0_sel:WORD_1 src1_sel:DWORD
	v_add3_u32 v92, v101, v92, s28
	v_add3_u32 v90, v90, v95, s28
	v_and_b32_e32 v91, 0xffff0000, v91
	v_add3_u32 v93, v100, v93, s28
	v_and_b32_e32 v90, 0xffff0000, v90
	v_or_b32_sdwa v91, v91, v92 dst_sel:DWORD dst_unused:UNUSED_PAD src0_sel:DWORD src1_sel:WORD_1
	v_mul_f32_e32 v92, 0xbfb8aa3b, v86
	v_or_b32_sdwa v90, v90, v93 dst_sel:DWORD dst_unused:UNUSED_PAD src0_sel:DWORD src1_sel:WORD_1
	v_exp_f32_e32 v92, v92
	v_mul_f32_e32 v93, 0xbfb8aa3b, v87
	v_or_b32_e32 v98, 16, v110
	v_exp_f32_e32 v93, v93
	v_mad_i64_i32 v[98:99], s[6:7], v98, s52, v[106:107]
	v_lshl_add_u64 v[98:99], v[98:99], 0, v[108:109]
	global_store_dwordx2 v[98:99], v[90:91], off
	v_add_f32_e32 v90, 1.0, v92
	v_mul_f32_e32 v92, 0xbfb8aa3b, v88
	v_add_f32_e32 v91, 1.0, v93
	v_exp_f32_e32 v93, v92
	v_mul_f32_e32 v92, 0xbfb8aa3b, v89
	v_exp_f32_e32 v94, v92
	v_rcp_f32_e32 v92, v91
	v_add_f32_e32 v91, 1.0, v93
	v_rcp_f32_e32 v90, v90
	v_add_f32_e32 v93, 1.0, v94
	v_rcp_f32_e32 v91, v91
	v_rcp_f32_e32 v93, v93
	v_mov_b32_e32 v94, v86
	v_mov_b32_e32 v95, v88
	v_mov_b32_e32 v88, v87
	v_pk_mul_f32 v[90:91], v[94:95], v[90:91]
	v_mov_b32_e32 v95, v84
	v_pk_mul_f32 v[86:87], v[88:89], v[92:93]
	v_mov_b32_e32 v84, v83
	v_mov_b32_e32 v94, v82
	v_pk_mul_f32 v[82:83], v[84:85], v[86:87]
	v_pk_mul_f32 v[90:91], v[94:95], v[90:91]
	v_and_b32_sdwa v86, v83, v177 dst_sel:DWORD dst_unused:UNUSED_PAD src0_sel:WORD_1 src1_sel:DWORD
	v_and_b32_sdwa v84, v91, v177 dst_sel:DWORD dst_unused:UNUSED_PAD src0_sel:WORD_1 src1_sel:DWORD
	v_and_b32_sdwa v87, v82, v177 dst_sel:DWORD dst_unused:UNUSED_PAD src0_sel:WORD_1 src1_sel:DWORD
	v_add3_u32 v83, v83, v86, s28
	v_and_b32_sdwa v85, v90, v177 dst_sel:DWORD dst_unused:UNUSED_PAD src0_sel:WORD_1 src1_sel:DWORD
	v_add3_u32 v84, v91, v84, s28
	v_add3_u32 v82, v82, v87, s28
	v_and_b32_e32 v83, 0xffff0000, v83
	v_add3_u32 v85, v90, v85, s28
	v_and_b32_e32 v82, 0xffff0000, v82
	v_or_b32_sdwa v83, v83, v84 dst_sel:DWORD dst_unused:UNUSED_PAD src0_sel:DWORD src1_sel:WORD_1
	v_mul_f32_e32 v84, 0xbfb8aa3b, v78
	v_or_b32_sdwa v82, v82, v85 dst_sel:DWORD dst_unused:UNUSED_PAD src0_sel:DWORD src1_sel:WORD_1
	v_exp_f32_e32 v84, v84
	v_mul_f32_e32 v85, 0xbfb8aa3b, v79
	v_exp_f32_e32 v85, v85
	global_store_dwordx2 v[98:99], v[82:83], off offset:32
	v_add_f32_e32 v82, 1.0, v84
	v_mul_f32_e32 v84, 0xbfb8aa3b, v80
	v_add_f32_e32 v83, 1.0, v85
	v_exp_f32_e32 v85, v84
	v_mul_f32_e32 v84, 0xbfb8aa3b, v81
	v_exp_f32_e32 v86, v84
	v_rcp_f32_e32 v84, v83
	v_add_f32_e32 v83, 1.0, v85
	v_rcp_f32_e32 v82, v82
	v_add_f32_e32 v85, 1.0, v86
	v_rcp_f32_e32 v83, v83
	v_rcp_f32_e32 v85, v85
	v_mov_b32_e32 v86, v78
	v_mov_b32_e32 v87, v80
	v_mov_b32_e32 v80, v79
	v_pk_mul_f32 v[82:83], v[86:87], v[82:83]
	v_mov_b32_e32 v87, v76
	v_pk_mul_f32 v[78:79], v[80:81], v[84:85]
	v_mov_b32_e32 v76, v75
	v_mov_b32_e32 v86, v74
	v_pk_mul_f32 v[74:75], v[76:77], v[78:79]
	v_pk_mul_f32 v[82:83], v[86:87], v[82:83]
	v_and_b32_sdwa v78, v75, v177 dst_sel:DWORD dst_unused:UNUSED_PAD src0_sel:WORD_1 src1_sel:DWORD
	v_and_b32_sdwa v76, v83, v177 dst_sel:DWORD dst_unused:UNUSED_PAD src0_sel:WORD_1 src1_sel:DWORD
	v_and_b32_sdwa v79, v74, v177 dst_sel:DWORD dst_unused:UNUSED_PAD src0_sel:WORD_1 src1_sel:DWORD
	v_add3_u32 v75, v75, v78, s28
	v_and_b32_sdwa v77, v82, v177 dst_sel:DWORD dst_unused:UNUSED_PAD src0_sel:WORD_1 src1_sel:DWORD
	v_add3_u32 v76, v83, v76, s28
	v_add3_u32 v74, v74, v79, s28
	v_and_b32_e32 v75, 0xffff0000, v75
	v_add3_u32 v77, v82, v77, s28
	v_and_b32_e32 v74, 0xffff0000, v74
	v_or_b32_sdwa v75, v75, v76 dst_sel:DWORD dst_unused:UNUSED_PAD src0_sel:DWORD src1_sel:WORD_1
	v_mul_f32_e32 v76, 0xbfb8aa3b, v70
	v_or_b32_sdwa v74, v74, v77 dst_sel:DWORD dst_unused:UNUSED_PAD src0_sel:DWORD src1_sel:WORD_1
	v_exp_f32_e32 v76, v76
	v_mul_f32_e32 v77, 0xbfb8aa3b, v71
	v_exp_f32_e32 v77, v77
	global_store_dwordx2 v[98:99], v[74:75], off offset:64
	v_add_f32_e32 v74, 1.0, v76
	v_mul_f32_e32 v76, 0xbfb8aa3b, v72
	v_add_f32_e32 v75, 1.0, v77
	v_exp_f32_e32 v77, v76
	v_mul_f32_e32 v76, 0xbfb8aa3b, v73
	v_exp_f32_e32 v78, v76
	v_rcp_f32_e32 v76, v75
	v_add_f32_e32 v75, 1.0, v77
	v_rcp_f32_e32 v74, v74
	v_add_f32_e32 v77, 1.0, v78
	v_rcp_f32_e32 v75, v75
	v_rcp_f32_e32 v77, v77
	v_mov_b32_e32 v78, v70
	v_mov_b32_e32 v79, v72
	v_mov_b32_e32 v72, v71
	v_pk_mul_f32 v[74:75], v[78:79], v[74:75]
	v_mov_b32_e32 v79, v68
	v_pk_mul_f32 v[70:71], v[72:73], v[76:77]
	v_mov_b32_e32 v68, v67
	v_mov_b32_e32 v78, v66
	v_pk_mul_f32 v[66:67], v[68:69], v[70:71]
	v_pk_mul_f32 v[74:75], v[78:79], v[74:75]
	v_and_b32_sdwa v70, v67, v177 dst_sel:DWORD dst_unused:UNUSED_PAD src0_sel:WORD_1 src1_sel:DWORD
	v_and_b32_sdwa v71, v66, v177 dst_sel:DWORD dst_unused:UNUSED_PAD src0_sel:WORD_1 src1_sel:DWORD
	v_and_b32_sdwa v68, v75, v177 dst_sel:DWORD dst_unused:UNUSED_PAD src0_sel:WORD_1 src1_sel:DWORD
	v_and_b32_sdwa v69, v74, v177 dst_sel:DWORD dst_unused:UNUSED_PAD src0_sel:WORD_1 src1_sel:DWORD
	v_add3_u32 v67, v67, v70, s28
	v_add3_u32 v66, v66, v71, s28
	v_add3_u32 v69, v74, v69, s28
	v_add3_u32 v68, v75, v68, s28
	v_and_b32_e32 v67, 0xffff0000, v67
	v_and_b32_e32 v66, 0xffff0000, v66
	v_or_b32_sdwa v67, v67, v68 dst_sel:DWORD dst_unused:UNUSED_PAD src0_sel:DWORD src1_sel:WORD_1
	v_or_b32_sdwa v66, v66, v69 dst_sel:DWORD dst_unused:UNUSED_PAD src0_sel:DWORD src1_sel:WORD_1
	global_store_dwordx2 v[98:99], v[66:67], off offset:96
	v_mul_f32_e32 v67, 0xbfb8aa3b, v62
	v_exp_f32_e32 v68, v67
	v_mul_f32_e32 v67, 0xbfb8aa3b, v63
	v_mul_f32_e32 v70, 0xbfb8aa3b, v64
	v_exp_f32_e32 v69, v67
	v_exp_f32_e32 v71, v70
	v_mul_f32_e32 v70, 0xbfb8aa3b, v65
	v_exp_f32_e32 v72, v70
	v_add_f32_e32 v69, 1.0, v69
	v_add_f32_e32 v68, 1.0, v68
	v_rcp_f32_e32 v70, v69
	v_add_f32_e32 v69, 1.0, v71
	v_add_f32_e32 v71, 1.0, v72
	v_rcp_f32_e32 v68, v68
	v_rcp_f32_e32 v69, v69
	v_rcp_f32_e32 v71, v71
	v_mov_b32_e32 v72, v62
	v_mov_b32_e32 v73, v64
	v_mov_b32_e32 v64, v63
	v_pk_mul_f32 v[68:69], v[72:73], v[68:69]
	v_mov_b32_e32 v73, v60
	v_pk_mul_f32 v[62:63], v[64:65], v[70:71]
	v_mov_b32_e32 v60, v59
	v_mov_b32_e32 v72, v58
	v_pk_mul_f32 v[58:59], v[60:61], v[62:63]
	v_pk_mul_f32 v[68:69], v[72:73], v[68:69]
	v_and_b32_sdwa v62, v59, v177 dst_sel:DWORD dst_unused:UNUSED_PAD src0_sel:WORD_1 src1_sel:DWORD
	v_and_b32_sdwa v60, v69, v177 dst_sel:DWORD dst_unused:UNUSED_PAD src0_sel:WORD_1 src1_sel:DWORD
	v_and_b32_sdwa v63, v58, v177 dst_sel:DWORD dst_unused:UNUSED_PAD src0_sel:WORD_1 src1_sel:DWORD
	v_add3_u32 v59, v59, v62, s28
	v_and_b32_sdwa v61, v68, v177 dst_sel:DWORD dst_unused:UNUSED_PAD src0_sel:WORD_1 src1_sel:DWORD
	v_add3_u32 v60, v69, v60, s28
	v_add3_u32 v58, v58, v63, s28
	v_and_b32_e32 v59, 0xffff0000, v59
	v_add3_u32 v61, v68, v61, s28
	v_and_b32_e32 v58, 0xffff0000, v58
	v_or_b32_sdwa v59, v59, v60 dst_sel:DWORD dst_unused:UNUSED_PAD src0_sel:DWORD src1_sel:WORD_1
	v_mul_f32_e32 v60, 0xbfb8aa3b, v54
	v_or_b32_sdwa v58, v58, v61 dst_sel:DWORD dst_unused:UNUSED_PAD src0_sel:DWORD src1_sel:WORD_1
	v_exp_f32_e32 v60, v60
	v_mul_f32_e32 v61, 0xbfb8aa3b, v55
	v_or_b32_e32 v66, 32, v110
	v_exp_f32_e32 v61, v61
	v_mad_i64_i32 v[66:67], s[6:7], v66, s52, v[106:107]
	v_lshl_add_u64 v[66:67], v[66:67], 0, v[108:109]
	global_store_dwordx2 v[66:67], v[58:59], off
	v_add_f32_e32 v58, 1.0, v60
	v_mul_f32_e32 v60, 0xbfb8aa3b, v56
	v_add_f32_e32 v59, 1.0, v61
	v_exp_f32_e32 v61, v60
	v_mul_f32_e32 v60, 0xbfb8aa3b, v57
	v_exp_f32_e32 v62, v60
	v_rcp_f32_e32 v60, v59
	v_add_f32_e32 v59, 1.0, v61
	v_rcp_f32_e32 v58, v58
	v_add_f32_e32 v61, 1.0, v62
	v_rcp_f32_e32 v59, v59
	v_rcp_f32_e32 v61, v61
	v_mov_b32_e32 v62, v54
	v_mov_b32_e32 v63, v56
	v_mov_b32_e32 v56, v55
	v_pk_mul_f32 v[58:59], v[62:63], v[58:59]
	v_mov_b32_e32 v63, v52
	v_pk_mul_f32 v[54:55], v[56:57], v[60:61]
	v_mov_b32_e32 v52, v51
	v_mov_b32_e32 v62, v50
	v_pk_mul_f32 v[50:51], v[52:53], v[54:55]
	v_pk_mul_f32 v[58:59], v[62:63], v[58:59]
	v_and_b32_sdwa v54, v51, v177 dst_sel:DWORD dst_unused:UNUSED_PAD src0_sel:WORD_1 src1_sel:DWORD
	v_and_b32_sdwa v52, v59, v177 dst_sel:DWORD dst_unused:UNUSED_PAD src0_sel:WORD_1 src1_sel:DWORD
	v_and_b32_sdwa v55, v50, v177 dst_sel:DWORD dst_unused:UNUSED_PAD src0_sel:WORD_1 src1_sel:DWORD
	v_add3_u32 v51, v51, v54, s28
	v_and_b32_sdwa v53, v58, v177 dst_sel:DWORD dst_unused:UNUSED_PAD src0_sel:WORD_1 src1_sel:DWORD
	v_add3_u32 v52, v59, v52, s28
	v_add3_u32 v50, v50, v55, s28
	v_and_b32_e32 v51, 0xffff0000, v51
	v_add3_u32 v53, v58, v53, s28
	v_and_b32_e32 v50, 0xffff0000, v50
	v_or_b32_sdwa v51, v51, v52 dst_sel:DWORD dst_unused:UNUSED_PAD src0_sel:DWORD src1_sel:WORD_1
	v_mul_f32_e32 v52, 0xbfb8aa3b, v46
	v_or_b32_sdwa v50, v50, v53 dst_sel:DWORD dst_unused:UNUSED_PAD src0_sel:DWORD src1_sel:WORD_1
	v_exp_f32_e32 v52, v52
	v_mul_f32_e32 v53, 0xbfb8aa3b, v47
	v_exp_f32_e32 v53, v53
	global_store_dwordx2 v[66:67], v[50:51], off offset:32
	v_add_f32_e32 v50, 1.0, v52
	v_mul_f32_e32 v52, 0xbfb8aa3b, v48
	v_add_f32_e32 v51, 1.0, v53
	v_exp_f32_e32 v53, v52
	v_mul_f32_e32 v52, 0xbfb8aa3b, v49
	v_exp_f32_e32 v54, v52
	v_rcp_f32_e32 v52, v51
	v_add_f32_e32 v51, 1.0, v53
	v_rcp_f32_e32 v50, v50
	v_add_f32_e32 v53, 1.0, v54
	v_rcp_f32_e32 v51, v51
	v_rcp_f32_e32 v53, v53
	v_mov_b32_e32 v54, v46
	v_mov_b32_e32 v55, v48
	v_mov_b32_e32 v48, v47
	v_pk_mul_f32 v[50:51], v[54:55], v[50:51]
	v_mov_b32_e32 v55, v44
	v_pk_mul_f32 v[46:47], v[48:49], v[52:53]
	v_mov_b32_e32 v44, v43
	v_mov_b32_e32 v54, v42
	v_pk_mul_f32 v[42:43], v[44:45], v[46:47]
	v_pk_mul_f32 v[50:51], v[54:55], v[50:51]
	v_and_b32_sdwa v46, v43, v177 dst_sel:DWORD dst_unused:UNUSED_PAD src0_sel:WORD_1 src1_sel:DWORD
	v_and_b32_sdwa v44, v51, v177 dst_sel:DWORD dst_unused:UNUSED_PAD src0_sel:WORD_1 src1_sel:DWORD
	v_and_b32_sdwa v47, v42, v177 dst_sel:DWORD dst_unused:UNUSED_PAD src0_sel:WORD_1 src1_sel:DWORD
	v_add3_u32 v43, v43, v46, s28
	v_and_b32_sdwa v45, v50, v177 dst_sel:DWORD dst_unused:UNUSED_PAD src0_sel:WORD_1 src1_sel:DWORD
	v_add3_u32 v44, v51, v44, s28
	v_add3_u32 v42, v42, v47, s28
	v_and_b32_e32 v43, 0xffff0000, v43
	v_add3_u32 v45, v50, v45, s28
	v_and_b32_e32 v42, 0xffff0000, v42
	v_or_b32_sdwa v43, v43, v44 dst_sel:DWORD dst_unused:UNUSED_PAD src0_sel:DWORD src1_sel:WORD_1
	v_mul_f32_e32 v44, 0xbfb8aa3b, v38
	v_or_b32_sdwa v42, v42, v45 dst_sel:DWORD dst_unused:UNUSED_PAD src0_sel:DWORD src1_sel:WORD_1
	v_exp_f32_e32 v44, v44
	v_mul_f32_e32 v45, 0xbfb8aa3b, v39
	v_exp_f32_e32 v45, v45
	global_store_dwordx2 v[66:67], v[42:43], off offset:64
	v_add_f32_e32 v42, 1.0, v44
	v_mul_f32_e32 v44, 0xbfb8aa3b, v40
	v_add_f32_e32 v43, 1.0, v45
	v_exp_f32_e32 v45, v44
	v_mul_f32_e32 v44, 0xbfb8aa3b, v41
	v_exp_f32_e32 v46, v44
	v_rcp_f32_e32 v44, v43
	v_add_f32_e32 v43, 1.0, v45
	v_rcp_f32_e32 v42, v42
	v_add_f32_e32 v45, 1.0, v46
	v_rcp_f32_e32 v43, v43
	v_rcp_f32_e32 v45, v45
	v_mov_b32_e32 v46, v38
	v_mov_b32_e32 v47, v40
	v_mov_b32_e32 v40, v39
	v_pk_mul_f32 v[42:43], v[46:47], v[42:43]
	v_mov_b32_e32 v47, v36
	v_pk_mul_f32 v[38:39], v[40:41], v[44:45]
	v_mov_b32_e32 v36, v35
	v_mov_b32_e32 v46, v34
	v_pk_mul_f32 v[34:35], v[36:37], v[38:39]
	v_pk_mul_f32 v[42:43], v[46:47], v[42:43]
	v_and_b32_sdwa v38, v35, v177 dst_sel:DWORD dst_unused:UNUSED_PAD src0_sel:WORD_1 src1_sel:DWORD
	v_and_b32_sdwa v39, v34, v177 dst_sel:DWORD dst_unused:UNUSED_PAD src0_sel:WORD_1 src1_sel:DWORD
	v_and_b32_sdwa v36, v43, v177 dst_sel:DWORD dst_unused:UNUSED_PAD src0_sel:WORD_1 src1_sel:DWORD
	v_and_b32_sdwa v37, v42, v177 dst_sel:DWORD dst_unused:UNUSED_PAD src0_sel:WORD_1 src1_sel:DWORD
	v_add3_u32 v35, v35, v38, s28
	v_add3_u32 v34, v34, v39, s28
	v_add3_u32 v37, v42, v37, s28
	v_add3_u32 v36, v43, v36, s28
	v_and_b32_e32 v35, 0xffff0000, v35
	v_and_b32_e32 v34, 0xffff0000, v34
	v_or_b32_sdwa v35, v35, v36 dst_sel:DWORD dst_unused:UNUSED_PAD src0_sel:DWORD src1_sel:WORD_1
	v_or_b32_sdwa v34, v34, v37 dst_sel:DWORD dst_unused:UNUSED_PAD src0_sel:DWORD src1_sel:WORD_1
	global_store_dwordx2 v[66:67], v[34:35], off offset:96
	v_mul_f32_e32 v35, 0xbfb8aa3b, v30
	v_exp_f32_e32 v36, v35
	v_mul_f32_e32 v35, 0xbfb8aa3b, v31
	v_mul_f32_e32 v38, 0xbfb8aa3b, v32
	v_exp_f32_e32 v37, v35
	v_exp_f32_e32 v39, v38
	v_mul_f32_e32 v38, 0xbfb8aa3b, v33
	v_exp_f32_e32 v40, v38
	v_add_f32_e32 v37, 1.0, v37
	v_add_f32_e32 v36, 1.0, v36
	v_rcp_f32_e32 v38, v37
	v_add_f32_e32 v37, 1.0, v39
	v_add_f32_e32 v39, 1.0, v40
	v_rcp_f32_e32 v36, v36
	v_rcp_f32_e32 v37, v37
	v_rcp_f32_e32 v39, v39
	v_mov_b32_e32 v40, v30
	v_mov_b32_e32 v41, v32
	v_mov_b32_e32 v32, v31
	v_pk_mul_f32 v[36:37], v[40:41], v[36:37]
	v_mov_b32_e32 v41, v28
	v_pk_mul_f32 v[30:31], v[32:33], v[38:39]
	v_mov_b32_e32 v28, v27
	v_mov_b32_e32 v40, v26
	v_pk_mul_f32 v[26:27], v[28:29], v[30:31]
	v_pk_mul_f32 v[36:37], v[40:41], v[36:37]
	v_and_b32_sdwa v30, v27, v177 dst_sel:DWORD dst_unused:UNUSED_PAD src0_sel:WORD_1 src1_sel:DWORD
	v_and_b32_sdwa v28, v37, v177 dst_sel:DWORD dst_unused:UNUSED_PAD src0_sel:WORD_1 src1_sel:DWORD
	v_and_b32_sdwa v31, v26, v177 dst_sel:DWORD dst_unused:UNUSED_PAD src0_sel:WORD_1 src1_sel:DWORD
	v_add3_u32 v27, v27, v30, s28
	v_and_b32_sdwa v29, v36, v177 dst_sel:DWORD dst_unused:UNUSED_PAD src0_sel:WORD_1 src1_sel:DWORD
	v_add3_u32 v28, v37, v28, s28
	v_add3_u32 v26, v26, v31, s28
	v_and_b32_e32 v27, 0xffff0000, v27
	v_add3_u32 v29, v36, v29, s28
	v_and_b32_e32 v26, 0xffff0000, v26
	v_or_b32_sdwa v27, v27, v28 dst_sel:DWORD dst_unused:UNUSED_PAD src0_sel:DWORD src1_sel:WORD_1
	v_mul_f32_e32 v28, 0xbfb8aa3b, v22
	v_or_b32_sdwa v26, v26, v29 dst_sel:DWORD dst_unused:UNUSED_PAD src0_sel:DWORD src1_sel:WORD_1
	v_exp_f32_e32 v28, v28
	v_mul_f32_e32 v29, 0xbfb8aa3b, v23
	v_or_b32_e32 v34, 48, v110
	v_exp_f32_e32 v29, v29
	v_mad_i64_i32 v[34:35], s[6:7], v34, s52, v[106:107]
	v_lshl_add_u64 v[34:35], v[34:35], 0, v[108:109]
	global_store_dwordx2 v[34:35], v[26:27], off
	v_add_f32_e32 v26, 1.0, v28
	v_mul_f32_e32 v28, 0xbfb8aa3b, v24
	v_add_f32_e32 v27, 1.0, v29
	v_exp_f32_e32 v29, v28
	v_mul_f32_e32 v28, 0xbfb8aa3b, v25
	v_exp_f32_e32 v30, v28
	v_rcp_f32_e32 v28, v27
	v_add_f32_e32 v27, 1.0, v29
	v_rcp_f32_e32 v26, v26
	v_add_f32_e32 v29, 1.0, v30
	v_rcp_f32_e32 v27, v27
	v_rcp_f32_e32 v29, v29
	v_mov_b32_e32 v30, v22
	v_mov_b32_e32 v31, v24
	v_mov_b32_e32 v24, v23
	v_pk_mul_f32 v[26:27], v[30:31], v[26:27]
	v_mov_b32_e32 v31, v20
	v_pk_mul_f32 v[22:23], v[24:25], v[28:29]
	v_mov_b32_e32 v20, v19
	v_mov_b32_e32 v30, v18
	v_pk_mul_f32 v[18:19], v[20:21], v[22:23]
	v_pk_mul_f32 v[26:27], v[30:31], v[26:27]
	v_and_b32_sdwa v22, v19, v177 dst_sel:DWORD dst_unused:UNUSED_PAD src0_sel:WORD_1 src1_sel:DWORD
	v_and_b32_sdwa v20, v27, v177 dst_sel:DWORD dst_unused:UNUSED_PAD src0_sel:WORD_1 src1_sel:DWORD
	v_and_b32_sdwa v23, v18, v177 dst_sel:DWORD dst_unused:UNUSED_PAD src0_sel:WORD_1 src1_sel:DWORD
	v_add3_u32 v19, v19, v22, s28
	v_and_b32_sdwa v21, v26, v177 dst_sel:DWORD dst_unused:UNUSED_PAD src0_sel:WORD_1 src1_sel:DWORD
	v_add3_u32 v20, v27, v20, s28
	v_add3_u32 v18, v18, v23, s28
	v_and_b32_e32 v19, 0xffff0000, v19
	v_add3_u32 v21, v26, v21, s28
	v_and_b32_e32 v18, 0xffff0000, v18
	v_or_b32_sdwa v19, v19, v20 dst_sel:DWORD dst_unused:UNUSED_PAD src0_sel:DWORD src1_sel:WORD_1
	v_mul_f32_e32 v20, 0xbfb8aa3b, v14
	v_or_b32_sdwa v18, v18, v21 dst_sel:DWORD dst_unused:UNUSED_PAD src0_sel:DWORD src1_sel:WORD_1
	v_exp_f32_e32 v20, v20
	v_mul_f32_e32 v21, 0xbfb8aa3b, v15
	v_exp_f32_e32 v21, v21
	global_store_dwordx2 v[34:35], v[18:19], off offset:32
	v_add_f32_e32 v18, 1.0, v20
	v_mul_f32_e32 v20, 0xbfb8aa3b, v16
	v_add_f32_e32 v19, 1.0, v21
	v_exp_f32_e32 v21, v20
	v_mul_f32_e32 v20, 0xbfb8aa3b, v17
	v_exp_f32_e32 v22, v20
	v_rcp_f32_e32 v20, v19
	v_add_f32_e32 v19, 1.0, v21
	v_rcp_f32_e32 v18, v18
	v_add_f32_e32 v21, 1.0, v22
	v_rcp_f32_e32 v19, v19
	v_rcp_f32_e32 v21, v21
	v_mov_b32_e32 v22, v14
	v_mov_b32_e32 v23, v16
	v_mov_b32_e32 v16, v15
	v_pk_mul_f32 v[18:19], v[22:23], v[18:19]
	v_mov_b32_e32 v23, v12
	v_pk_mul_f32 v[14:15], v[16:17], v[20:21]
	v_mov_b32_e32 v12, v11
	v_mov_b32_e32 v22, v10
	v_pk_mul_f32 v[10:11], v[12:13], v[14:15]
	v_pk_mul_f32 v[18:19], v[22:23], v[18:19]
	v_and_b32_sdwa v14, v11, v177 dst_sel:DWORD dst_unused:UNUSED_PAD src0_sel:WORD_1 src1_sel:DWORD
	v_and_b32_sdwa v12, v19, v177 dst_sel:DWORD dst_unused:UNUSED_PAD src0_sel:WORD_1 src1_sel:DWORD
	v_and_b32_sdwa v15, v10, v177 dst_sel:DWORD dst_unused:UNUSED_PAD src0_sel:WORD_1 src1_sel:DWORD
	v_add3_u32 v11, v11, v14, s28
	v_and_b32_sdwa v13, v18, v177 dst_sel:DWORD dst_unused:UNUSED_PAD src0_sel:WORD_1 src1_sel:DWORD
	v_add3_u32 v12, v19, v12, s28
	v_add3_u32 v10, v10, v15, s28
	v_and_b32_e32 v11, 0xffff0000, v11
	v_add3_u32 v13, v18, v13, s28
	v_and_b32_e32 v10, 0xffff0000, v10
	v_or_b32_sdwa v11, v11, v12 dst_sel:DWORD dst_unused:UNUSED_PAD src0_sel:DWORD src1_sel:WORD_1
	v_mul_f32_e32 v12, 0xbfb8aa3b, v6
	v_or_b32_sdwa v10, v10, v13 dst_sel:DWORD dst_unused:UNUSED_PAD src0_sel:DWORD src1_sel:WORD_1
	v_exp_f32_e32 v12, v12
	v_mul_f32_e32 v13, 0xbfb8aa3b, v7
	v_exp_f32_e32 v13, v13
	global_store_dwordx2 v[34:35], v[10:11], off offset:64
	v_add_f32_e32 v10, 1.0, v12
	v_mul_f32_e32 v12, 0xbfb8aa3b, v8
	v_add_f32_e32 v11, 1.0, v13
	v_exp_f32_e32 v13, v12
	v_mul_f32_e32 v12, 0xbfb8aa3b, v9
	v_exp_f32_e32 v14, v12
	v_rcp_f32_e32 v12, v11
	v_add_f32_e32 v11, 1.0, v13
	v_rcp_f32_e32 v10, v10
	v_add_f32_e32 v13, 1.0, v14
	v_rcp_f32_e32 v11, v11
	v_rcp_f32_e32 v13, v13
	v_mov_b32_e32 v14, v6
	v_mov_b32_e32 v15, v8
	v_mov_b32_e32 v8, v7
	v_pk_mul_f32 v[10:11], v[14:15], v[10:11]
	v_mov_b32_e32 v15, v4
	v_pk_mul_f32 v[6:7], v[8:9], v[12:13]
	v_mov_b32_e32 v4, v3
	v_mov_b32_e32 v14, v2
	v_pk_mul_f32 v[2:3], v[4:5], v[6:7]
	v_pk_mul_f32 v[10:11], v[14:15], v[10:11]
	v_and_b32_sdwa v6, v3, v177 dst_sel:DWORD dst_unused:UNUSED_PAD src0_sel:WORD_1 src1_sel:DWORD
	v_and_b32_sdwa v7, v2, v177 dst_sel:DWORD dst_unused:UNUSED_PAD src0_sel:WORD_1 src1_sel:DWORD
	v_and_b32_sdwa v4, v11, v177 dst_sel:DWORD dst_unused:UNUSED_PAD src0_sel:WORD_1 src1_sel:DWORD
	v_and_b32_sdwa v5, v10, v177 dst_sel:DWORD dst_unused:UNUSED_PAD src0_sel:WORD_1 src1_sel:DWORD
	v_add3_u32 v3, v3, v6, s28
	v_add3_u32 v2, v2, v7, s28
	v_add3_u32 v5, v10, v5, s28
	v_add3_u32 v4, v11, v4, s28
	v_and_b32_e32 v3, 0xffff0000, v3
	v_and_b32_e32 v2, 0xffff0000, v2
	s_add_i32 s14, s14, s11
	v_or_b32_sdwa v3, v3, v4 dst_sel:DWORD dst_unused:UNUSED_PAD src0_sel:DWORD src1_sel:WORD_1
	v_or_b32_sdwa v2, v2, v5 dst_sel:DWORD dst_unused:UNUSED_PAD src0_sel:DWORD src1_sel:WORD_1
	s_cmpk_gt_i32 s14, 0x5ff
	global_store_dwordx2 v[34:35], v[2:3], off offset:96
	s_cbranch_scc0 .LBB0_1461

.LBB0_1528:
	s_bitcmp1_b32 s4, 0
	s_cselect_b32 s2, 0x12000, 0
	v_or_b32_e32 v218, s2, v207
	v_add_u32_e32 v214, v218, v0
	v_add_u32_e32 v246, v218, v167
	ds_read_b128 v[184:187], v214
	ds_read_b128 v[218:221], v246 offset:32768
	ds_read_b128 v[198:201], v214 offset:2048
	ds_read_b128 v[210:213], v214 offset:4096
	ds_read_b128 v[214:217], v214 offset:6144
	ds_read_b128 v[222:225], v246 offset:34816
	ds_read_b128 v[226:229], v246 offset:36864
	ds_read_b128 v[230:233], v246 offset:38912
	ds_read_b128 v[234:237], v246 offset:40960
	ds_read_b128 v[238:241], v246 offset:43008
	ds_read_b128 v[242:245], v246 offset:45056
	ds_read_b128 v[246:249], v246 offset:47104
	s_add_i32 s10, s4, 1
	s_bitcmp1_b32 s10, 0
	s_cselect_b32 s3, 0x12000, 0
	v_add_u32_e32 v171, s3, v166
	v_xor_b32_e32 v169, 64, v207
	v_add3_u32 v169, s2, v167, v169
	s_waitcnt lgkmcnt(10)
	v_mfma_f32_16x16x32_bf16 v[158:161], v[218:221], v[184:187], v[158:161]
	s_waitcnt lgkmcnt(9)
	v_mfma_f32_16x16x32_bf16 v[94:97], v[218:221], v[198:201], v[94:97]
	s_waitcnt lgkmcnt(8)
	v_mfma_f32_16x16x32_bf16 v[62:65], v[218:221], v[210:213], v[62:65]
	s_waitcnt lgkmcnt(7)
	v_mfma_f32_16x16x32_bf16 v[30:33], v[218:221], v[214:217], v[30:33]
	ds_read_b128 v[218:221], v169 offset:32768
	s_waitcnt lgkmcnt(7)
	v_mfma_f32_16x16x32_bf16 v[154:157], v[222:225], v[184:187], v[154:157]
	v_mfma_f32_16x16x32_bf16 v[90:93], v[222:225], v[198:201], v[90:93]
	v_mfma_f32_16x16x32_bf16 v[58:61], v[222:225], v[210:213], v[58:61]
	v_mfma_f32_16x16x32_bf16 v[26:29], v[222:225], v[214:217], v[26:29]
	ds_read_b128 v[222:225], v169 offset:34816
	s_waitcnt lgkmcnt(7)
	v_mfma_f32_16x16x32_bf16 v[150:153], v[226:229], v[184:187], v[150:153]
	v_mfma_f32_16x16x32_bf16 v[86:89], v[226:229], v[198:201], v[86:89]
	v_mfma_f32_16x16x32_bf16 v[54:57], v[226:229], v[210:213], v[54:57]
	v_mfma_f32_16x16x32_bf16 v[22:25], v[226:229], v[214:217], v[22:25]
	ds_read_b128 v[226:229], v169 offset:36864
	s_waitcnt lgkmcnt(7)
	v_mfma_f32_16x16x32_bf16 v[146:149], v[230:233], v[184:187], v[146:149]
	v_mfma_f32_16x16x32_bf16 v[82:85], v[230:233], v[198:201], v[82:85]
	v_mfma_f32_16x16x32_bf16 v[50:53], v[230:233], v[210:213], v[50:53]
	v_mfma_f32_16x16x32_bf16 v[18:21], v[230:233], v[214:217], v[18:21]
	ds_read_b128 v[230:233], v169 offset:38912
	s_waitcnt lgkmcnt(7)
	v_mfma_f32_16x16x32_bf16 v[134:137], v[234:237], v[184:187], v[134:137]
	v_mfma_f32_16x16x32_bf16 v[78:81], v[234:237], v[198:201], v[78:81]
	v_mfma_f32_16x16x32_bf16 v[46:49], v[234:237], v[210:213], v[46:49]
	v_mfma_f32_16x16x32_bf16 v[14:17], v[234:237], v[214:217], v[14:17]
	ds_read_b128 v[234:237], v169 offset:40960
	s_waitcnt lgkmcnt(7)
	v_mfma_f32_16x16x32_bf16 v[106:109], v[238:241], v[184:187], v[106:109]
	v_mfma_f32_16x16x32_bf16 v[74:77], v[238:241], v[198:201], v[74:77]
	v_mfma_f32_16x16x32_bf16 v[42:45], v[238:241], v[210:213], v[42:45]
	v_mfma_f32_16x16x32_bf16 v[10:13], v[238:241], v[214:217], v[10:13]
	ds_read_b128 v[238:241], v169 offset:43008
	s_waitcnt lgkmcnt(7)
	v_mfma_f32_16x16x32_bf16 v[102:105], v[242:245], v[184:187], v[102:105]
	v_mfma_f32_16x16x32_bf16 v[70:73], v[242:245], v[198:201], v[70:73]
	v_mfma_f32_16x16x32_bf16 v[38:41], v[242:245], v[210:213], v[38:41]
	v_mfma_f32_16x16x32_bf16 v[6:9], v[242:245], v[214:217], v[6:9]
	ds_read_b128 v[242:245], v169 offset:45056
	s_waitcnt lgkmcnt(7)
	v_mfma_f32_16x16x32_bf16 v[98:101], v[246:249], v[184:187], v[98:101]
	v_mfma_f32_16x16x32_bf16 v[66:69], v[246:249], v[198:201], v[66:69]
	v_xor_b32_e32 v169, 64, v207
	v_add3_u32 v169, s2, v0, v169
	ds_read_b128 v[184:187], v169
	ds_read_b128 v[198:201], v169 offset:2048
	v_mfma_f32_16x16x32_bf16 v[34:37], v[246:249], v[210:213], v[34:37]
	ds_read_b128 v[210:213], v169 offset:4096
	v_mfma_f32_16x16x32_bf16 v[2:5], v[246:249], v[214:217], v[2:5]
	ds_read_b128 v[214:217], v169 offset:6144
	v_xor_b32_e32 v169, 64, v207
	v_add3_u32 v169, s2, v167, v169
	ds_read_b128 v[246:249], v169 offset:47104
	s_waitcnt lgkmcnt(4)
	v_mfma_f32_16x16x32_bf16 v[158:161], v[218:221], v[184:187], v[158:161]
	s_waitcnt lgkmcnt(3)
	v_mfma_f32_16x16x32_bf16 v[94:97], v[218:221], v[198:201], v[94:97]
	s_waitcnt lgkmcnt(2)
	v_mfma_f32_16x16x32_bf16 v[62:65], v[218:221], v[210:213], v[62:65]
	s_waitcnt lgkmcnt(1)
	v_mfma_f32_16x16x32_bf16 v[30:33], v[218:221], v[214:217], v[30:33]
	s_waitcnt vmcnt(7)
	ds_write_b128 v171, v[118:121]
	v_mfma_f32_16x16x32_bf16 v[154:157], v[222:225], v[184:187], v[154:157]
	v_mfma_f32_16x16x32_bf16 v[90:93], v[222:225], v[198:201], v[90:93]
	global_load_dwordx4 v[118:121], v168, vcc offset:256
	v_mfma_f32_16x16x32_bf16 v[58:61], v[222:225], v[210:213], v[58:61]
	v_mfma_f32_16x16x32_bf16 v[26:29], v[222:225], v[214:217], v[26:29]
	s_waitcnt vmcnt(7)
	ds_write_b128 v171, v[110:113] offset:8192
	v_mfma_f32_16x16x32_bf16 v[150:153], v[226:229], v[184:187], v[150:153]
	v_mfma_f32_16x16x32_bf16 v[86:89], v[226:229], v[198:201], v[86:89]
	v_add_u32_e32 v110, 0x58000, v168
	global_load_dwordx4 v[110:113], v110, vcc offset:256
	v_mfma_f32_16x16x32_bf16 v[54:57], v[226:229], v[210:213], v[54:57]
	v_mfma_f32_16x16x32_bf16 v[22:25], v[226:229], v[214:217], v[22:25]
	s_waitcnt vmcnt(7)
	ds_write_b128 v171, v[114:117] offset:16384
	v_mfma_f32_16x16x32_bf16 v[146:149], v[230:233], v[184:187], v[146:149]
	v_mfma_f32_16x16x32_bf16 v[82:85], v[230:233], v[198:201], v[82:85]
	v_add_u32_e32 v114, 0xb0000, v168
	global_load_dwordx4 v[114:117], v114, vcc offset:256
	v_mfma_f32_16x16x32_bf16 v[50:53], v[230:233], v[210:213], v[50:53]
	v_mfma_f32_16x16x32_bf16 v[18:21], v[230:233], v[214:217], v[18:21]
	s_waitcnt vmcnt(7)
	ds_write_b128 v171, v[130:133] offset:24576
	v_mfma_f32_16x16x32_bf16 v[134:137], v[234:237], v[184:187], v[134:137]
	v_mfma_f32_16x16x32_bf16 v[78:81], v[234:237], v[198:201], v[78:81]
	v_add_u32_e32 v130, 0x108000, v168
	global_load_dwordx4 v[130:133], v130, vcc offset:256
	v_mfma_f32_16x16x32_bf16 v[46:49], v[234:237], v[210:213], v[46:49]
	v_mfma_f32_16x16x32_bf16 v[14:17], v[234:237], v[214:217], v[14:17]
	s_waitcnt vmcnt(7)
	ds_write_b128 v171, v[126:129] offset:32768
	v_mfma_f32_16x16x32_bf16 v[106:109], v[238:241], v[184:187], v[106:109]
	v_mfma_f32_16x16x32_bf16 v[74:77], v[238:241], v[198:201], v[74:77]
	global_load_dwordx4 v[126:129], v170, s[100:101] offset:256
	v_mfma_f32_16x16x32_bf16 v[42:45], v[238:241], v[210:213], v[42:45]
	v_mfma_f32_16x16x32_bf16 v[10:13], v[238:241], v[214:217], v[10:13]
	s_waitcnt vmcnt(7)
	ds_write_b128 v171, v[122:125] offset:40960
	v_mfma_f32_16x16x32_bf16 v[102:105], v[242:245], v[184:187], v[102:105]
	v_mfma_f32_16x16x32_bf16 v[70:73], v[242:245], v[198:201], v[70:73]
	v_add_u32_e32 v122, 0x58000, v170
	global_load_dwordx4 v[122:125], v122, s[100:101] offset:256
	v_mfma_f32_16x16x32_bf16 v[38:41], v[242:245], v[210:213], v[38:41]
	v_mfma_f32_16x16x32_bf16 v[6:9], v[242:245], v[214:217], v[6:9]
	s_waitcnt vmcnt(7)
	ds_write_b128 v171, v[142:145] offset:49152
	s_waitcnt lgkmcnt(7)
	v_mfma_f32_16x16x32_bf16 v[98:101], v[246:249], v[184:187], v[98:101]
	v_mfma_f32_16x16x32_bf16 v[66:69], v[246:249], v[198:201], v[66:69]
	v_add_u32_e32 v142, 0xb0000, v170
	global_load_dwordx4 v[142:145], v142, s[100:101] offset:256
	v_mfma_f32_16x16x32_bf16 v[34:37], v[246:249], v[210:213], v[34:37]
	v_mfma_f32_16x16x32_bf16 v[2:5], v[246:249], v[214:217], v[2:5]
	s_waitcnt vmcnt(7)
	ds_write_b128 v171, v[138:141] offset:57344
	v_add_u32_e32 v138, 0x108000, v170
	global_load_dwordx4 v[138:141], v138, s[100:101] offset:256
	v_add_u32_e32 v168, 0x80, v168
	v_add_u32_e32 v170, 0x80, v170
	s_waitcnt lgkmcnt(0)
	s_barrier
	s_cmp_eq_u32 s10, 44
	s_mov_b32 s4, s10
	s_cbranch_scc0 .LBB0_1528
	s_waitcnt vmcnt(4)
	v_add_u32_e32 v110, s7, v206
	s_waitcnt vmcnt(3)
	v_or_b32_e32 v114, v110, v205
	v_cmp_lt_i32_e32 vcc, s97, v114
	v_ashrrev_i32_e32 v112, 31, v114
	v_add_u32_e32 v116, 0xffffc000, v114
	v_ashrrev_i32_e32 v115, 11, v110
	v_cndmask_b32_e64 v113, v112, 0, vcc
	v_cndmask_b32_e32 v112, v114, v116, vcc
	v_mov_b32_e32 v116, s45
	v_mov_b32_e32 v117, s13
	v_mov_b32_e32 v118, s44
	v_mov_b32_e32 v119, s12
	v_or_b32_e32 v110, s6, v208
	s_waitcnt vmcnt(2)
	v_cndmask_b32_e64 v122, v115, 8, vcc
	v_cndmask_b32_e32 v121, v116, v117, vcc
	v_cndmask_b32_e32 v120, v118, v119, vcc
	v_lshlrev_b64 v[112:113], 12, v[112:113]
	v_ashrrev_i32_e32 v111, 31, v110
	v_lshl_add_u64 v[112:113], v[120:121], 0, v[112:113]
	v_mul_hi_i32_i24_e32 v121, 0x9000, v122
	v_mul_i32_i24_e32 v120, 0x9000, v122
	v_lshl_add_u64 v[120:121], s[14:15], 0, v[120:121]
	v_lshlrev_b64 v[110:111], 2, v[110:111]
	s_waitcnt vmcnt(0)
	v_lshl_add_u64 v[128:129], v[120:121], 0, v[110:111]
	global_load_dwordx4 v[120:123], v[128:129], off
	v_lshl_add_u64 v[112:113], v[112:113], 0, v[110:111]
	global_load_dwordx4 v[124:127], v[112:113], off
	s_waitcnt vmcnt(1)
	v_pk_mul_f32 v[120:121], v[120:121], 0.5 op_sel_hi:[1,0]
	v_pk_mul_f32 v[122:123], v[122:123], 0.5 op_sel_hi:[1,0]
	s_waitcnt vmcnt(0)
	v_pk_fma_f32 v[120:121], v[158:159], v[120:121], v[124:125]
	v_pk_fma_f32 v[122:123], v[160:161], v[122:123], v[126:127]
	global_store_dwordx4 v[112:113], v[120:123], off
	global_load_dwordx4 v[120:123], v[128:129], off offset:64
	s_nop 0
	global_load_dwordx4 v[124:127], v[112:113], off offset:64
	s_waitcnt vmcnt(1)
	v_pk_mul_f32 v[120:121], v[120:121], 0.5 op_sel_hi:[1,0]
	v_pk_mul_f32 v[122:123], v[122:123], 0.5 op_sel_hi:[1,0]
	s_waitcnt vmcnt(0)
	v_pk_fma_f32 v[120:121], v[154:155], v[120:121], v[124:125]
	v_pk_fma_f32 v[122:123], v[156:157], v[122:123], v[126:127]
	global_store_dwordx4 v[112:113], v[120:123], off offset:64
	global_load_dwordx4 v[120:123], v[128:129], off offset:128
	s_nop 0
	global_load_dwordx4 v[124:127], v[112:113], off offset:128
	s_waitcnt vmcnt(1)
	v_pk_mul_f32 v[120:121], v[120:121], 0.5 op_sel_hi:[1,0]
	v_pk_mul_f32 v[122:123], v[122:123], 0.5 op_sel_hi:[1,0]
	s_waitcnt vmcnt(0)
	v_pk_fma_f32 v[120:121], v[150:151], v[120:121], v[124:125]
	v_pk_fma_f32 v[122:123], v[152:153], v[122:123], v[126:127]
	global_store_dwordx4 v[112:113], v[120:123], off offset:128
	global_load_dwordx4 v[120:123], v[128:129], off offset:192
	s_nop 0
	global_load_dwordx4 v[124:127], v[112:113], off offset:192
	s_waitcnt vmcnt(1)
	v_pk_mul_f32 v[120:121], v[120:121], 0.5 op_sel_hi:[1,0]
	v_pk_mul_f32 v[122:123], v[122:123], 0.5 op_sel_hi:[1,0]
	s_waitcnt vmcnt(0)
	v_pk_fma_f32 v[120:121], v[146:147], v[120:121], v[124:125]
	v_pk_fma_f32 v[122:123], v[148:149], v[122:123], v[126:127]
	global_store_dwordx4 v[112:113], v[120:123], off offset:192
	global_load_dwordx4 v[120:123], v[128:129], off offset:256
	s_nop 0
	global_load_dwordx4 v[124:127], v[112:113], off offset:256
	s_waitcnt vmcnt(1)
	v_pk_mul_f32 v[120:121], v[120:121], 0.5 op_sel_hi:[1,0]
	v_pk_mul_f32 v[122:123], v[122:123], 0.5 op_sel_hi:[1,0]
	s_waitcnt vmcnt(0)
	v_pk_fma_f32 v[120:121], v[134:135], v[120:121], v[124:125]
	v_pk_fma_f32 v[122:123], v[136:137], v[122:123], v[126:127]
	global_store_dwordx4 v[112:113], v[120:123], off offset:256
	global_load_dwordx4 v[120:123], v[128:129], off offset:320
	s_nop 0
	global_load_dwordx4 v[124:127], v[112:113], off offset:320
	s_waitcnt vmcnt(1)
	v_pk_mul_f32 v[120:121], v[120:121], 0.5 op_sel_hi:[1,0]
	v_pk_mul_f32 v[122:123], v[122:123], 0.5 op_sel_hi:[1,0]
	s_waitcnt vmcnt(0)
	v_pk_fma_f32 v[106:107], v[106:107], v[120:121], v[124:125]
	v_pk_fma_f32 v[108:109], v[108:109], v[122:123], v[126:127]
	global_store_dwordx4 v[112:113], v[106:109], off offset:320
	global_load_dwordx4 v[106:109], v[128:129], off offset:384
	s_nop 0
	global_load_dwordx4 v[120:123], v[112:113], off offset:384
	s_waitcnt vmcnt(1)
	v_pk_mul_f32 v[106:107], v[106:107], 0.5 op_sel_hi:[1,0]
	v_pk_mul_f32 v[108:109], v[108:109], 0.5 op_sel_hi:[1,0]
	s_waitcnt vmcnt(0)
	v_pk_fma_f32 v[102:103], v[102:103], v[106:107], v[120:121]
	v_pk_fma_f32 v[104:105], v[104:105], v[108:109], v[122:123]
	global_store_dwordx4 v[112:113], v[102:105], off offset:384
	global_load_dwordx4 v[102:105], v[128:129], off offset:448
	s_nop 0
	global_load_dwordx4 v[106:109], v[112:113], off offset:448
	s_waitcnt vmcnt(1)
	v_pk_mul_f32 v[102:103], v[102:103], 0.5 op_sel_hi:[1,0]
	v_pk_mul_f32 v[104:105], v[104:105], 0.5 op_sel_hi:[1,0]
	s_waitcnt vmcnt(0)
	v_pk_fma_f32 v[98:99], v[98:99], v[102:103], v[106:107]
	v_pk_fma_f32 v[100:101], v[100:101], v[104:105], v[108:109]
	global_store_dwordx4 v[112:113], v[98:101], off offset:448
	s_nop 1
	v_or_b32_e32 v98, 16, v114
	v_cmp_lt_i32_e32 vcc, s97, v98
	v_add_u32_e32 v100, 0xffffc010, v114
	v_ashrrev_i32_e32 v99, 31, v98
	v_cndmask_b32_e64 v99, v99, 0, vcc
	v_cndmask_b32_e32 v98, v98, v100, vcc
	v_cndmask_b32_e64 v102, v115, 8, vcc
	v_cndmask_b32_e32 v101, v116, v117, vcc
	v_cndmask_b32_e32 v100, v118, v119, vcc
	v_lshlrev_b64 v[98:99], 12, v[98:99]
	v_lshl_add_u64 v[98:99], v[100:101], 0, v[98:99]
	v_mul_hi_i32_i24_e32 v101, 0x9000, v102
	v_mul_i32_i24_e32 v100, 0x9000, v102
	v_lshl_add_u64 v[100:101], s[14:15], 0, v[100:101]
	v_lshl_add_u64 v[108:109], v[100:101], 0, v[110:111]
	global_load_dwordx4 v[100:103], v[108:109], off
	v_lshl_add_u64 v[98:99], v[98:99], 0, v[110:111]
	global_load_dwordx4 v[104:107], v[98:99], off
	s_waitcnt vmcnt(1)
	v_pk_mul_f32 v[100:101], v[100:101], 0.5 op_sel_hi:[1,0]
	v_pk_mul_f32 v[102:103], v[102:103], 0.5 op_sel_hi:[1,0]
	s_waitcnt vmcnt(0)
	v_pk_fma_f32 v[94:95], v[94:95], v[100:101], v[104:105]
	v_pk_fma_f32 v[96:97], v[96:97], v[102:103], v[106:107]
	global_store_dwordx4 v[98:99], v[94:97], off
	global_load_dwordx4 v[94:97], v[108:109], off offset:64
	s_nop 0
	global_load_dwordx4 v[100:103], v[98:99], off offset:64
	s_waitcnt vmcnt(1)
	v_pk_mul_f32 v[94:95], v[94:95], 0.5 op_sel_hi:[1,0]
	v_pk_mul_f32 v[96:97], v[96:97], 0.5 op_sel_hi:[1,0]
	s_waitcnt vmcnt(0)
	v_pk_fma_f32 v[90:91], v[90:91], v[94:95], v[100:101]
	v_pk_fma_f32 v[92:93], v[92:93], v[96:97], v[102:103]
	global_store_dwordx4 v[98:99], v[90:93], off offset:64
	global_load_dwordx4 v[90:93], v[108:109], off offset:128
	s_nop 0
	global_load_dwordx4 v[94:97], v[98:99], off offset:128
	s_waitcnt vmcnt(1)
	v_pk_mul_f32 v[90:91], v[90:91], 0.5 op_sel_hi:[1,0]
	v_pk_mul_f32 v[92:93], v[92:93], 0.5 op_sel_hi:[1,0]
	s_waitcnt vmcnt(0)
	v_pk_fma_f32 v[86:87], v[86:87], v[90:91], v[94:95]
	v_pk_fma_f32 v[88:89], v[88:89], v[92:93], v[96:97]
	global_store_dwordx4 v[98:99], v[86:89], off offset:128
	global_load_dwordx4 v[86:89], v[108:109], off offset:192
	s_nop 0
	global_load_dwordx4 v[90:93], v[98:99], off offset:192
	s_waitcnt vmcnt(1)
	v_pk_mul_f32 v[86:87], v[86:87], 0.5 op_sel_hi:[1,0]
	v_pk_mul_f32 v[88:89], v[88:89], 0.5 op_sel_hi:[1,0]
	s_waitcnt vmcnt(0)
	v_pk_fma_f32 v[82:83], v[82:83], v[86:87], v[90:91]
	v_pk_fma_f32 v[84:85], v[84:85], v[88:89], v[92:93]
	global_store_dwordx4 v[98:99], v[82:85], off offset:192
	global_load_dwordx4 v[82:85], v[108:109], off offset:256
	s_nop 0
	global_load_dwordx4 v[86:89], v[98:99], off offset:256
	s_waitcnt vmcnt(1)
	v_pk_mul_f32 v[82:83], v[82:83], 0.5 op_sel_hi:[1,0]
	v_pk_mul_f32 v[84:85], v[84:85], 0.5 op_sel_hi:[1,0]
	s_waitcnt vmcnt(0)
	v_pk_fma_f32 v[78:79], v[78:79], v[82:83], v[86:87]
	v_pk_fma_f32 v[80:81], v[80:81], v[84:85], v[88:89]
	global_store_dwordx4 v[98:99], v[78:81], off offset:256
	global_load_dwordx4 v[78:81], v[108:109], off offset:320
	s_nop 0
	global_load_dwordx4 v[82:85], v[98:99], off offset:320
	s_waitcnt vmcnt(1)
	v_pk_mul_f32 v[78:79], v[78:79], 0.5 op_sel_hi:[1,0]
	v_pk_mul_f32 v[80:81], v[80:81], 0.5 op_sel_hi:[1,0]
	s_waitcnt vmcnt(0)
	v_pk_fma_f32 v[74:75], v[74:75], v[78:79], v[82:83]
	v_pk_fma_f32 v[76:77], v[76:77], v[80:81], v[84:85]
	global_store_dwordx4 v[98:99], v[74:77], off offset:320
	global_load_dwordx4 v[74:77], v[108:109], off offset:384
	s_nop 0
	global_load_dwordx4 v[78:81], v[98:99], off offset:384
	s_waitcnt vmcnt(1)
	v_pk_mul_f32 v[74:75], v[74:75], 0.5 op_sel_hi:[1,0]
	v_pk_mul_f32 v[76:77], v[76:77], 0.5 op_sel_hi:[1,0]
	s_waitcnt vmcnt(0)
	v_pk_fma_f32 v[70:71], v[70:71], v[74:75], v[78:79]
	v_pk_fma_f32 v[72:73], v[72:73], v[76:77], v[80:81]
	global_store_dwordx4 v[98:99], v[70:73], off offset:384
	global_load_dwordx4 v[70:73], v[108:109], off offset:448
	s_nop 0
	global_load_dwordx4 v[74:77], v[98:99], off offset:448
	s_waitcnt vmcnt(1)
	v_pk_mul_f32 v[70:71], v[70:71], 0.5 op_sel_hi:[1,0]
	v_pk_mul_f32 v[72:73], v[72:73], 0.5 op_sel_hi:[1,0]
	s_waitcnt vmcnt(0)
	v_pk_fma_f32 v[66:67], v[66:67], v[70:71], v[74:75]
	v_pk_fma_f32 v[68:69], v[68:69], v[72:73], v[76:77]
	global_store_dwordx4 v[98:99], v[66:69], off offset:448
	s_nop 1
	v_or_b32_e32 v66, 32, v114
	v_cmp_lt_i32_e32 vcc, s97, v66
	v_add_u32_e32 v68, 0xffffc020, v114
	v_ashrrev_i32_e32 v67, 31, v66
	v_cndmask_b32_e64 v67, v67, 0, vcc
	v_cndmask_b32_e32 v66, v66, v68, vcc
	v_cndmask_b32_e64 v70, v115, 8, vcc
	v_cndmask_b32_e32 v69, v116, v117, vcc
	v_cndmask_b32_e32 v68, v118, v119, vcc
	v_lshlrev_b64 v[66:67], 12, v[66:67]
	v_lshl_add_u64 v[66:67], v[68:69], 0, v[66:67]
	v_mul_hi_i32_i24_e32 v69, 0x9000, v70
	v_mul_i32_i24_e32 v68, 0x9000, v70
	v_lshl_add_u64 v[68:69], s[14:15], 0, v[68:69]
	v_lshl_add_u64 v[76:77], v[68:69], 0, v[110:111]
	global_load_dwordx4 v[68:71], v[76:77], off
	v_lshl_add_u64 v[66:67], v[66:67], 0, v[110:111]
	global_load_dwordx4 v[72:75], v[66:67], off
	s_waitcnt vmcnt(1)
	v_pk_mul_f32 v[68:69], v[68:69], 0.5 op_sel_hi:[1,0]
	v_pk_mul_f32 v[70:71], v[70:71], 0.5 op_sel_hi:[1,0]
	s_waitcnt vmcnt(0)
	v_pk_fma_f32 v[62:63], v[62:63], v[68:69], v[72:73]
	v_pk_fma_f32 v[64:65], v[64:65], v[70:71], v[74:75]
	global_store_dwordx4 v[66:67], v[62:65], off
	global_load_dwordx4 v[62:65], v[76:77], off offset:64
	s_nop 0
	global_load_dwordx4 v[68:71], v[66:67], off offset:64
	s_waitcnt vmcnt(1)
	v_pk_mul_f32 v[62:63], v[62:63], 0.5 op_sel_hi:[1,0]
	v_pk_mul_f32 v[64:65], v[64:65], 0.5 op_sel_hi:[1,0]
	s_waitcnt vmcnt(0)
	v_pk_fma_f32 v[58:59], v[58:59], v[62:63], v[68:69]
	v_pk_fma_f32 v[60:61], v[60:61], v[64:65], v[70:71]
	global_store_dwordx4 v[66:67], v[58:61], off offset:64
	global_load_dwordx4 v[58:61], v[76:77], off offset:128
	s_nop 0
	global_load_dwordx4 v[62:65], v[66:67], off offset:128
	s_waitcnt vmcnt(1)
	v_pk_mul_f32 v[58:59], v[58:59], 0.5 op_sel_hi:[1,0]
	v_pk_mul_f32 v[60:61], v[60:61], 0.5 op_sel_hi:[1,0]
	s_waitcnt vmcnt(0)
	v_pk_fma_f32 v[54:55], v[54:55], v[58:59], v[62:63]
	v_pk_fma_f32 v[56:57], v[56:57], v[60:61], v[64:65]
	global_store_dwordx4 v[66:67], v[54:57], off offset:128
	global_load_dwordx4 v[54:57], v[76:77], off offset:192
	s_nop 0
	global_load_dwordx4 v[58:61], v[66:67], off offset:192
	s_waitcnt vmcnt(1)
	v_pk_mul_f32 v[54:55], v[54:55], 0.5 op_sel_hi:[1,0]
	v_pk_mul_f32 v[56:57], v[56:57], 0.5 op_sel_hi:[1,0]
	s_waitcnt vmcnt(0)
	v_pk_fma_f32 v[50:51], v[50:51], v[54:55], v[58:59]
	v_pk_fma_f32 v[52:53], v[52:53], v[56:57], v[60:61]
	global_store_dwordx4 v[66:67], v[50:53], off offset:192
	global_load_dwordx4 v[50:53], v[76:77], off offset:256
	s_nop 0
	global_load_dwordx4 v[54:57], v[66:67], off offset:256
	s_waitcnt vmcnt(1)
	v_pk_mul_f32 v[50:51], v[50:51], 0.5 op_sel_hi:[1,0]
	v_pk_mul_f32 v[52:53], v[52:53], 0.5 op_sel_hi:[1,0]
	s_waitcnt vmcnt(0)
	v_pk_fma_f32 v[46:47], v[46:47], v[50:51], v[54:55]
	v_pk_fma_f32 v[48:49], v[48:49], v[52:53], v[56:57]
	global_store_dwordx4 v[66:67], v[46:49], off offset:256
	global_load_dwordx4 v[46:49], v[76:77], off offset:320
	s_nop 0
	global_load_dwordx4 v[50:53], v[66:67], off offset:320
	s_waitcnt vmcnt(1)
	v_pk_mul_f32 v[46:47], v[46:47], 0.5 op_sel_hi:[1,0]
	v_pk_mul_f32 v[48:49], v[48:49], 0.5 op_sel_hi:[1,0]
	s_waitcnt vmcnt(0)
	v_pk_fma_f32 v[42:43], v[42:43], v[46:47], v[50:51]
	v_pk_fma_f32 v[44:45], v[44:45], v[48:49], v[52:53]
	global_store_dwordx4 v[66:67], v[42:45], off offset:320
	global_load_dwordx4 v[42:45], v[76:77], off offset:384
	s_nop 0
	global_load_dwordx4 v[46:49], v[66:67], off offset:384
	s_waitcnt vmcnt(1)
	v_pk_mul_f32 v[42:43], v[42:43], 0.5 op_sel_hi:[1,0]
	v_pk_mul_f32 v[44:45], v[44:45], 0.5 op_sel_hi:[1,0]
	s_waitcnt vmcnt(0)
	v_pk_fma_f32 v[38:39], v[38:39], v[42:43], v[46:47]
	v_pk_fma_f32 v[40:41], v[40:41], v[44:45], v[48:49]
	global_store_dwordx4 v[66:67], v[38:41], off offset:384
	global_load_dwordx4 v[38:41], v[76:77], off offset:448
	s_nop 0
	global_load_dwordx4 v[42:45], v[66:67], off offset:448
	s_waitcnt vmcnt(1)
	v_pk_mul_f32 v[38:39], v[38:39], 0.5 op_sel_hi:[1,0]
	v_pk_mul_f32 v[40:41], v[40:41], 0.5 op_sel_hi:[1,0]
	s_waitcnt vmcnt(0)
	v_pk_fma_f32 v[34:35], v[34:35], v[38:39], v[42:43]
	v_pk_fma_f32 v[36:37], v[36:37], v[40:41], v[44:45]
	global_store_dwordx4 v[66:67], v[34:37], off offset:448
	s_nop 1
	v_or_b32_e32 v34, 48, v114
	v_cmp_lt_i32_e32 vcc, s97, v34
	v_add_u32_e32 v36, 0xffffc030, v114
	v_ashrrev_i32_e32 v35, 31, v34
	v_cndmask_b32_e64 v35, v35, 0, vcc
	v_cndmask_b32_e32 v34, v34, v36, vcc
	v_cndmask_b32_e64 v38, v115, 8, vcc
	v_cndmask_b32_e32 v37, v116, v117, vcc
	v_cndmask_b32_e32 v36, v118, v119, vcc
	v_lshlrev_b64 v[34:35], 12, v[34:35]
	v_lshl_add_u64 v[34:35], v[36:37], 0, v[34:35]
	v_mul_hi_i32_i24_e32 v37, 0x9000, v38
	v_mul_i32_i24_e32 v36, 0x9000, v38
	v_lshl_add_u64 v[36:37], s[14:15], 0, v[36:37]
	v_lshl_add_u64 v[44:45], v[36:37], 0, v[110:111]
	global_load_dwordx4 v[36:39], v[44:45], off
	v_lshl_add_u64 v[34:35], v[34:35], 0, v[110:111]
	global_load_dwordx4 v[40:43], v[34:35], off
	s_waitcnt vmcnt(1)
	v_pk_mul_f32 v[36:37], v[36:37], 0.5 op_sel_hi:[1,0]
	v_pk_mul_f32 v[38:39], v[38:39], 0.5 op_sel_hi:[1,0]
	s_waitcnt vmcnt(0)
	v_pk_fma_f32 v[30:31], v[30:31], v[36:37], v[40:41]
	v_pk_fma_f32 v[32:33], v[32:33], v[38:39], v[42:43]
	global_store_dwordx4 v[34:35], v[30:33], off
	global_load_dwordx4 v[30:33], v[44:45], off offset:64
	s_nop 0
	global_load_dwordx4 v[36:39], v[34:35], off offset:64
	s_waitcnt vmcnt(1)
	v_pk_mul_f32 v[30:31], v[30:31], 0.5 op_sel_hi:[1,0]
	v_pk_mul_f32 v[32:33], v[32:33], 0.5 op_sel_hi:[1,0]
	s_waitcnt vmcnt(0)
	v_pk_fma_f32 v[26:27], v[26:27], v[30:31], v[36:37]
	v_pk_fma_f32 v[28:29], v[28:29], v[32:33], v[38:39]
	global_store_dwordx4 v[34:35], v[26:29], off offset:64
	global_load_dwordx4 v[26:29], v[44:45], off offset:128
	s_nop 0
	global_load_dwordx4 v[30:33], v[34:35], off offset:128
	s_waitcnt vmcnt(1)
	v_pk_mul_f32 v[26:27], v[26:27], 0.5 op_sel_hi:[1,0]
	v_pk_mul_f32 v[28:29], v[28:29], 0.5 op_sel_hi:[1,0]
	s_waitcnt vmcnt(0)
	v_pk_fma_f32 v[22:23], v[22:23], v[26:27], v[30:31]
	v_pk_fma_f32 v[24:25], v[24:25], v[28:29], v[32:33]
	global_store_dwordx4 v[34:35], v[22:25], off offset:128
	global_load_dwordx4 v[22:25], v[44:45], off offset:192
	s_nop 0
	global_load_dwordx4 v[26:29], v[34:35], off offset:192
	s_waitcnt vmcnt(1)
	v_pk_mul_f32 v[22:23], v[22:23], 0.5 op_sel_hi:[1,0]
	v_pk_mul_f32 v[24:25], v[24:25], 0.5 op_sel_hi:[1,0]
	s_waitcnt vmcnt(0)
	v_pk_fma_f32 v[18:19], v[18:19], v[22:23], v[26:27]
	v_pk_fma_f32 v[20:21], v[20:21], v[24:25], v[28:29]
	global_store_dwordx4 v[34:35], v[18:21], off offset:192
	global_load_dwordx4 v[18:21], v[44:45], off offset:256
	s_nop 0
	global_load_dwordx4 v[22:25], v[34:35], off offset:256
	s_waitcnt vmcnt(1)
	v_pk_mul_f32 v[18:19], v[18:19], 0.5 op_sel_hi:[1,0]
	v_pk_mul_f32 v[20:21], v[20:21], 0.5 op_sel_hi:[1,0]
	s_waitcnt vmcnt(0)
	v_pk_fma_f32 v[14:15], v[14:15], v[18:19], v[22:23]
	v_pk_fma_f32 v[16:17], v[16:17], v[20:21], v[24:25]
	global_store_dwordx4 v[34:35], v[14:17], off offset:256
	global_load_dwordx4 v[14:17], v[44:45], off offset:320
	s_nop 0
	global_load_dwordx4 v[18:21], v[34:35], off offset:320
	s_waitcnt vmcnt(1)
	v_pk_mul_f32 v[14:15], v[14:15], 0.5 op_sel_hi:[1,0]
	v_pk_mul_f32 v[16:17], v[16:17], 0.5 op_sel_hi:[1,0]
	s_waitcnt vmcnt(0)
	v_pk_fma_f32 v[10:11], v[10:11], v[14:15], v[18:19]
	v_pk_fma_f32 v[12:13], v[12:13], v[16:17], v[20:21]
	global_store_dwordx4 v[34:35], v[10:13], off offset:320
	global_load_dwordx4 v[10:13], v[44:45], off offset:384
	s_nop 0
	global_load_dwordx4 v[14:17], v[34:35], off offset:384
	s_waitcnt vmcnt(1)
	v_pk_mul_f32 v[10:11], v[10:11], 0.5 op_sel_hi:[1,0]
	v_pk_mul_f32 v[12:13], v[12:13], 0.5 op_sel_hi:[1,0]
	s_waitcnt vmcnt(0)
	v_pk_fma_f32 v[6:7], v[6:7], v[10:11], v[14:15]
	v_pk_fma_f32 v[8:9], v[8:9], v[12:13], v[16:17]
	global_store_dwordx4 v[34:35], v[6:9], off offset:384
	global_load_dwordx4 v[6:9], v[44:45], off offset:448
	s_nop 0
	global_load_dwordx4 v[10:13], v[34:35], off offset:448
	s_waitcnt vmcnt(1)
	v_pk_mul_f32 v[6:7], v[6:7], 0.5 op_sel_hi:[1,0]
	v_pk_mul_f32 v[8:9], v[8:9], 0.5 op_sel_hi:[1,0]
	s_waitcnt vmcnt(0)
	v_pk_fma_f32 v[2:3], v[2:3], v[6:7], v[10:11]
	v_pk_fma_f32 v[4:5], v[4:5], v[8:9], v[12:13]
	global_store_dwordx4 v[34:35], v[2:5], off offset:448
	s_add_i32 s18, s18, s11
	s_cmpk_gt_i32 s18, 0xff
	s_cbranch_scc0 .LBB0_1527
